# K tile LDS swizzle over 16 granules (conflict-free ds_read_b128 groups) on top of deferred PV for waves 4-7
# speedup vs baseline: 1.0095x; 1.0095x over previous
; #define LAS __attribute__((address_space(3)))
; __device__ __forceinline__ float bf2f(unsigned b) { return __uint_as_float(b << 16); }
; __device__ __forceinline__ float sigmoidf_(float x) { return __builtin_amdgcn_rcpf(1.0f + __expf(-x)); }
; template <int VAR>
; __device__ __forceinline__ void nsa_attn_mfma(Frame& F, bf16* Y) {
;     ...
;     int lane = F.lane; asm volatile("" : "+v"(lane));
;     const int r32 = lane & 31, hi = lane >> 5, tsub = r32 >> 3, j = r32 & 7, tl_ = wid * 64 + lane;
;     const int krow = tl_ >> 4, kcol = ((lane & 15) ^ (krow & 7)) * 8;
;     const int vkk = (wid >> 1) * 8 + ((lane >> 2) & 7), vrow = (vkk & ~0xC) | ((vkk & 4) << 1) | ((vkk & 8) >> 1), vcol = ((wid & 1) * 2 + (lane >> 5)) * 32 + (lane & 3) * 8;
;     const int vb0 = (int)(uintptr_t)((LAS unsigned char*)lds + AT_V) + v_rd_base(lane);
;     float* li_l = wsf; float* al_l = wsf + 32;
;     v4u* otl = (v4u*)(lds + AT_OT) + tl_;
;     constexpr int ROWP = 136;
;     unsigned short* rowst = (unsigned short*)(lds + AT_K) + (wid * 32 + 4 * hi) * ROWP + r32;
;     const int wg = uu >> 2, b = wg >> 6, kq_ = wg & 63, k32_ = (kq_ + 32) & 63;
;     const int g = ui, qb = (ui == 0) ? kq_ : (ui == 1) ? 63 - kq_ : (ui == 2) ? k32_ : 63 - k32_;
;     const int t0 = qb * 32, cur = t0 >> 6;
;     const int t = t0 + 4 * wid + tsub, h = g * 8 + j;
;     const float slope2 = exp2f(-0.25f * (float)(h + 1)) * LOG2E;
;     const size_t rowq = (size_t)(b * SEQ + t) * NSA_NP;
;     bf16x8 qr[8];
; #pragma unroll
;     for (int d0 = 0; d0 < 8; ++d0) qr[d0] = *(const bf16x8*)(proj + rowq + NSA_Q + h * 128 + d0 * 16 + hi * 8);
;     const float g0 = sigmoidf_(bf2f(proj[rowq + NSA_GL + 0 * 32 + h])), g1 = sigmoidf_(bf2f(proj[rowq + NSA_GL + 1 * 32 + h])), g2 = sigmoidf_(bf2f(proj[rowq + NSA_GL + 2 * 32 + h]));
;     f32x16 o[4];
; #pragma unroll
;     for (int d = 0; d < 4; ++d) { o[d] = f32x16{}; }
;     __syncthreads();
;     {
;       const bf16* kc = KC + (size_t)(b * 4 + g) * 128 * 128; const bf16* vc = VC + (size_t)(b * 4 + g) * 128 * 128;
;       { const bf16* kcp = kc + krow * 128 + kcol; const bf16* vcp = vc + vrow * 128 + vcol; TDMA(kcp, vcp, 128, 0, 0); TDMA(kcp + 64 * 128, vcp + 64 * 128, 128, 1, 1); }
;       TWAIT();
;       f32x16 pA0, pA1, pB0, pB1;
;       qkt(pA0, pA1, K_lds, qr, r32, hi); qkt(pB0, pB1, K_lds + SHM_K, qr, r32, hi);
.LBB0_603:
	v_readlane_b32 s0, v254, 32
	v_lshrrev_b32_e32 v4, 1, v178
	v_bfe_u32 v2, v178, 2, 2
	v_add_u32_e32 v145, s0, v178
	v_and_b32_e32 v4, 8, v4
	v_readlane_b32 s0, v254, 33
	v_ashrrev_i32_e32 v150, 5, v178
	s_lshl_b32 s33, s4, 5
	v_or3_b32 v99, s0, v2, v4
	v_readlane_b32 s0, v254, 34
	v_bfe_u32 v140, v178, 3, 2
	v_lshlrev_b32_e32 v147, 3, v178
	v_add_u32_e32 v2, s0, v150
	v_readlane_b32 s0, v254, 36
	s_ashr_i32 s2, s80, 8
	s_add_i32 s0, s33, s0
	v_and_b32_e32 v151, 7, v178
	v_and_b32_e32 v148, 24, v147
	v_or_b32_e32 v181, s0, v140
	s_lshl_b32 s75, s6, 3
	s_lshl_b32 s84, s2, 11
	v_lshl_or_b32 v96, v2, 5, v148
	v_or_b32_e32 v64, s75, v151
	v_add_u32_e32 v2, s84, v181
	v_writelane_b32 v254, s0, 62
	v_mad_i64_i32 v[4:5], s[0:1], v2, s89, v[136:137]
	v_lshlrev_b32_e32 v2, 8, v64
	v_lshlrev_b32_e32 v8, 3, v150
	v_lshl_add_u64 v[6:7], v[4:5], 0, v[2:3]
	v_ashrrev_i32_e32 v9, 31, v8
	v_lshl_add_u64 v[6:7], v[8:9], 1, v[6:7]
	global_load_dwordx4 v[104:107], v[6:7], off
	global_load_dwordx4 v[108:111], v[6:7], off offset:32
	global_load_dwordx4 v[112:115], v[6:7], off offset:64
	global_load_dwordx4 v[116:119], v[6:7], off offset:96
	global_load_dwordx4 v[120:123], v[6:7], off offset:128
	global_load_dwordx4 v[124:127], v[6:7], off offset:160
	global_load_dwordx4 v[128:131], v[6:7], off offset:192
	global_load_dwordx4 v[132:135], v[6:7], off offset:224
	v_lshlrev_b32_e32 v2, 1, v64
	v_lshl_add_u64 v[4:5], v[4:5], 0, v[2:3]
	s_movk_i32 s0, 0x5000
	v_add_co_u32_e32 v4, vcc, s0, v4
	s_lshl_b32 s0, s2, 2
	s_or_b32 s0, s0, s6
	s_ashr_i32 s1, s0, 31
	v_ashrrev_i32_e32 v98, 4, v145
	s_lshr_b32 s85, s4, 1
	v_addc_co_u32_e32 v5, vcc, 0, v5, vcc
	s_lshl_b64 s[0:1], s[0:1], 15
	v_readlane_b32 s2, v254, 25
	v_and_b32_e32 v179, 15, v178
	global_load_ushort v146, v[4:5], off offset:2048
	global_load_ushort v144, v[4:5], off offset:2112
	global_load_ushort v143, v[4:5], off offset:2176
	s_add_u32 s2, s2, s0
	v_readlane_b32 s3, v254, 27
	v_lshlrev_b32_e32 v4, 7, v98
	v_bitop3_b32 v142, v98, v179, 15 bitop3:0x6c
	s_addc_u32 s3, s3, s1
	v_readlane_b32 s5, v254, 29
	v_ashrrev_i32_e32 v5, 31, v4
	s_add_u32 s0, s5, s0
	v_readlane_b32 s5, v254, 31
	v_lshl_add_u64 v[4:5], v[4:5], 1, s[2:3]
	v_lshlrev_b32_e32 v2, 4, v142
	s_mov_b32 m0, s83
	s_addc_u32 s1, s5, s1
	v_lshl_add_u64 v[4:5], v[4:5], 0, v[2:3]
	v_lshlrev_b32_e32 v6, 8, v99
	v_mov_b32_e32 v7, v3
	v_ashrrev_i32_e32 v97, 31, v96
	s_mov_b64 s[12:13], 0x2000
	v_readlane_b32 s3, v254, 41
	s_waitcnt lgkmcnt(0)
	s_barrier
	v_lshl_add_u64 v[6:7], s[0:1], 0, v[6:7]
	v_lshlrev_b64 v[68:69], 1, v[96:97]
	global_load_lds_dwordx4 v[4:5], off
	v_lshl_add_u64 v[8:9], v[4:5], 0, s[12:13]
	s_mov_b32 m0, s3
	v_readlane_b32 s0, v254, 42
	v_lshl_add_u64 v[6:7], v[6:7], 0, v[68:69]
	global_load_lds_dwordx4 v[8:9], off
	s_mov_b32 m0, s0
	v_readlane_b32 s0, v254, 43
	global_load_lds_dwordx4 v[6:7], off
	v_lshl_add_u64 v[8:9], v[6:7], 0, s[12:13]
	s_mov_b32 m0, s0
	s_mov_b64 s[12:13], 0x4000
	v_readlane_b32 s0, v254, 44
	global_load_lds_dwordx4 v[8:9], off
	v_lshl_add_u64 v[8:9], v[4:5], 0, s[12:13]
	s_mov_b32 m0, s0
	s_mov_b64 s[14:15], 0x6000
	v_readlane_b32 s0, v254, 45
	v_and_b32_e32 v180, 31, v178
	global_load_lds_dwordx4 v[8:9], off
	v_lshl_add_u64 v[4:5], v[4:5], 0, s[14:15]
	s_mov_b32 m0, s0
	v_readlane_b32 s0, v254, 46
	v_lshlrev_b32_e32 v149, 4, v178
	global_load_lds_dwordx4 v[4:5], off
	v_lshl_add_u64 v[4:5], v[6:7], 0, s[12:13]
	s_mov_b32 m0, s0
	v_readlane_b32 s0, v254, 47
	v_lshlrev_b32_e32 v24, 4, v150
	v_lshlrev_b32_e32 v25, 8, v180
	v_and_b32_e32 v26, 0xf0, v149
	global_load_lds_dwordx4 v[4:5], off
	v_lshl_add_u64 v[4:5], v[6:7], 0, s[14:15]
	s_mov_b32 m0, s0
	v_xad_u32 v182, v26, v24, v25
	global_load_lds_dwordx4 v[4:5], off
	v_add_u32_e32 v27, 0, v182
	s_waitcnt vmcnt(0)
	s_waitcnt vmcnt(0) lgkmcnt(0)
	s_barrier
	ds_read_b128 v[4:7], v27 offset:8192
	ds_read_b128 v[52:55], v27
	s_waitcnt lgkmcnt(1)
	v_mfma_f32_32x32x16_bf16 v[4:19], v[4:7], v[104:107], 0
	v_add_u32_e32 v20, 32, v24
	v_xad_u32 v183, v20, v26, v25
	v_add_u32_e32 v60, 0, v183
	ds_read_b128 v[20:23], v60 offset:8192
	ds_read_b128 v[70:73], v60
	s_mov_b32 s0, 0xc2fc0000
	s_lshl_b32 s96, s6, 8
	s_mov_b32 m0, s83
	s_waitcnt lgkmcnt(1)
	v_mfma_f32_32x32x16_bf16 v[4:19], v[20:23], v[108:111], v[4:19]
	v_add_u32_e32 v20, 64, v24
	v_xad_u32 v184, v20, v26, v25
	v_add_u32_e32 v65, 0, v184
	ds_read_b128 v[20:23], v65 offset:8192
	ds_read_b128 v[74:77], v65
	v_lshlrev_b32_e32 v189, 2, v150
	s_waitcnt lgkmcnt(1)
	v_mfma_f32_32x32x16_bf16 v[4:19], v[20:23], v[112:115], v[4:19]
	v_add_u32_e32 v20, 0x60, v24
	v_xad_u32 v185, v20, v26, v25
	v_add_u32_e32 v66, 0, v185
	ds_read_b128 v[20:23], v66 offset:8192
	ds_read_b128 v[78:81], v66
	s_waitcnt lgkmcnt(1)
	v_mfma_f32_32x32x16_bf16 v[4:19], v[20:23], v[116:119], v[4:19]
	v_add_u32_e32 v20, 0x80, v24
	v_xad_u32 v186, v20, v26, v25
	v_add_u32_e32 v67, 0, v186
	ds_read_b128 v[20:23], v67 offset:8192
	ds_read_b128 v[82:85], v67
	s_waitcnt lgkmcnt(1)
	v_mfma_f32_32x32x16_bf16 v[4:19], v[20:23], v[120:123], v[4:19]
	v_add_u32_e32 v20, 0xa0, v24
	v_xad_u32 v187, v20, v26, v25
	v_add_u32_e32 v94, 0, v187
	ds_read_b128 v[20:23], v94 offset:8192
	ds_read_b128 v[86:89], v94
	s_waitcnt lgkmcnt(1)
	v_mfma_f32_32x32x16_bf16 v[4:19], v[20:23], v[124:127], v[4:19]
	v_add_u32_e32 v20, 0xc0, v24
	v_xad_u32 v188, v20, v26, v25
	v_add_u32_e32 v95, 0, v188
	ds_read_b128 v[20:23], v95 offset:8192
	ds_read_b128 v[90:93], v95
	s_waitcnt lgkmcnt(1)
	v_mfma_f32_32x32x16_bf16 v[4:19], v[20:23], v[128:131], v[4:19]
	v_add_u32_e32 v20, 0xe0, v24
	v_xad_u32 v190, v20, v26, v25
	v_add_u32_e32 v139, 0, v190
	ds_read_b128 v[20:23], v139 offset:8192
	ds_read_b128 v[152:155], v139
	s_waitcnt lgkmcnt(1)
; template <int VAR>
; __device__ __forceinline__ void nsa_attn_mfma(Frame& F, bf16* Y) {
;     ...
;       qkt(pA0, pA1, K_lds, qr, r32, hi); qkt(pB0, pB1, K_lds + SHM_K, qr, r32, hi);
;       __syncthreads();
;       if (VAR < 5) TDMA(proj + (size_t)(b * SEQ + cur * 64 + krow) * NSA_NP + NSA_KS + g * 128 + kcol, proj + (size_t)(b * SEQ + cur * 64 + vrow) * NSA_NP + NSA_VS + g * 128 + vcol, NSA_NP, 0, 2);
;       const float sl16 = 16.f * slope2, s32_ = sl16 + sl16, s64_ = s32_ + s32_, s128_ = s64_ + s64_;
;       const float baseA = slope2 * (float)(16 * (4 * hi) + 31 - t);
;       const float ca_[4] = {0.f, sl16, s32_, s32_ + sl16};
;       float cb_[16]; cb_[0] = baseA;
; #pragma unroll
;       for (int q = 1; q < 16; ++q) cb_[q] = cb_[q - 1] + s128_;
;       float mx = -1e30f;
;       const int nlim = ((t - 31) >> 4) - 4 * hi;
; #pragma unroll
;       for (int r = 0; r < 16; ++r) { const int c = (r & 3) + 8 * (r >> 2);
;         float a0 = fmaf(pA0[r], CSC, ca_[r & 3] + cb_[r >> 2]), a1 = fmaf(pA1[r], CSC, ca_[r & 3] + cb_[4 + (r >> 2)]);
;         float b0 = fmaf(pB0[r], CSC, ca_[r & 3] + cb_[8 + (r >> 2)]), b1 = fmaf(pB1[r], CSC, ca_[r & 3] + cb_[12 + (r >> 2)]);
;         a0 = (c > nlim) ? -1e30f : a0; a1 = (c + 32 > nlim) ? -1e30f : a1;
;         b0 = (c + 64 > nlim) ? -1e30f : b0; b1 = (c + 96 > nlim || (c == 27 && hi)) ? -1e30f : b1;
;         pA0[r] = a0; pA1[r] = a1; pB0[r] = b0; pB1[r] = b1; mx = fmaxf(fmaxf(mx, fmaxf(a0, a1)), fmaxf(b0, b1)); }
	v_mfma_f32_32x32x16_bf16 v[4:19], v[20:23], v[132:135], v[4:19]
	ds_read_b128 v[20:23], v27 offset:16384
	ds_read_b128 v[24:27], v27 offset:24576
	ds_read_b128 v[56:59], v60 offset:16384
	ds_read_b128 v[60:63], v60 offset:24576
	s_waitcnt lgkmcnt(3)
	v_mfma_f32_32x32x16_bf16 v[36:51], v[20:23], v[104:107], 0
	s_waitcnt lgkmcnt(2)
	v_mfma_f32_32x32x16_bf16 v[20:35], v[24:27], v[104:107], 0
	s_waitcnt lgkmcnt(1)
	v_mfma_f32_32x32x16_bf16 v[36:51], v[56:59], v[108:111], v[36:51]
	s_waitcnt lgkmcnt(0)
	v_mfma_f32_32x32x16_bf16 v[20:35], v[60:63], v[108:111], v[20:35]
	ds_read_b128 v[56:59], v65 offset:16384
	ds_read_b128 v[60:63], v65 offset:24576
	s_waitcnt lgkmcnt(1)
	v_mfma_f32_32x32x16_bf16 v[36:51], v[56:59], v[112:115], v[36:51]
	s_waitcnt lgkmcnt(0)
	v_mfma_f32_32x32x16_bf16 v[20:35], v[60:63], v[112:115], v[20:35]
	ds_read_b128 v[56:59], v66 offset:16384
	ds_read_b128 v[60:63], v66 offset:24576
	s_waitcnt lgkmcnt(1)
	v_mfma_f32_32x32x16_bf16 v[36:51], v[56:59], v[116:119], v[36:51]
	s_waitcnt lgkmcnt(0)
	v_mfma_f32_32x32x16_bf16 v[20:35], v[60:63], v[116:119], v[20:35]
	ds_read_b128 v[56:59], v67 offset:16384
	ds_read_b128 v[60:63], v67 offset:24576
	s_waitcnt lgkmcnt(1)
	v_mfma_f32_32x32x16_bf16 v[36:51], v[56:59], v[120:123], v[36:51]
	s_waitcnt lgkmcnt(0)
	v_mfma_f32_32x32x16_bf16 v[20:35], v[60:63], v[120:123], v[20:35]
	ds_read_b128 v[56:59], v94 offset:16384
	ds_read_b128 v[60:63], v94 offset:24576
	s_waitcnt lgkmcnt(1)
	v_mfma_f32_32x32x16_bf16 v[36:51], v[56:59], v[124:127], v[36:51]
	s_waitcnt lgkmcnt(0)
	v_mfma_f32_32x32x16_bf16 v[20:35], v[60:63], v[124:127], v[20:35]
	ds_read_b128 v[56:59], v95 offset:16384
	ds_read_b128 v[60:63], v95 offset:24576
	s_waitcnt lgkmcnt(1)
	v_mfma_f32_32x32x16_bf16 v[36:51], v[56:59], v[128:131], v[36:51]
	ds_read_b128 v[56:59], v139 offset:16384
	s_waitcnt lgkmcnt(1)
	v_mfma_f32_32x32x16_bf16 v[20:35], v[60:63], v[128:131], v[20:35]
	v_add_u32_e32 v60, 1, v64
	v_cvt_f32_ubyte0_e32 v64, v60
	ds_read_b128 v[60:63], v139 offset:24576
	s_waitcnt lgkmcnt(0)
	s_barrier
	v_mfma_f32_32x32x16_bf16 v[36:51], v[56:59], v[132:135], v[36:51]
	v_mul_f32_e32 v56, 0xbe800000, v64
	v_cmp_gt_f32_e32 vcc, s0, v56
	s_lshl_b32 s0, s85, 6
	s_add_i32 s2, s0, s84
	v_cndmask_b32_e32 v56, 0, v172, vcc
	v_fmac_f32_e32 v56, 0xbe800000, v64
	v_exp_f32_e32 v56, v56
	v_cndmask_b32_e32 v57, 0, v173, vcc
	v_mfma_f32_32x32x16_bf16 v[20:35], v[60:63], v[132:135], v[20:35]
	v_add_u32_e32 v94, s2, v98
	v_ldexp_f32 v56, v56, v57
	v_mul_f32_e32 v141, 0x3fb8aa3b, v56
	v_mad_i64_i32 v[94:95], s[0:1], v94, s89, v[136:137]
	v_lshl_add_u64 v[94:95], v[94:95], 0, s[96:97]
	v_lshl_add_u64 v[94:95], v[94:95], 0, v[2:3]
	v_mfma_f32_32x32x16_bf16 v[52:67], v[52:55], v[104:107], 0
	s_mov_b64 s[0:1], 0x2800
	v_lshl_add_u64 v[156:157], v[94:95], 0, s[0:1]
	s_mov_b64 s[0:1], 0xb6800
	global_load_lds_dwordx4 v[156:157], off
	s_mov_b32 m0, s3
	v_add_u32_e32 v2, s2, v99
	v_mfma_f32_32x32x16_bf16 v[52:67], v[70:73], v[108:111], v[52:67]
	v_lshl_add_u64 v[70:71], v[94:95], 0, s[0:1]
	global_load_lds_dwordx4 v[70:71], off
	v_mad_i64_i32 v[70:71], s[0:1], v2, s89, v[136:137]
	v_lshl_or_b32 v2, v150, 6, 31
	v_sub_u32_e32 v2, v2, v181
	v_mfma_f32_32x32x16_bf16 v[52:67], v[74:77], v[112:115], v[52:67]
	v_cvt_f32_i32_e32 v139, v2
	v_mov_b32_e32 v2, v141
	v_lshl_add_u64 v[70:71], v[70:71], 0, s[96:97]
	v_lshl_add_u64 v[68:69], v[70:71], 0, v[68:69]
	s_mov_b64 s[0:1], 0x2c00
	v_lshl_add_u64 v[70:71], v[68:69], 0, s[0:1]
	v_readlane_b32 s0, v254, 48
	v_mfma_f32_32x32x16_bf16 v[52:67], v[78:81], v[116:119], v[52:67]
	v_mul_f32_e64 v80, v2, v138
	v_mul_f32_e64 v81, v2, v139
	v_add_f32_e64 v78, v80, v80
	v_add_f32_e64 v79, v81, v81
	s_mov_b32 m0, s0
	v_pk_fma_f32 v[76:77], v[80:81], 2.0, v[78:79] op_sel_hi:[1,0,1]
	global_load_lds_dwordx4 v[70:71], off
	v_pk_fma_f32 v[156:157], v[76:77], 2.0, v[80:81] op_sel:[0,0,1] op_sel_hi:[1,0,0]
	v_mfma_f32_32x32x16_bf16 v[52:67], v[82:85], v[120:123], v[52:67]
	v_fma_f32 v82, v76, 2.0, v156
	v_fma_f32 v83, v77, 2.0, v157
	s_mov_b64 s[0:1], 0xb6c00
	v_fma_f32 v70, v76, 2.0, v82
	v_fma_f32 v71, v77, 2.0, v83
	v_lshl_add_u64 v[68:69], v[68:69], 0, s[0:1]
	v_pk_fma_f32 v[158:159], v[76:77], 2.0, v[70:71] op_sel_hi:[1,0,1]
	v_subrev_u32_e32 v71, 31, v181
	v_ashrrev_i32_e32 v71, 4, v71
	v_mfma_f32_32x32x16_bf16 v[52:67], v[86:89], v[124:127], v[52:67]
	v_fma_f32 v88, v76, 2.0, v158
	v_fma_f32 v89, v77, 2.0, v159
	v_sub_u32_e32 v71, v71, v189
	v_fma_f32 v84, v76, 2.0, v88
	v_fma_f32 v85, v77, 2.0, v89
	v_cmp_lt_i32_e64 s[2:3], -1, v71
	v_pk_fma_f32 v[72:73], v[76:77], 2.0, v[84:85] op_sel_hi:[1,0,1]
	s_movk_i32 s0, 0x5f
	v_pk_fma_f32 v[160:161], v[76:77], 2.0, v[72:73] op_sel_hi:[1,0,1]
	v_mfma_f32_32x32x16_bf16 v[52:67], v[90:93], v[128:131], v[52:67]
	v_fma_f32 v162, v76, 2.0, v160
	v_fma_f32 v163, v77, 2.0, v161
	v_add_f32_e32 v73, 0, v81
	v_fma_f32 v86, v76, 2.0, v162
	v_fma_f32 v87, v77, 2.0, v163
	v_pk_fma_f32 v[94:95], v[78:79], 2.0, v[76:77] op_sel_hi:[1,0,1]
	v_pk_fma_f32 v[74:75], v[76:77], 2.0, v[86:87] op_sel_hi:[1,0,1]
	v_cmp_lt_u32_e32 vcc, 31, v178
	v_pk_fma_f32 v[90:91], v[76:77], 2.0, v[74:75] op_sel_hi:[1,0,1]
	v_mfma_f32_32x32x16_bf16 v[52:67], v[152:155], v[132:135], v[52:67]
	v_fma_f32 v92, v76, 2.0, v90
	v_fma_f32 v93, v77, 2.0, v91
	v_mov_b32_e32 v76, v80
	v_mov_b32_e32 v77, v94
	v_mov_b32_e32 v79, v92
	v_pk_add_f32 v[76:77], v[76:77], v[78:79]
	s_nop 5
	v_fmac_f32_e32 v73, 0x3e0293ee, v52
	v_add_f32_e32 v52, 0, v158
	v_fmac_f32_e32 v52, 0x3e0293ee, v4
	v_add_f32_e32 v4, 0, v160
	v_fmac_f32_e32 v4, 0x3e0293ee, v36
	v_add_f32_e32 v36, 0, v90
	v_fmac_f32_e32 v36, 0x3e0293ee, v20
	v_cndmask_b32_e64 v20, v174, v73, s[2:3]
; __device__ __forceinline__ float swapmax(float x) { auto rr = __builtin_amdgcn_permlane32_swap(__float_as_uint(x), __float_as_uint(x), false, false); return fmaxf(__uint_as_float(rr[0]), __uint_as_float(rr[1])); }
; template <int VAR>
; __device__ __forceinline__ void nsa_attn_mfma(Frame& F, bf16* Y) {
;     ...
;       const int nlim = ((t - 31) >> 4) - 4 * hi;
; #pragma unroll
;       for (int r = 0; r < 16; ++r) { const int c = (r & 3) + 8 * (r >> 2);
;         float a0 = fmaf(pA0[r], CSC, ca_[r & 3] + cb_[r >> 2]), a1 = fmaf(pA1[r], CSC, ca_[r & 3] + cb_[4 + (r >> 2)]);
;         float b0 = fmaf(pB0[r], CSC, ca_[r & 3] + cb_[8 + (r >> 2)]), b1 = fmaf(pB1[r], CSC, ca_[r & 3] + cb_[12 + (r >> 2)]);
;         a0 = (c > nlim) ? -1e30f : a0; a1 = (c + 32 > nlim) ? -1e30f : a1;
;         b0 = (c + 64 > nlim) ? -1e30f : b0; b1 = (c + 96 > nlim || (c == 27 && hi)) ? -1e30f : b1;
;         pA0[r] = a0; pA1[r] = a1; pB0[r] = b0; pB1[r] = b1; mx = fmaxf(fmaxf(mx, fmaxf(a0, a1)), fmaxf(b0, b1)); }
;       mx = swapmax(mx);
	v_cmp_lt_i32_e64 s[2:3], 31, v71
	v_add_f32_e32 v2, v94, v77
	s_nop 0
	v_cndmask_b32_e64 v52, v174, v52, s[2:3]
	v_cmp_lt_i32_e64 s[2:3], 63, v71
	s_nop 1
	v_cndmask_b32_e64 v73, v174, v4, s[2:3]
	v_cmp_lt_i32_e64 s[2:3], s0, v71
	v_max_f32_e32 v4, v20, v52
	s_mov_b32 s0, 0xf149f2ca
	v_cndmask_b32_e64 v36, v174, v36, s[2:3]
	v_max_f32_e32 v75, v73, v36
	v_max3_f32 v4, v4, s0, v75
	v_add_f32_e32 v75, v80, v81
	v_fmac_f32_e32 v75, 0x3e0293ee, v53
	v_add_f32_e32 v53, v80, v158
	v_fmac_f32_e32 v53, 0x3e0293ee, v5
	v_add_f32_e32 v5, v80, v160
	v_fmac_f32_e32 v5, 0x3e0293ee, v37
	v_add_f32_e32 v37, v80, v90
	v_cmp_lt_i32_e64 s[2:3], 0, v71
	v_fmac_f32_e32 v37, 0x3e0293ee, v21
	s_movk_i32 s0, 0x60
	v_cndmask_b32_e64 v21, v174, v75, s[2:3]
	v_cmp_lt_i32_e64 s[2:3], 32, v71
	s_nop 1
	v_cndmask_b32_e64 v53, v174, v53, s[2:3]
	v_cmp_lt_i32_e64 s[2:3], 64, v71
	s_nop 1
	v_cndmask_b32_e64 v75, v174, v5, s[2:3]
	v_cmp_lt_i32_e64 s[2:3], s0, v71
	v_max_f32_e32 v5, v21, v53
	s_movk_i32 s0, 0x41
	v_cndmask_b32_e64 v37, v174, v37, s[2:3]
	v_max_f32_e32 v79, v75, v37
	v_max3_f32 v4, v4, v5, v79
	v_add_f32_e32 v5, v78, v81
	v_fmac_f32_e32 v5, 0x3e0293ee, v54
	v_add_f32_e32 v54, v78, v158
	v_fmac_f32_e32 v54, 0x3e0293ee, v6
	v_add_f32_e32 v6, v78, v160
	v_fmac_f32_e32 v6, 0x3e0293ee, v38
	v_add_f32_e32 v38, v78, v90
	v_cmp_lt_i32_e64 s[2:3], 1, v71
	v_fmac_f32_e32 v38, 0x3e0293ee, v22
	s_nop 0
	v_cndmask_b32_e64 v22, v174, v5, s[2:3]
	v_cmp_lt_i32_e64 s[2:3], 33, v71
	s_nop 1
	v_cndmask_b32_e64 v54, v174, v54, s[2:3]
	v_cmp_lt_i32_e64 s[2:3], s0, v71
	s_movk_i32 s0, 0x61
	v_max_f32_e32 v5, v22, v54
	v_cndmask_b32_e64 v6, v174, v6, s[2:3]
	v_cmp_lt_i32_e64 s[2:3], s0, v71
	s_movk_i32 s0, 0x42
	s_nop 0
	v_cndmask_b32_e64 v38, v174, v38, s[2:3]
	v_max_f32_e32 v79, v6, v38
	v_max3_f32 v4, v4, v5, v79
	v_add_f32_e32 v5, v76, v81
	v_fmac_f32_e32 v5, 0x3e0293ee, v55
	v_add_f32_e32 v55, v76, v158
	v_cmp_lt_i32_e64 s[2:3], 2, v71
	v_fmac_f32_e32 v55, 0x3e0293ee, v7
	v_add_f32_e32 v7, v76, v160
	v_cndmask_b32_e64 v79, v174, v5, s[2:3]
	v_cmp_lt_i32_e64 s[2:3], 34, v71
	v_fmac_f32_e32 v7, 0x3e0293ee, v39
	v_add_f32_e32 v39, v76, v90
	v_cndmask_b32_e64 v55, v174, v55, s[2:3]
	v_cmp_lt_i32_e64 s[2:3], s0, v71
	s_movk_i32 s0, 0x62
	v_fmac_f32_e32 v39, 0x3e0293ee, v23
	v_cndmask_b32_e64 v7, v174, v7, s[2:3]
	v_cmp_lt_i32_e64 s[2:3], s0, v71
	v_max_f32_e32 v5, v79, v55
	s_movk_i32 s0, 0x47
	v_cndmask_b32_e64 v39, v174, v39, s[2:3]
	v_max_f32_e32 v23, v7, v39
	v_max3_f32 v4, v4, v5, v23
	v_add_f32_e32 v5, 0, v156
	v_fmac_f32_e32 v5, 0x3e0293ee, v56
	v_add_f32_e32 v23, 0, v88
	v_cmp_lt_i32_e64 s[2:3], 7, v71
	v_fmac_f32_e32 v23, 0x3e0293ee, v8
	v_add_f32_e32 v8, 0, v162
	v_cndmask_b32_e64 v56, v174, v5, s[2:3]
	v_cmp_lt_i32_e64 s[2:3], 39, v71
	v_fmac_f32_e32 v8, 0x3e0293ee, v40
	v_add_f32_e32 v40, 0, v92
	v_cndmask_b32_e64 v81, v174, v23, s[2:3]
	v_cmp_lt_i32_e64 s[2:3], s0, v71
	s_movk_i32 s0, 0x67
	v_fmac_f32_e32 v40, 0x3e0293ee, v24
	v_cndmask_b32_e64 v8, v174, v8, s[2:3]
	v_cmp_lt_i32_e64 s[2:3], s0, v71
	v_max_f32_e32 v5, v56, v81
	s_movk_i32 s0, 0x48
	v_cndmask_b32_e64 v40, v174, v40, s[2:3]
	v_max_f32_e32 v23, v8, v40
	v_max3_f32 v4, v4, v5, v23
	v_add_f32_e32 v5, v80, v156
	v_add_f32_e32 v23, v80, v88
	v_fmac_f32_e32 v5, 0x3e0293ee, v57
	v_fmac_f32_e32 v23, 0x3e0293ee, v9
	v_add_f32_e32 v9, v80, v162
	v_cmp_lt_i32_e64 s[2:3], 8, v71
	v_fmac_f32_e32 v9, 0x3e0293ee, v41
	v_add_f32_e32 v24, v80, v92
	v_cndmask_b32_e64 v41, v174, v5, s[2:3]
	v_cmp_lt_i32_e64 s[2:3], 40, v71
	v_fmac_f32_e32 v24, 0x3e0293ee, v25
	s_nop 0
	v_cndmask_b32_e64 v57, v174, v23, s[2:3]
	v_cmp_lt_i32_e64 s[2:3], s0, v71
	s_movk_i32 s0, 0x68
	v_max_f32_e32 v5, v41, v57
	v_cndmask_b32_e64 v9, v174, v9, s[2:3]
	v_cmp_lt_i32_e64 s[2:3], s0, v71
	s_movk_i32 s0, 0x49
	s_nop 0
	v_cndmask_b32_e64 v83, v174, v24, s[2:3]
	v_max_f32_e32 v23, v9, v83
	v_max3_f32 v4, v4, v5, v23
	v_add_f32_e32 v5, v78, v156
	v_add_f32_e32 v23, v78, v88
	v_fmac_f32_e32 v5, 0x3e0293ee, v58
	v_fmac_f32_e32 v23, 0x3e0293ee, v10
	v_add_f32_e32 v10, v78, v162
	v_cmp_lt_i32_e64 s[2:3], 9, v71
	v_fmac_f32_e32 v10, 0x3e0293ee, v42
	v_add_f32_e32 v24, v78, v92
	v_cndmask_b32_e64 v42, v174, v5, s[2:3]
	v_cmp_lt_i32_e64 s[2:3], 41, v71
	v_fmac_f32_e32 v24, 0x3e0293ee, v26
	s_nop 0
	v_cndmask_b32_e64 v85, v174, v23, s[2:3]
	v_cmp_lt_i32_e64 s[2:3], s0, v71
	s_movk_i32 s0, 0x69
	v_max_f32_e32 v5, v42, v85
	v_cndmask_b32_e64 v87, v174, v10, s[2:3]
	v_cmp_lt_i32_e64 s[2:3], s0, v71
	v_add_f32_e32 v23, v76, v92
	v_fmac_f32_e32 v23, 0x3e0293ee, v27
	v_cndmask_b32_e64 v89, v174, v24, s[2:3]
	v_max_f32_e32 v10, v87, v89
	v_max3_f32 v4, v4, v5, v10
	v_add_f32_e32 v5, v76, v156
	v_fmac_f32_e32 v5, 0x3e0293ee, v59
	v_add_f32_e32 v10, v76, v88
	v_cmp_lt_i32_e64 s[2:3], 10, v71
	v_fmac_f32_e32 v10, 0x3e0293ee, v11
	v_add_f32_e32 v11, v76, v162
	v_cndmask_b32_e64 v27, v174, v5, s[2:3]
	v_cmp_lt_i32_e64 s[2:3], 42, v71
	s_movk_i32 s0, 0x4a
	v_fmac_f32_e32 v11, 0x3e0293ee, v43
	v_cndmask_b32_e64 v59, v174, v10, s[2:3]
	v_cmp_lt_i32_e64 s[2:3], s0, v71
	s_movk_i32 s0, 0x6a
	v_max_f32_e32 v5, v27, v59
	v_cndmask_b32_e64 v88, v174, v11, s[2:3]
	v_cmp_lt_i32_e64 s[2:3], s0, v71
	v_add_f32_e32 v11, 0, v86
	s_movk_i32 s0, 0x4f
	v_cndmask_b32_e64 v90, v174, v23, s[2:3]
	v_max_f32_e32 v10, v88, v90
	v_max3_f32 v4, v4, v5, v10
	v_add_f32_e32 v5, 0, v82
	v_add_f32_e32 v10, 0, v84
	v_fmac_f32_e32 v5, 0x3e0293ee, v60
	v_fmac_f32_e32 v10, 0x3e0293ee, v12
	v_add_f32_e32 v12, 0, v77
	v_cmp_lt_i32_e64 s[2:3], 15, v71
	v_fmac_f32_e32 v12, 0x3e0293ee, v28
	v_fmac_f32_e32 v11, 0x3e0293ee, v44
	v_cndmask_b32_e64 v28, v174, v5, s[2:3]
	v_cmp_lt_i32_e64 s[2:3], 47, v71
; __device__ __forceinline__ float swapmax(float x) { auto rr = __builtin_amdgcn_permlane32_swap(__float_as_uint(x), __float_as_uint(x), false, false); return fmaxf(__uint_as_float(rr[0]), __uint_as_float(rr[1])); }
; template <int VAR>
; __device__ __forceinline__ void nsa_attn_mfma(Frame& F, bf16* Y) {
;     ...
;       const int nlim = ((t - 31) >> 4) - 4 * hi;
; #pragma unroll
;       for (int r = 0; r < 16; ++r) { const int c = (r & 3) + 8 * (r >> 2);
;         float a0 = fmaf(pA0[r], CSC, ca_[r & 3] + cb_[r >> 2]), a1 = fmaf(pA1[r], CSC, ca_[r & 3] + cb_[4 + (r >> 2)]);
;         float b0 = fmaf(pB0[r], CSC, ca_[r & 3] + cb_[8 + (r >> 2)]), b1 = fmaf(pB1[r], CSC, ca_[r & 3] + cb_[12 + (r >> 2)]);
;         a0 = (c > nlim) ? -1e30f : a0; a1 = (c + 32 > nlim) ? -1e30f : a1;
;         b0 = (c + 64 > nlim) ? -1e30f : b0; b1 = (c + 96 > nlim || (c == 27 && hi)) ? -1e30f : b1;
;         pA0[r] = a0; pA1[r] = a1; pB0[r] = b0; pB1[r] = b1; mx = fmaxf(fmaxf(mx, fmaxf(a0, a1)), fmaxf(b0, b1)); }
;       mx = swapmax(mx);
;       float ps = 0.f;
; #pragma unroll
;       for (int r = 0; r < 16; ++r) { pA0[r] = __builtin_amdgcn_exp2f(pA0[r] - mx); pA1[r] = __builtin_amdgcn_exp2f(pA1[r] - mx); pB0[r] = __builtin_amdgcn_exp2f(pB0[r] - mx); pB1[r] = __builtin_amdgcn_exp2f(pB1[r] - mx);
;         ps += (pA0[r] + pA1[r]) + (pB0[r] + pB1[r]); }
	s_nop 1
	v_cndmask_b32_e64 v44, v174, v10, s[2:3]
	v_cmp_lt_i32_e64 s[2:3], s0, v71
	s_movk_i32 s0, 0x6f
	v_max_f32_e32 v5, v28, v44
	v_cndmask_b32_e64 v60, v174, v11, s[2:3]
	v_cmp_lt_i32_e64 s[2:3], s0, v71
	v_add_f32_e32 v11, v80, v86
	s_movk_i32 s0, 0x50
	v_cndmask_b32_e64 v91, v174, v12, s[2:3]
	v_max_f32_e32 v10, v60, v91
	v_max3_f32 v4, v4, v5, v10
	v_add_f32_e32 v5, v80, v82
	v_fmac_f32_e32 v5, 0x3e0293ee, v61
	v_add_f32_e32 v10, v80, v84
	v_add_f32_e32 v12, v80, v77
	v_cmp_lt_i32_e64 s[2:3], 16, v71
	v_fmac_f32_e32 v10, 0x3e0293ee, v13
	v_fmac_f32_e32 v12, 0x3e0293ee, v29
	v_cndmask_b32_e64 v29, v174, v5, s[2:3]
	v_cmp_lt_i32_e64 s[2:3], 48, v71
	v_fmac_f32_e32 v11, 0x3e0293ee, v45
	s_nop 0
	v_cndmask_b32_e64 v45, v174, v10, s[2:3]
	v_cmp_lt_i32_e64 s[2:3], s0, v71
	s_movk_i32 s0, 0x70
	v_max_f32_e32 v5, v29, v45
	v_cndmask_b32_e64 v92, v174, v11, s[2:3]
	v_cmp_lt_i32_e64 s[2:3], s0, v71
	v_add_f32_e32 v11, v78, v86
	s_movk_i32 s0, 0x51
	v_cndmask_b32_e64 v93, v174, v12, s[2:3]
	v_max_f32_e32 v10, v92, v93
	v_max3_f32 v4, v4, v5, v10
	v_add_f32_e32 v5, v78, v82
	v_fmac_f32_e32 v5, 0x3e0293ee, v62
	v_add_f32_e32 v10, v78, v84
	v_cmp_lt_i32_e64 s[2:3], 17, v71
	v_fmac_f32_e32 v10, 0x3e0293ee, v14
	v_add_f32_e32 v12, v78, v77
	v_cndmask_b32_e64 v14, v174, v5, s[2:3]
	v_cmp_lt_i32_e64 s[2:3], 49, v71
	v_fmac_f32_e32 v11, 0x3e0293ee, v46
	v_fmac_f32_e32 v12, 0x3e0293ee, v30
	v_cndmask_b32_e64 v30, v174, v10, s[2:3]
	v_cmp_lt_i32_e64 s[2:3], s0, v71
	s_movk_i32 s0, 0x71
	v_max_f32_e32 v5, v14, v30
	v_cndmask_b32_e64 v46, v174, v11, s[2:3]
	v_cmp_lt_i32_e64 s[2:3], s0, v71
	v_add_f32_e32 v11, v76, v86
	s_movk_i32 s0, 0x52
	v_cndmask_b32_e64 v94, v174, v12, s[2:3]
	v_max_f32_e32 v10, v46, v94
	v_max3_f32 v4, v4, v5, v10
	v_add_f32_e32 v5, v76, v82
	v_fmac_f32_e32 v5, 0x3e0293ee, v63
	v_add_f32_e32 v10, v76, v84
	v_cmp_lt_i32_e64 s[2:3], 18, v71
	v_fmac_f32_e32 v10, 0x3e0293ee, v15
	v_add_f32_e32 v12, v76, v77
	v_cndmask_b32_e64 v15, v174, v5, s[2:3]
	v_cmp_lt_i32_e64 s[2:3], 50, v71
	v_fmac_f32_e32 v11, 0x3e0293ee, v47
	v_fmac_f32_e32 v12, 0x3e0293ee, v31
	v_cndmask_b32_e64 v31, v174, v10, s[2:3]
	v_cmp_lt_i32_e64 s[2:3], s0, v71
	s_movk_i32 s0, 0x72
	v_max_f32_e32 v5, v15, v31
	v_cndmask_b32_e64 v47, v174, v11, s[2:3]
	v_cmp_lt_i32_e64 s[2:3], s0, v71
	v_add_f32_e32 v11, 0, v74
	s_movk_i32 s0, 0x57
	v_cndmask_b32_e64 v77, v174, v12, s[2:3]
	v_max_f32_e32 v10, v47, v77
	v_max3_f32 v4, v4, v5, v10
	v_add_f32_e32 v5, 0, v70
	v_fmac_f32_e32 v5, 0x3e0293ee, v64
	v_add_f32_e32 v10, 0, v72
	v_cmp_lt_i32_e64 s[2:3], 23, v71
	v_fmac_f32_e32 v10, 0x3e0293ee, v16
	v_add_f32_e32 v12, 0, v2
	v_cndmask_b32_e64 v16, v174, v5, s[2:3]
	v_cmp_lt_i32_e64 s[2:3], 55, v71
	v_fmac_f32_e32 v11, 0x3e0293ee, v48
	v_fmac_f32_e32 v12, 0x3e0293ee, v32
	v_cndmask_b32_e64 v32, v174, v10, s[2:3]
	v_cmp_lt_i32_e64 s[2:3], s0, v71
	s_movk_i32 s0, 0x77
	v_max_f32_e32 v5, v16, v32
	v_cndmask_b32_e64 v48, v174, v11, s[2:3]
	v_cmp_lt_i32_e64 s[2:3], s0, v71
	v_add_f32_e32 v11, v80, v74
	s_movk_i32 s0, 0x58
	v_cndmask_b32_e64 v82, v174, v12, s[2:3]
	v_max_f32_e32 v10, v48, v82
	v_max3_f32 v4, v4, v5, v10
	v_add_f32_e32 v5, v80, v70
	v_fmac_f32_e32 v5, 0x3e0293ee, v65
	v_add_f32_e32 v10, v80, v72
	v_cmp_lt_i32_e64 s[2:3], 24, v71
	v_fmac_f32_e32 v10, 0x3e0293ee, v17
	v_add_f32_e32 v12, v80, v2
	v_cndmask_b32_e64 v17, v174, v5, s[2:3]
	v_cmp_lt_i32_e64 s[2:3], 56, v71
	v_fmac_f32_e32 v11, 0x3e0293ee, v49
	v_fmac_f32_e32 v12, 0x3e0293ee, v33
	v_cndmask_b32_e64 v33, v174, v10, s[2:3]
	v_cmp_lt_i32_e64 s[2:3], s0, v71
	s_movk_i32 s0, 0x78
	v_max_f32_e32 v5, v17, v33
	v_cndmask_b32_e64 v49, v174, v11, s[2:3]
	v_cmp_lt_i32_e64 s[2:3], s0, v71
	v_add_f32_e32 v11, v78, v74
	s_movk_i32 s0, 0x59
	v_cndmask_b32_e64 v80, v174, v12, s[2:3]
	v_max_f32_e32 v10, v49, v80
	v_max3_f32 v4, v4, v5, v10
	v_add_f32_e32 v5, v78, v70
	v_fmac_f32_e32 v5, 0x3e0293ee, v66
	v_add_f32_e32 v10, v78, v72
	v_cmp_lt_i32_e64 s[2:3], 25, v71
	v_fmac_f32_e32 v10, 0x3e0293ee, v18
	v_add_f32_e32 v12, v78, v2
	v_cndmask_b32_e64 v78, v174, v5, s[2:3]
	v_cmp_lt_i32_e64 s[2:3], 57, v71
	v_fmac_f32_e32 v11, 0x3e0293ee, v50
	v_fmac_f32_e32 v12, 0x3e0293ee, v34
	v_cndmask_b32_e64 v84, v174, v10, s[2:3]
	v_cmp_lt_i32_e64 s[2:3], s0, v71
	s_movk_i32 s0, 0x79
	v_max_f32_e32 v5, v78, v84
	v_cndmask_b32_e64 v86, v174, v11, s[2:3]
	v_cmp_lt_i32_e64 s[2:3], s0, v71
	v_add_f32_e32 v11, v76, v74
	s_movk_i32 s0, 0x5a
	v_cndmask_b32_e64 v95, v174, v12, s[2:3]
	v_max_f32_e32 v10, v86, v95
	v_max3_f32 v4, v4, v5, v10
	v_add_f32_e32 v5, v76, v70
	v_fmac_f32_e32 v5, 0x3e0293ee, v67
	v_add_f32_e32 v10, v76, v72
	v_cmp_lt_i32_e64 s[2:3], 26, v71
	v_fmac_f32_e32 v10, 0x3e0293ee, v19
	v_fmac_f32_e32 v11, 0x3e0293ee, v51
	v_cndmask_b32_e64 v67, v174, v5, s[2:3]
	v_cmp_lt_i32_e64 s[2:3], 58, v71
	v_add_f32_e32 v2, v76, v2
	v_fmac_f32_e32 v2, 0x3e0293ee, v35
	v_cndmask_b32_e64 v70, v174, v10, s[2:3]
	v_cmp_lt_i32_e64 s[2:3], s0, v71
	s_movk_i32 s0, 0x7b
	v_max_f32_e32 v5, v67, v70
	v_cndmask_b32_e64 v72, v174, v11, s[2:3]
	v_cmp_gt_i32_e64 s[2:3], s0, v71
	v_readlane_b32 s0, v254, 49
	s_mov_b32 m0, s0
	s_or_b64 vcc, vcc, s[2:3]
	global_load_lds_dwordx4 v[68:69], off
	v_cndmask_b32_e32 v2, v2, v174, vcc
	v_max_f32_e32 v10, v72, v2
	v_max3_f32 v4, v4, v5, v10
	v_mov_b32_e32 v5, v4
	s_nop 1
	v_permlane32_swap_b32_e32 v4, v5
	v_max_f32_e32 v5, v5, v5
	v_max_f32_e32 v4, v4, v4
	v_max_f32_e32 v71, v4, v5
	v_sub_f32_e32 v9, v9, v71
	v_exp_f32_e32 v168, v9
	v_sub_f32_e32 v9, v83, v71
	v_sub_f32_e32 v4, v20, v71
	v_sub_f32_e32 v5, v52, v71
	v_sub_f32_e32 v10, v73, v71
	v_sub_f32_e32 v11, v36, v71
	v_sub_f32_e32 v20, v75, v71
	v_exp_f32_e32 v170, v9
; __device__ __forceinline__ float swapmax(float x) { auto rr = __builtin_amdgcn_permlane32_swap(__float_as_uint(x), __float_as_uint(x), false, false); return fmaxf(__uint_as_float(rr[0]), __uint_as_float(rr[1])); }
; __device__ __forceinline__ float swapsum(float x) { auto rr = __builtin_amdgcn_permlane32_swap(__float_as_uint(x), __float_as_uint(x), false, false); return __uint_as_float(rr[0]) + __uint_as_float(rr[1]); }
; template <int VAR>
; __device__ __forceinline__ void nsa_attn_mfma(Frame& F, bf16* Y) {
;     ...
;       mx = swapmax(mx);
;       float ps = 0.f;
; #pragma unroll
;       for (int r = 0; r < 16; ++r) { pA0[r] = __builtin_amdgcn_exp2f(pA0[r] - mx); pA1[r] = __builtin_amdgcn_exp2f(pA1[r] - mx); pB0[r] = __builtin_amdgcn_exp2f(pB0[r] - mx); pB1[r] = __builtin_amdgcn_exp2f(pB1[r] - mx);
;         ps += (pA0[r] + pA1[r]) + (pB0[r] + pB1[r]); }
;       ps = swapsum(ps);
;       const float anyv = (t >= 31) ? 1.f : 0.f; const float inv = anyv / ps;
;       bf16x8 pa0, pa1, pa2, pa3;
;       bf16x8 pa4, pa5, pa6, pa7;
;       PK4(pA0, 0, pa0); PK4(pA0, 8, pa1); PK4(pA1, 0, pa2); PK4(pA1, 8, pa3);
;       PK4(pB0, 0, pa4); PK4(pB0, 8, pa5); PK4(pB1, 0, pa6); PK4(pB1, 8, pa7);
	v_sub_f32_e32 v9, v42, v71
	v_exp_f32_e32 v4, v4
	v_exp_f32_e32 v5, v5
	v_exp_f32_e32 v10, v10
	v_exp_f32_e32 v12, v11
	v_sub_f32_e32 v11, v21, v71
	v_sub_f32_e32 v13, v53, v71
	v_exp_f32_e32 v23, v20
	v_sub_f32_e32 v20, v37, v71
	v_exp_f32_e32 v163, v9
	v_sub_f32_e32 v9, v85, v71
	v_exp_f32_e32 v11, v11
	v_exp_f32_e32 v13, v13
	v_exp_f32_e32 v24, v20
	v_exp_f32_e32 v164, v9
	v_sub_f32_e32 v9, v87, v71
	v_exp_f32_e32 v165, v9
	v_sub_f32_e32 v9, v89, v71
	v_exp_f32_e32 v166, v9
	v_sub_f32_e32 v9, v27, v71
	v_add_f32_e32 v18, v4, v5
	v_add_f32_e32 v19, v10, v12
	v_sub_f32_e32 v21, v22, v71
	v_sub_f32_e32 v6, v6, v71
	v_exp_f32_e32 v156, v9
	v_sub_f32_e32 v9, v59, v71
	v_add_f32_e32 v18, v18, v19
	v_add_f32_e32 v19, v11, v13
	v_add_f32_e32 v20, v23, v24
	v_exp_f32_e32 v25, v21
	v_sub_f32_e32 v21, v54, v71
	v_exp_f32_e32 v35, v6
	v_sub_f32_e32 v6, v38, v71
	v_exp_f32_e32 v157, v9
	v_sub_f32_e32 v9, v88, v71
	v_exp_f32_e32 v26, v21
	v_exp_f32_e32 v43, v6
	v_add_f32_e32 v6, v19, v20
	v_sub_f32_e32 v20, v79, v71
	v_sub_f32_e32 v7, v7, v71
	v_exp_f32_e32 v158, v9
	v_sub_f32_e32 v9, v90, v71
	v_exp_f32_e32 v58, v20
	v_sub_f32_e32 v20, v55, v71
	v_exp_f32_e32 v154, v7
	v_sub_f32_e32 v7, v39, v71
	v_exp_f32_e32 v155, v9
	v_sub_f32_e32 v9, v28, v71
	v_exp_f32_e32 v152, v20
	v_exp_f32_e32 v39, v7
	v_exp_f32_e32 v61, v9
	v_sub_f32_e32 v9, v44, v71
	v_add_f32_e32 v18, 0, v18
	v_exp_f32_e32 v63, v9
	v_sub_f32_e32 v9, v60, v71
	v_add_f32_e32 v6, v6, v18
	v_add_f32_e32 v18, v25, v26
	v_add_f32_e32 v19, v35, v43
	v_exp_f32_e32 v64, v9
	v_sub_f32_e32 v9, v91, v71
	v_add_f32_e32 v7, v18, v19
	v_sub_f32_e32 v19, v56, v71
	v_sub_f32_e32 v8, v8, v71
	v_exp_f32_e32 v66, v9
	v_sub_f32_e32 v9, v29, v71
	v_add_f32_e32 v6, v7, v6
	v_add_f32_e32 v7, v58, v152
	v_add_f32_e32 v18, v154, v39
	v_exp_f32_e32 v62, v19
	v_sub_f32_e32 v19, v81, v71
	v_exp_f32_e32 v159, v8
	v_sub_f32_e32 v8, v40, v71
	v_exp_f32_e32 v50, v9
	v_sub_f32_e32 v9, v45, v71
	v_exp_f32_e32 v65, v19
	v_exp_f32_e32 v161, v8
	v_add_f32_e32 v7, v7, v18
	v_sub_f32_e32 v18, v41, v71
	v_exp_f32_e32 v51, v9
	v_sub_f32_e32 v9, v92, v71
	v_exp_f32_e32 v160, v18
	v_sub_f32_e32 v18, v57, v71
	v_exp_f32_e32 v56, v9
	v_sub_f32_e32 v9, v93, v71
	v_exp_f32_e32 v162, v18
	v_exp_f32_e32 v57, v9
	v_sub_f32_e32 v9, v14, v71
	v_exp_f32_e32 v42, v9
	v_sub_f32_e32 v9, v30, v71
	v_add_f32_e32 v6, v7, v6
	v_add_f32_e32 v7, v62, v65
	v_add_f32_e32 v8, v159, v161
	v_exp_f32_e32 v44, v9
	v_sub_f32_e32 v9, v46, v71
	v_add_f32_e32 v7, v7, v8
	v_exp_f32_e32 v45, v9
	v_sub_f32_e32 v9, v94, v71
	v_add_f32_e32 v6, v7, v6
	v_add_f32_e32 v7, v160, v162
	v_add_f32_e32 v8, v168, v170
	v_exp_f32_e32 v46, v9
	v_sub_f32_e32 v9, v15, v71
	v_add_f32_e32 v7, v7, v8
	v_exp_f32_e32 v36, v9
	v_sub_f32_e32 v9, v31, v71
	v_add_f32_e32 v6, v7, v6
	v_add_f32_e32 v7, v163, v164
	v_add_f32_e32 v8, v165, v166
	v_exp_f32_e32 v37, v9
	v_sub_f32_e32 v9, v47, v71
	v_add_f32_e32 v7, v7, v8
	v_exp_f32_e32 v38, v9
	v_sub_f32_e32 v9, v77, v71
	v_add_f32_e32 v6, v7, v6
	v_add_f32_e32 v7, v156, v157
	v_add_f32_e32 v8, v158, v155
	v_exp_f32_e32 v34, v9
	v_sub_f32_e32 v9, v16, v71
	v_add_f32_e32 v7, v7, v8
	v_exp_f32_e32 v27, v9
	v_sub_f32_e32 v9, v32, v71
	v_add_f32_e32 v6, v7, v6
	v_add_f32_e32 v7, v61, v63
	v_add_f32_e32 v8, v64, v66
	v_exp_f32_e32 v28, v9
	v_sub_f32_e32 v9, v48, v71
	v_add_f32_e32 v7, v7, v8
	v_exp_f32_e32 v29, v9
	v_sub_f32_e32 v9, v82, v71
	v_add_f32_e32 v6, v7, v6
	v_add_f32_e32 v7, v50, v51
	v_add_f32_e32 v8, v56, v57
	v_exp_f32_e32 v30, v9
	v_sub_f32_e32 v9, v17, v71
	v_add_f32_e32 v7, v7, v8
	v_exp_f32_e32 v18, v9
	v_sub_f32_e32 v9, v33, v71
	v_add_f32_e32 v6, v7, v6
	v_add_f32_e32 v7, v42, v44
	v_add_f32_e32 v8, v45, v46
	v_exp_f32_e32 v19, v9
	v_sub_f32_e32 v9, v49, v71
	v_add_f32_e32 v7, v7, v8
	v_exp_f32_e32 v20, v9
	v_sub_f32_e32 v9, v80, v71
	v_add_f32_e32 v6, v7, v6
	v_add_f32_e32 v7, v36, v37
	v_add_f32_e32 v8, v38, v34
	v_exp_f32_e32 v22, v9
	v_add_f32_e32 v7, v7, v8
	v_sub_f32_e32 v9, v78, v71
	v_add_f32_e32 v6, v7, v6
	v_add_f32_e32 v7, v27, v28
	v_add_f32_e32 v8, v29, v30
	v_exp_f32_e32 v14, v9
	v_sub_f32_e32 v9, v84, v71
	v_add_f32_e32 v7, v7, v8
	v_exp_f32_e32 v15, v9
	v_sub_f32_e32 v9, v86, v71
	v_add_f32_e32 v6, v7, v6
	v_add_f32_e32 v7, v18, v19
	v_add_f32_e32 v8, v20, v22
	v_exp_f32_e32 v16, v9
	v_sub_f32_e32 v9, v95, v71
	v_exp_f32_e32 v17, v9
	v_add_f32_e32 v7, v7, v8
	v_add_f32_e32 v21, v7, v6
	v_sub_f32_e32 v6, v67, v71
	v_sub_f32_e32 v7, v70, v71
	v_sub_f32_e32 v8, v72, v71
	v_sub_f32_e32 v2, v2, v71
	v_exp_f32_e32 v6, v6
	v_exp_f32_e32 v7, v7
	v_exp_f32_e32 v8, v8
	v_exp_f32_e32 v9, v2
	v_add_f32_e32 v31, v14, v15
	v_add_f32_e32 v32, v16, v17
	v_add_f32_e32 v2, v31, v32
	v_add_f32_e32 v2, v2, v21
	v_add_f32_e32 v21, v6, v7
	v_add_f32_e32 v31, v8, v9
	v_add_f32_e32 v21, v21, v31
	v_add_f32_e32 v2, v21, v2
	v_mov_b32_e32 v21, v2
	s_nop 1
	v_permlane32_swap_b32_e32 v2, v21
	v_cmp_lt_i32_e32 vcc, 30, v181
	v_add_f32_e32 v2, v2, v21
	v_cvt_pk_bf16_f32 v52, v4, v11
	v_cvt_pk_bf16_f32 v53, v25, v58
	v_cvt_pk_bf16_f32 v54, v62, v160
	v_cvt_pk_bf16_f32 v55, v163, v156
	s_nop 0
	v_cndmask_b32_e64 v21, 0, 1.0, vcc
	v_div_scale_f32 v31, s[0:1], v2, v2, v21
	v_rcp_f32_e32 v32, v31
	v_cvt_pk_bf16_f32 v92, v61, v50
	v_cvt_pk_bf16_f32 v93, v42, v36
	v_cvt_pk_bf16_f32 v94, v27, v18
	v_cvt_pk_bf16_f32 v95, v14, v6
	v_cvt_pk_bf16_f32 v88, v5, v13
	s_nop 0
	v_fma_f32 v33, -v31, v32, 1.0
	v_fmac_f32_e32 v32, v33, v32
	v_div_scale_f32 v33, vcc, v21, v2, v21
	v_mul_f32_e32 v40, v33, v32
	v_fma_f32 v41, -v31, v40, v33
	v_fmac_f32_e32 v40, v41, v32
	v_fma_f32 v31, -v31, v40, v33
	v_div_fmas_f32 v31, v31, v32, v40
	v_cvt_pk_bf16_f32 v89, v26, v152
; #define SBAR() __builtin_amdgcn_sched_barrier(0)
; template <int VAR>
; __device__ __forceinline__ void nsa_attn_mfma(Frame& F, bf16* Y) {
;     ...
;       const float anyv = (t >= 31) ? 1.f : 0.f; const float inv = anyv / ps;
;       bf16x8 pa0, pa1, pa2, pa3;
;       bf16x8 pa4, pa5, pa6, pa7;
;       PK4(pA0, 0, pa0); PK4(pA0, 8, pa1); PK4(pA1, 0, pa2); PK4(pA1, 8, pa3);
;       PK4(pB0, 0, pa4); PK4(pB0, 8, pa5); PK4(pB1, 0, pa6); PK4(pB1, 8, pa7);
;       SBAR();
;       if (cur <= 15) {
;         if (lane == 0) { mkl[4 * wid + 0] = 0xffffffffu; mkl[4 * wid + 1] = 0xffffffffu; mkl[4 * wid + 2] = 0xffffffffu; mkl[4 * wid + 3] = 0xffffffffu; }
;       } else {
; #pragma unroll
;       for (int r = 0; r < 16; ++r) {
;         float a0 = pA0[r] * inv, a1 = pA1[r] * inv, b0 = pB0[r] * inv, b1 = pB1[r] * inv;
;         a0 += __shfl_xor(a0, 1); a1 += __shfl_xor(a1, 1); b0 += __shfl_xor(b0, 1); b1 += __shfl_xor(b1, 1);
;         a0 += __shfl_xor(a0, 2); a1 += __shfl_xor(a1, 2); b0 += __shfl_xor(b0, 2); b1 += __shfl_xor(b1, 2);
;         a0 += __shfl_xor(a0, 4); a1 += __shfl_xor(a1, 4); b0 += __shfl_xor(b0, 4); b1 += __shfl_xor(b1, 4);
;         pA0[r] = a0; pA1[r] = a1; pB0[r] = b0; pB1[r] = b1; }
	v_cvt_pk_bf16_f32 v90, v65, v162
	v_cvt_pk_bf16_f32 v91, v164, v157
	v_cvt_pk_bf16_f32 v84, v63, v51
	v_cvt_pk_bf16_f32 v85, v44, v37
	v_cvt_pk_bf16_f32 v86, v28, v19
	v_cvt_pk_bf16_f32 v87, v15, v7
	v_cvt_pk_bf16_f32 v68, v10, v23
	v_cvt_pk_bf16_f32 v69, v35, v154
	v_cvt_pk_bf16_f32 v70, v159, v168
	v_cvt_pk_bf16_f32 v71, v165, v158
	v_cvt_pk_bf16_f32 v72, v64, v56
	v_cvt_pk_bf16_f32 v73, v45, v38
	v_cvt_pk_bf16_f32 v74, v29, v20
	v_cvt_pk_bf16_f32 v75, v16, v8
	v_cvt_pk_bf16_f32 v76, v12, v24
	v_cvt_pk_bf16_f32 v77, v43, v39
	v_cvt_pk_bf16_f32 v78, v161, v170
	v_cvt_pk_bf16_f32 v79, v166, v155
	v_cvt_pk_bf16_f32 v80, v66, v57
	v_cvt_pk_bf16_f32 v81, v46, v34
	v_cvt_pk_bf16_f32 v82, v30, v22
	v_cvt_pk_bf16_f32 v83, v17, v9
	v_div_fixup_f32 v2, v31, v2, v21
	v_permlane32_swap_b32_e32 v52, v54
	v_permlane32_swap_b32_e32 v53, v55
	v_permlane32_swap_b32_e32 v92, v94
	v_permlane32_swap_b32_e32 v93, v95
	v_permlane32_swap_b32_e32 v88, v90
	v_permlane32_swap_b32_e32 v89, v91
	v_permlane32_swap_b32_e32 v84, v86
	v_permlane32_swap_b32_e32 v85, v87
	v_permlane32_swap_b32_e32 v68, v70
	v_permlane32_swap_b32_e32 v69, v71
	v_permlane32_swap_b32_e32 v72, v74
	v_permlane32_swap_b32_e32 v73, v75
	v_permlane32_swap_b32_e32 v76, v78
	v_permlane32_swap_b32_e32 v77, v79
	v_permlane32_swap_b32_e32 v80, v82
	v_permlane32_swap_b32_e32 v81, v83
	s_mov_b64 s[0:1], -1
	s_cmp_lt_u32 s4, 32
	v_cmp_gt_u32_e32 vcc, 32, v178
	s_cbranch_scc1 .LBB0_859
	v_and_b32_e32 v31, 64, v175
	v_xor_b32_e32 v21, 1, v175
	v_add_u32_e32 v41, 64, v31
	v_cmp_lt_i32_e64 s[2:3], v21, v41
	v_mul_f32_e32 v31, v2, v4
	v_mul_f32_e32 v32, v2, v5
	v_cndmask_b32_e64 v21, v175, v21, s[2:3]
	v_lshlrev_b32_e32 v60, 2, v21
	v_mul_f32_e32 v33, v2, v10
	v_mul_f32_e32 v40, v2, v12
	ds_bpermute_b32 v31, v60, v31
	ds_bpermute_b32 v32, v60, v32
	ds_bpermute_b32 v33, v60, v33
	ds_bpermute_b32 v40, v60, v40
	v_xor_b32_e32 v21, 2, v175
	v_cmp_lt_i32_e64 s[2:3], v21, v41
	s_waitcnt lgkmcnt(0)
	v_fmac_f32_e32 v31, v2, v4
	v_fmac_f32_e32 v32, v2, v5
	v_cndmask_b32_e64 v21, v175, v21, s[2:3]
	v_lshlrev_b32_e32 v59, 2, v21
	v_fmac_f32_e32 v33, v2, v10
	v_fmac_f32_e32 v40, v2, v12
	ds_bpermute_b32 v4, v59, v31
	ds_bpermute_b32 v5, v59, v32
	ds_bpermute_b32 v12, v59, v33
	ds_bpermute_b32 v47, v59, v40
	v_xor_b32_e32 v21, 4, v175
	v_cmp_lt_i32_e64 s[2:3], v21, v41
	s_waitcnt lgkmcnt(0)
	v_add_f32_e32 v4, v31, v4
	v_add_f32_e32 v10, v32, v5
	v_cndmask_b32_e64 v21, v175, v21, s[2:3]
	v_lshlrev_b32_e32 v139, 2, v21
	v_add_f32_e32 v21, v33, v12
	v_add_f32_e32 v32, v40, v47
	v_mul_f32_e32 v31, v2, v11
	v_mul_f32_e32 v33, v2, v13
	v_mul_f32_e32 v40, v2, v23
	v_mul_f32_e32 v47, v2, v24
	ds_bpermute_b32 v48, v60, v31
	ds_bpermute_b32 v33, v60, v33
	ds_bpermute_b32 v40, v60, v40
	ds_bpermute_b32 v49, v60, v47
	v_mul_f32_e32 v153, v2, v43
	s_waitcnt lgkmcnt(0)
	v_fmac_f32_e32 v48, v2, v11
	v_fmac_f32_e32 v33, v2, v13
	v_fmac_f32_e32 v40, v2, v23
	v_fmac_f32_e32 v49, v2, v24
	ds_bpermute_b32 v11, v59, v48
	ds_bpermute_b32 v13, v59, v33
	ds_bpermute_b32 v24, v59, v40
	ds_bpermute_b32 v67, v59, v49
	ds_bpermute_b32 v153, v60, v153
	s_waitcnt lgkmcnt(0)
	v_add_f32_e32 v11, v48, v11
	v_add_f32_e32 v23, v33, v13
	v_add_f32_e32 v33, v40, v24
	v_add_f32_e32 v48, v49, v67
	v_mul_f32_e32 v40, v2, v25
	v_mul_f32_e32 v49, v2, v26
	v_mul_f32_e32 v67, v2, v35
	ds_bpermute_b32 v167, v60, v40
	ds_bpermute_b32 v49, v60, v49
	ds_bpermute_b32 v169, v60, v67
	v_fmac_f32_e32 v153, v2, v43
	ds_bpermute_b32 v171, v59, v153
	s_waitcnt lgkmcnt(0)
	v_fmac_f32_e32 v167, v2, v25
	v_fmac_f32_e32 v49, v2, v26
	v_fmac_f32_e32 v169, v2, v35
	ds_bpermute_b32 v25, v59, v167
	ds_bpermute_b32 v26, v59, v49
	ds_bpermute_b32 v43, v59, v169
	v_add_f32_e32 v153, v153, v171
	v_mul_f32_e32 v191, v2, v39
	s_waitcnt lgkmcnt(0)
	v_add_f32_e32 v25, v167, v25
	v_add_f32_e32 v35, v49, v26
	v_add_f32_e32 v49, v169, v43
	v_mul_f32_e32 v43, v2, v58
	v_mul_f32_e32 v167, v2, v152
	v_mul_f32_e32 v169, v2, v154
	ds_bpermute_b32 v171, v60, v43
	ds_bpermute_b32 v167, v60, v167
	ds_bpermute_b32 v169, v60, v169
	v_mul_f32_e32 v199, v2, v166
	ds_bpermute_b32 v199, v60, v199
	s_waitcnt lgkmcnt(0)
	v_fmac_f32_e32 v171, v2, v58
	v_fmac_f32_e32 v167, v2, v152
	v_fmac_f32_e32 v169, v2, v154
	ds_bpermute_b32 v58, v60, v191
	ds_bpermute_b32 v154, v59, v171
	ds_bpermute_b32 v191, v59, v167
	ds_bpermute_b32 v192, v59, v169
	v_fmac_f32_e32 v199, v2, v166
	s_waitcnt lgkmcnt(0)
	v_fmac_f32_e32 v58, v2, v39
	v_add_f32_e32 v39, v171, v154
	v_add_f32_e32 v154, v167, v191
	v_add_f32_e32 v169, v169, v192
	ds_bpermute_b32 v171, v59, v58
	ds_bpermute_b32 v191, v139, v39
	ds_bpermute_b32 v192, v139, v154
	ds_bpermute_b32 v193, v139, v169
	ds_bpermute_b32 v202, v59, v199
	s_waitcnt lgkmcnt(0)
	v_add_f32_e32 v171, v58, v171
	v_add_f32_e32 v39, v39, v191
	v_add_f32_e32 v58, v154, v192
	v_add_f32_e32 v154, v169, v193
	v_mul_f32_e32 v169, v2, v62
	v_mul_f32_e32 v191, v2, v65
	v_mul_f32_e32 v192, v2, v159
	v_mul_f32_e32 v193, v2, v161
	ds_bpermute_b32 v169, v60, v169
	ds_bpermute_b32 v191, v60, v191
	ds_bpermute_b32 v192, v60, v192
	ds_bpermute_b32 v193, v60, v193
	ds_bpermute_b32 v194, v139, v171
	s_waitcnt lgkmcnt(0)
	v_fmac_f32_e32 v169, v2, v62
	v_fmac_f32_e32 v191, v2, v65
	v_fmac_f32_e32 v192, v2, v159
	v_fmac_f32_e32 v193, v2, v161
	ds_bpermute_b32 v62, v59, v169
	ds_bpermute_b32 v65, v59, v191
	ds_bpermute_b32 v161, v59, v192
	ds_bpermute_b32 v195, v59, v193
	v_add_f32_e32 v171, v171, v194
	s_waitcnt lgkmcnt(0)
; template <int VAR>
; __device__ __forceinline__ void nsa_attn_mfma(Frame& F, bf16* Y) {
;     ...
; #pragma unroll
;       for (int r = 0; r < 16; ++r) {
;         float a0 = pA0[r] * inv, a1 = pA1[r] * inv, b0 = pB0[r] * inv, b1 = pB1[r] * inv;
;         a0 += __shfl_xor(a0, 1); a1 += __shfl_xor(a1, 1); b0 += __shfl_xor(b0, 1); b1 += __shfl_xor(b1, 1);
;         a0 += __shfl_xor(a0, 2); a1 += __shfl_xor(a1, 2); b0 += __shfl_xor(b0, 2); b1 += __shfl_xor(b1, 2);
;         a0 += __shfl_xor(a0, 4); a1 += __shfl_xor(a1, 4); b0 += __shfl_xor(b0, 4); b1 += __shfl_xor(b1, 4);
;         pA0[r] = a0; pA1[r] = a1; pB0[r] = b0; pB1[r] = b1; }
	v_add_f32_e32 v62, v169, v62
	v_add_f32_e32 v159, v191, v65
	v_add_f32_e32 v169, v192, v161
	v_add_f32_e32 v192, v193, v195
	v_mul_f32_e32 v191, v2, v160
	v_mul_f32_e32 v193, v2, v162
	v_mul_f32_e32 v194, v2, v168
	v_mul_f32_e32 v195, v2, v170
	ds_bpermute_b32 v196, v60, v191
	ds_bpermute_b32 v193, v60, v193
	ds_bpermute_b32 v194, v60, v194
	ds_bpermute_b32 v197, v60, v195
	v_add_f32_e32 v199, v199, v202
	s_waitcnt lgkmcnt(0)
	v_fmac_f32_e32 v196, v2, v160
	v_fmac_f32_e32 v193, v2, v162
	v_fmac_f32_e32 v194, v2, v168
	v_fmac_f32_e32 v197, v2, v170
	ds_bpermute_b32 v160, v59, v196
	ds_bpermute_b32 v162, v59, v193
	ds_bpermute_b32 v170, v59, v194
	ds_bpermute_b32 v198, v59, v197
	v_mul_f32_e32 v203, v2, v155
	s_waitcnt lgkmcnt(0)
	v_add_f32_e32 v160, v196, v160
	v_add_f32_e32 v168, v193, v162
	v_add_f32_e32 v193, v194, v170
	v_add_f32_e32 v196, v197, v198
	v_mul_f32_e32 v194, v2, v163
	v_mul_f32_e32 v197, v2, v164
	v_mul_f32_e32 v198, v2, v165
	ds_bpermute_b32 v200, v60, v194
	ds_bpermute_b32 v197, v60, v197
	ds_bpermute_b32 v201, v60, v198
	v_mul_f32_e32 v211, v2, v46
	ds_bpermute_b32 v211, v60, v211
	s_waitcnt lgkmcnt(0)
	v_fmac_f32_e32 v200, v2, v163
	v_fmac_f32_e32 v197, v2, v164
	v_fmac_f32_e32 v201, v2, v165
	ds_bpermute_b32 v163, v59, v200
	ds_bpermute_b32 v164, v59, v197
	ds_bpermute_b32 v166, v59, v201
	v_fmac_f32_e32 v211, v2, v46
	ds_bpermute_b32 v214, v59, v211
	s_waitcnt lgkmcnt(0)
	v_add_f32_e32 v163, v200, v163
	v_add_f32_e32 v165, v197, v164
	v_add_f32_e32 v197, v201, v166
	v_mul_f32_e32 v166, v2, v156
	v_mul_f32_e32 v200, v2, v157
	v_mul_f32_e32 v201, v2, v158
	ds_bpermute_b32 v202, v60, v166
	ds_bpermute_b32 v200, v60, v200
	ds_bpermute_b32 v201, v60, v201
	v_add_f32_e32 v211, v211, v214
	v_mul_f32_e32 v215, v2, v34
	s_waitcnt lgkmcnt(0)
	v_fmac_f32_e32 v202, v2, v156
	v_fmac_f32_e32 v200, v2, v157
	v_fmac_f32_e32 v201, v2, v158
	ds_bpermute_b32 v156, v60, v203
	ds_bpermute_b32 v158, v59, v202
	ds_bpermute_b32 v203, v59, v200
	ds_bpermute_b32 v204, v59, v201
	v_mul_f32_e32 v224, v2, v17
	s_waitcnt lgkmcnt(0)
	v_fmac_f32_e32 v156, v2, v155
	v_add_f32_e32 v155, v202, v158
	v_add_f32_e32 v158, v200, v203
	v_add_f32_e32 v201, v201, v204
	ds_bpermute_b32 v202, v59, v156
	ds_bpermute_b32 v203, v139, v155
	ds_bpermute_b32 v204, v139, v158
	ds_bpermute_b32 v205, v139, v201
	ds_bpermute_b32 v226, v60, v224
	s_waitcnt lgkmcnt(0)
	v_add_f32_e32 v202, v156, v202
	v_add_f32_e32 v155, v155, v203
	v_add_f32_e32 v156, v158, v204
	v_add_f32_e32 v158, v201, v205
	v_mul_f32_e32 v201, v2, v61
	v_mul_f32_e32 v203, v2, v63
	v_mul_f32_e32 v204, v2, v64
	v_mul_f32_e32 v205, v2, v66
	ds_bpermute_b32 v201, v60, v201
	ds_bpermute_b32 v203, v60, v203
	ds_bpermute_b32 v204, v60, v204
	ds_bpermute_b32 v205, v60, v205
	ds_bpermute_b32 v206, v139, v202
	s_waitcnt lgkmcnt(0)
	v_fmac_f32_e32 v201, v2, v61
	v_fmac_f32_e32 v203, v2, v63
	v_fmac_f32_e32 v204, v2, v64
	v_fmac_f32_e32 v205, v2, v66
	ds_bpermute_b32 v61, v59, v201
	ds_bpermute_b32 v63, v59, v203
	ds_bpermute_b32 v66, v59, v204
	ds_bpermute_b32 v207, v59, v205
	v_add_f32_e32 v202, v202, v206
	s_waitcnt lgkmcnt(0)
	v_add_f32_e32 v61, v201, v61
	v_add_f32_e32 v64, v203, v63
	v_add_f32_e32 v201, v204, v66
	v_add_f32_e32 v204, v205, v207
	v_mul_f32_e32 v203, v2, v50
	v_mul_f32_e32 v205, v2, v51
	v_mul_f32_e32 v206, v2, v56
	v_mul_f32_e32 v207, v2, v57
	ds_bpermute_b32 v208, v60, v203
	ds_bpermute_b32 v205, v60, v205
	ds_bpermute_b32 v206, v60, v206
	ds_bpermute_b32 v209, v60, v207
	v_fmac_f32_e32 v226, v2, v17
	s_waitcnt lgkmcnt(0)
	v_fmac_f32_e32 v208, v2, v50
	v_fmac_f32_e32 v205, v2, v51
	v_fmac_f32_e32 v206, v2, v56
	v_fmac_f32_e32 v209, v2, v57
	ds_bpermute_b32 v50, v59, v208
	ds_bpermute_b32 v51, v59, v205
	ds_bpermute_b32 v57, v59, v206
	ds_bpermute_b32 v210, v59, v209
	ds_bpermute_b32 v227, v59, v226
	s_waitcnt lgkmcnt(0)
	v_add_f32_e32 v50, v208, v50
	v_add_f32_e32 v56, v205, v51
	v_add_f32_e32 v205, v206, v57
	v_add_f32_e32 v208, v209, v210
	v_mul_f32_e32 v206, v2, v42
	v_mul_f32_e32 v209, v2, v44
	v_mul_f32_e32 v210, v2, v45
	ds_bpermute_b32 v212, v60, v206
	ds_bpermute_b32 v209, v60, v209
	ds_bpermute_b32 v213, v60, v210
	v_add_f32_e32 v226, v226, v227
	v_mul_f32_e32 v227, v2, v9
	s_waitcnt lgkmcnt(0)
	v_fmac_f32_e32 v212, v2, v42
	v_fmac_f32_e32 v209, v2, v44
	v_fmac_f32_e32 v213, v2, v45
	ds_bpermute_b32 v42, v59, v212
	ds_bpermute_b32 v44, v59, v209
	ds_bpermute_b32 v46, v59, v213
	ds_bpermute_b32 v5, v139, v4
	ds_bpermute_b32 v12, v139, v10
	s_waitcnt lgkmcnt(0)
	v_add_f32_e32 v42, v212, v42
	v_add_f32_e32 v45, v209, v44
	v_add_f32_e32 v209, v213, v46
	v_mul_f32_e32 v46, v2, v36
	v_mul_f32_e32 v212, v2, v37
	v_mul_f32_e32 v213, v2, v38
	ds_bpermute_b32 v214, v60, v46
	ds_bpermute_b32 v212, v60, v212
	ds_bpermute_b32 v213, v60, v213
	ds_bpermute_b32 v31, v139, v21
	ds_bpermute_b32 v47, v139, v32
	s_waitcnt lgkmcnt(0)
	v_fmac_f32_e32 v214, v2, v36
	v_fmac_f32_e32 v212, v2, v37
	v_fmac_f32_e32 v213, v2, v38
	ds_bpermute_b32 v36, v60, v215
	ds_bpermute_b32 v38, v59, v214
	ds_bpermute_b32 v215, v59, v212
	ds_bpermute_b32 v217, v59, v213
	ds_bpermute_b32 v13, v139, v11
	s_waitcnt lgkmcnt(0)
	v_fmac_f32_e32 v36, v2, v34
	v_add_f32_e32 v34, v214, v38
	v_add_f32_e32 v38, v212, v215
	v_add_f32_e32 v213, v213, v217
	ds_bpermute_b32 v214, v59, v36
	ds_bpermute_b32 v215, v139, v34
	ds_bpermute_b32 v217, v139, v38
	ds_bpermute_b32 v218, v139, v213
	ds_bpermute_b32 v24, v139, v23
	s_waitcnt lgkmcnt(0)
; template <int VAR>
; __device__ __forceinline__ void nsa_attn_mfma(Frame& F, bf16* Y) {
;     ...
;       for (int r = 0; r < 16; ++r) {
;         float a0 = pA0[r] * inv, a1 = pA1[r] * inv, b0 = pB0[r] * inv, b1 = pB1[r] * inv;
;         a0 += __shfl_xor(a0, 1); a1 += __shfl_xor(a1, 1); b0 += __shfl_xor(b0, 1); b1 += __shfl_xor(b1, 1);
;         a0 += __shfl_xor(a0, 2); a1 += __shfl_xor(a1, 2); b0 += __shfl_xor(b0, 2); b1 += __shfl_xor(b1, 2);
;         a0 += __shfl_xor(a0, 4); a1 += __shfl_xor(a1, 4); b0 += __shfl_xor(b0, 4); b1 += __shfl_xor(b1, 4);
;         pA0[r] = a0; pA1[r] = a1; pB0[r] = b0; pB1[r] = b1; }
;       float slc[16];
; #pragma unroll
;       for (int T = 0; T < 4; ++T)
; #pragma unroll
;         for (int q = 0; q < 4; ++q) {
;           const f32x16& P = (T == 0) ? pA0 : (T == 1) ? pA1 : (T == 2) ? pB0 : pB1;
;           slc[T * 4 + q] = 2.f * (P[4 * q] + P[4 * q + 1] + P[4 * q + 2]) + P[4 * q + 3];
;           float a;
;           if (q > 0) a = P[4 * (q - 1) + 3];
;           else if (T > 0) { const f32x16& Pm = (T == 1) ? pA0 : (T == 2) ? pA1 : pB0; a = Pm[15]; }
;           else a = 0.f;
;           const float give = hi ? a : P[4 * q + 3];
;           slc[T * 4 + q] += __shfl_xor(give, 32); }
;       if (j == 0) {
	v_add_f32_e32 v214, v36, v214
	v_add_f32_e32 v34, v34, v215
	v_add_f32_e32 v36, v38, v217
	v_add_f32_e32 v38, v213, v218
	v_mul_f32_e32 v213, v2, v27
	v_mul_f32_e32 v215, v2, v28
	v_mul_f32_e32 v217, v2, v29
	v_mul_f32_e32 v218, v2, v30
	ds_bpermute_b32 v213, v60, v213
	ds_bpermute_b32 v215, v60, v215
	ds_bpermute_b32 v217, v60, v217
	ds_bpermute_b32 v218, v60, v218
	ds_bpermute_b32 v219, v139, v214
	s_waitcnt lgkmcnt(0)
	v_fmac_f32_e32 v213, v2, v27
	v_fmac_f32_e32 v215, v2, v28
	v_fmac_f32_e32 v217, v2, v29
	v_fmac_f32_e32 v218, v2, v30
	ds_bpermute_b32 v27, v59, v213
	ds_bpermute_b32 v28, v59, v215
	ds_bpermute_b32 v30, v59, v217
	ds_bpermute_b32 v220, v59, v218
	v_add_f32_e32 v214, v214, v219
	s_waitcnt lgkmcnt(0)
	v_add_f32_e32 v27, v213, v27
	v_add_f32_e32 v29, v215, v28
	v_add_f32_e32 v213, v217, v30
	v_add_f32_e32 v217, v218, v220
	v_mul_f32_e32 v215, v2, v18
	v_mul_f32_e32 v220, v2, v22
	v_mul_f32_e32 v218, v2, v19
	v_mul_f32_e32 v219, v2, v20
	ds_bpermute_b32 v221, v60, v215
	ds_bpermute_b32 v222, v60, v220
	ds_bpermute_b32 v218, v60, v218
	ds_bpermute_b32 v219, v60, v219
	ds_bpermute_b32 v40, v139, v33
	s_waitcnt lgkmcnt(0)
	v_fmac_f32_e32 v221, v2, v18
	v_fmac_f32_e32 v222, v2, v22
	v_fmac_f32_e32 v218, v2, v19
	v_fmac_f32_e32 v219, v2, v20
	ds_bpermute_b32 v18, v59, v221
	ds_bpermute_b32 v223, v59, v222
	ds_bpermute_b32 v19, v59, v218
	ds_bpermute_b32 v22, v59, v219
	ds_bpermute_b32 v67, v139, v48
	s_waitcnt lgkmcnt(0)
	v_add_f32_e32 v18, v221, v18
	v_add_f32_e32 v221, v222, v223
	v_mul_f32_e32 v222, v2, v15
	v_mul_f32_e32 v223, v2, v16
	v_add_f32_e32 v20, v218, v19
	v_add_f32_e32 v218, v219, v22
	v_mul_f32_e32 v219, v2, v14
	ds_bpermute_b32 v222, v60, v222
	ds_bpermute_b32 v223, v60, v223
	ds_bpermute_b32 v225, v60, v219
	ds_bpermute_b32 v26, v139, v25
	ds_bpermute_b32 v43, v139, v35
	s_waitcnt lgkmcnt(0)
	v_fmac_f32_e32 v222, v2, v15
	v_fmac_f32_e32 v223, v2, v16
	v_fmac_f32_e32 v225, v2, v14
	ds_bpermute_b32 v15, v59, v222
	ds_bpermute_b32 v17, v59, v223
	ds_bpermute_b32 v14, v59, v225
	ds_bpermute_b32 v152, v139, v49
	ds_bpermute_b32 v167, v139, v153
	s_waitcnt lgkmcnt(0)
	v_add_f32_e32 v16, v222, v15
	v_add_f32_e32 v222, v223, v17
	v_mul_f32_e32 v17, v2, v6
	v_add_f32_e32 v14, v225, v14
	v_mul_f32_e32 v225, v2, v8
	ds_bpermute_b32 v228, v60, v17
	v_mul_f32_e32 v223, v2, v7
	ds_bpermute_b32 v225, v60, v225
	ds_bpermute_b32 v223, v60, v223
	ds_bpermute_b32 v60, v60, v227
	s_waitcnt lgkmcnt(0)
	v_fmac_f32_e32 v228, v2, v6
	ds_bpermute_b32 v6, v59, v228
	v_fmac_f32_e32 v225, v2, v8
	v_fmac_f32_e32 v223, v2, v7
	v_fmac_f32_e32 v60, v2, v9
	ds_bpermute_b32 v8, v59, v225
	ds_bpermute_b32 v7, v59, v223
	ds_bpermute_b32 v9, v59, v60
	s_waitcnt lgkmcnt(0)
	v_add_f32_e32 v6, v228, v6
	ds_bpermute_b32 v65, v139, v62
	v_add_f32_e32 v59, v225, v8
	ds_bpermute_b32 v8, v139, v6
	v_add_f32_e32 v7, v223, v7
	v_add_f32_e32 v9, v60, v9
	ds_bpermute_b32 v60, v139, v7
	ds_bpermute_b32 v223, v139, v59
	ds_bpermute_b32 v225, v139, v9
	s_waitcnt lgkmcnt(0)
	v_add_f32_e32 v8, v6, v8
	v_xor_b32_e32 v6, 32, v175
	v_cmp_lt_i32_e64 s[2:3], v6, v41
	v_add_f32_e32 v60, v7, v60
	v_add_f32_e32 v229, v59, v223
	v_add_f32_e32 v233, v9, v225
	v_cndmask_b32_e64 v6, v175, v6, s[2:3]
	ds_bpermute_b32 v161, v139, v159
	ds_bpermute_b32 v191, v139, v169
	ds_bpermute_b32 v195, v139, v192
	ds_bpermute_b32 v162, v139, v160
	ds_bpermute_b32 v170, v139, v168
	ds_bpermute_b32 v194, v139, v193
	ds_bpermute_b32 v198, v139, v196
	ds_bpermute_b32 v164, v139, v163
	ds_bpermute_b32 v166, v139, v165
	ds_bpermute_b32 v157, v139, v197
	ds_bpermute_b32 v200, v139, v199
	ds_bpermute_b32 v63, v139, v61
	ds_bpermute_b32 v66, v139, v64
	ds_bpermute_b32 v203, v139, v201
	ds_bpermute_b32 v207, v139, v204
	ds_bpermute_b32 v51, v139, v50
	ds_bpermute_b32 v57, v139, v56
	ds_bpermute_b32 v206, v139, v205
	ds_bpermute_b32 v210, v139, v208
	ds_bpermute_b32 v44, v139, v42
	ds_bpermute_b32 v46, v139, v45
	ds_bpermute_b32 v37, v139, v209
	ds_bpermute_b32 v212, v139, v211
	ds_bpermute_b32 v28, v139, v27
	ds_bpermute_b32 v30, v139, v29
	ds_bpermute_b32 v215, v139, v213
	ds_bpermute_b32 v220, v139, v217
	ds_bpermute_b32 v19, v139, v18
	ds_bpermute_b32 v22, v139, v20
	ds_bpermute_b32 v219, v139, v218
	ds_bpermute_b32 v224, v139, v221
	ds_bpermute_b32 v15, v139, v14
	ds_bpermute_b32 v17, v139, v16
	ds_bpermute_b32 v227, v139, v222
	ds_bpermute_b32 v234, v139, v226
	v_lshlrev_b32_e32 v238, 2, v6
	v_cndmask_b32_e32 v6, 0, v39, vcc
	v_cndmask_b32_e32 v7, v39, v155, vcc
	v_cndmask_b32_e32 v9, v155, v34, vcc
	v_cndmask_b32_e32 v41, v34, v8, vcc
	v_cndmask_b32_e32 v59, v8, v58, vcc
	v_cndmask_b32_e32 v139, v58, v156, vcc
	v_cndmask_b32_e32 v223, v156, v36, vcc
	v_cndmask_b32_e32 v225, v36, v60, vcc
	v_cndmask_b32_e32 v228, v60, v154, vcc
	v_cndmask_b32_e32 v230, v154, v158, vcc
	v_cndmask_b32_e32 v231, v158, v38, vcc
	v_cndmask_b32_e32 v232, v38, v229, vcc
	v_cndmask_b32_e32 v235, v229, v171, vcc
	v_cndmask_b32_e32 v236, v171, v202, vcc
	v_cndmask_b32_e32 v237, v202, v214, vcc
	v_cndmask_b32_e32 v239, v214, v233, vcc
	ds_bpermute_b32 v6, v238, v6
	ds_bpermute_b32 v7, v238, v7
	ds_bpermute_b32 v9, v238, v9
	ds_bpermute_b32 v41, v238, v41
	ds_bpermute_b32 v59, v238, v59
	ds_bpermute_b32 v139, v238, v139
	ds_bpermute_b32 v223, v238, v223
	ds_bpermute_b32 v225, v238, v225
	ds_bpermute_b32 v228, v238, v228
	ds_bpermute_b32 v230, v238, v230
	ds_bpermute_b32 v231, v238, v231
	ds_bpermute_b32 v232, v238, v232
	ds_bpermute_b32 v235, v238, v235
	ds_bpermute_b32 v236, v238, v236
	ds_bpermute_b32 v237, v238, v237
	ds_bpermute_b32 v238, v238, v239
	v_cmp_eq_u32_e64 s[2:3], 0, v151
	s_and_saveexec_b64 s[0:1], s[2:3]
	s_cbranch_execz .LBB0_606
; template <int VAR>
; __device__ __forceinline__ void nsa_attn_mfma(Frame& F, bf16* Y) {
;     ...
;           slc[T * 4 + q] = 2.f * (P[4 * q] + P[4 * q + 1] + P[4 * q + 2]) + P[4 * q + 3];
;           float a;
;           if (q > 0) a = P[4 * (q - 1) + 3];
;           else if (T > 0) { const f32x16& Pm = (T == 1) ? pA0 : (T == 2) ? pA1 : pB0; a = Pm[15]; }
;           else a = 0.f;
;           const float give = hi ? a : P[4 * q + 3];
;           slc[T * 4 + q] += __shfl_xor(give, 32); }
;       if (j == 0) {
; #pragma unroll
;         for (int T = 0; T < 4; ++T)
; #pragma unroll
;           for (int q = 0; q < 4; ++q) { const int blk = 8 * T + 2 * q + hi;
;             const float s = (blk == 0 || blk == cur || blk == cur - 1) ? 1e6f : (blk > cur ? -1.0f : slc[T * 4 + q]);
;             scl[(4 * wid + tsub) * 32 + blk] = s; }
	v_add_f32_e32 v10, v10, v12
	v_add_f32_e32 v12, v23, v24
	v_add_f32_e32 v10, v10, v12
	s_waitcnt lgkmcnt(0)
	v_add_f32_e32 v12, v14, v15
	v_add_f32_e32 v14, v27, v28
	v_add_f32_e32 v15, v18, v19
	v_add_f32_e32 v14, v14, v15
	v_add_f32_e32 v12, v14, v12
	v_add_f32_e32 v14, v61, v63
	v_add_f32_e32 v15, v50, v51
	v_fmac_f32_e32 v8, 2.0, v12
	v_add_f32_e32 v12, v42, v44
	v_add_f32_e32 v14, v14, v15
	v_add_f32_e32 v12, v14, v12
	v_add_f32_e32 v14, v62, v65
	v_add_f32_e32 v15, v160, v162
	v_fmac_f32_e32 v34, 2.0, v12
	v_add_f32_e32 v12, v163, v164
	v_add_f32_e32 v14, v14, v15
	v_add_f32_e32 v12, v14, v12
	v_add_f32_e32 v4, v4, v5
	v_add_f32_e32 v5, v11, v13
	v_fmac_f32_e32 v155, 2.0, v12
	v_add_f32_e32 v12, v25, v26
	v_add_f32_e32 v4, v4, v5
	v_add_f32_e32 v4, v4, v12
	v_readlane_b32 s2, v254, 36
	v_fmac_f32_e32 v39, 2.0, v4
	s_add_i32 s7, s85, -1
	v_or_b32_e32 v5, s2, v140
	v_cmp_eq_u32_e64 s[2:3], s85, v150
	v_add_f32_e32 v4, v39, v6
	s_or_b64 s[4:5], vcc, s[2:3]
	v_cmp_eq_u32_e32 vcc, s7, v150
	v_cmp_ge_i32_e64 s[2:3], s85, v150
	s_or_b64 vcc, s[4:5], vcc
	v_lshlrev_b32_e32 v5, 7, v5
	v_cndmask_b32_e64 v4, -1.0, v4, s[2:3]
	v_readlane_b32 s2, v254, 50
	v_add_u32_e32 v6, 2, v150
	v_cndmask_b32_e32 v4, v4, v176, vcc
	v_add3_u32 v5, s2, v5, v189
	v_cmp_eq_u32_e32 vcc, 0, v6
	v_cmp_eq_u32_e64 s[2:3], s85, v6
	v_add_f32_e32 v7, v155, v7
	s_or_b64 s[4:5], vcc, s[2:3]
	v_cmp_eq_u32_e32 vcc, s7, v6
	v_cmp_ge_i32_e64 s[2:3], s85, v6
	s_or_b64 vcc, s[4:5], vcc
	v_add_f32_e32 v9, v34, v9
	v_cndmask_b32_e64 v6, -1.0, v7, s[2:3]
	v_cndmask_b32_e32 v6, v6, v176, vcc
	ds_write2_b32 v5, v4, v6 offset1:2
	v_add_u32_e32 v4, 4, v150
	v_cmp_eq_u32_e32 vcc, 0, v4
	v_cmp_eq_u32_e64 s[2:3], s85, v4
	s_or_b64 s[4:5], vcc, s[2:3]
	v_cmp_eq_u32_e32 vcc, s7, v4
	v_cmp_ge_i32_e64 s[2:3], s85, v4
	v_add_f32_e32 v16, v16, v17
	v_add_f32_e32 v17, v29, v30
	v_add_f32_e32 v20, v20, v22
	v_cndmask_b32_e64 v4, -1.0, v9, s[2:3]
	s_or_b64 vcc, s[4:5], vcc
	v_add_u32_e32 v6, 6, v150
	v_add_f32_e32 v17, v17, v20
	v_add_f32_e32 v20, v64, v66
	v_add_f32_e32 v22, v56, v57
	v_cndmask_b32_e32 v4, v4, v176, vcc
	v_cmp_eq_u32_e32 vcc, 0, v6
	v_cmp_eq_u32_e64 s[2:3], s85, v6
	v_add_f32_e32 v16, v17, v16
	v_add_f32_e32 v17, v45, v46
	v_add_f32_e32 v20, v20, v22
	v_add_f32_e32 v22, v159, v161
	v_add_f32_e32 v29, v168, v170
	v_add_f32_e32 v8, v8, v41
	s_or_b64 s[4:5], vcc, s[2:3]
	v_cmp_eq_u32_e32 vcc, s7, v6
	v_cmp_ge_i32_e64 s[2:3], s85, v6
	v_add_f32_e32 v17, v20, v17
	v_add_f32_e32 v20, v165, v166
	v_add_f32_e32 v22, v22, v29
	v_cndmask_b32_e64 v6, -1.0, v8, s[2:3]
	s_or_b64 vcc, s[4:5], vcc
	v_add_f32_e32 v20, v22, v20
	v_add_f32_e32 v22, v35, v43
	v_cndmask_b32_e32 v6, v6, v176, vcc
	v_add_f32_e32 v10, v10, v22
	ds_write2_b32 v5, v4, v6 offset0:4 offset1:6
	v_add_u32_e32 v4, 8, v150
	v_fmac_f32_e32 v58, 2.0, v10
	v_cmp_eq_u32_e32 vcc, 0, v4
	v_cmp_eq_u32_e64 s[2:3], s85, v4
	v_add_f32_e32 v10, v58, v59
	s_or_b64 s[4:5], vcc, s[2:3]
	v_cmp_eq_u32_e32 vcc, s7, v4
	v_cmp_ge_i32_e64 s[2:3], s85, v4
	s_or_b64 vcc, s[4:5], vcc
	v_add_u32_e32 v6, 10, v150
	v_cndmask_b32_e64 v4, -1.0, v10, s[2:3]
	v_fmac_f32_e32 v156, 2.0, v20
	v_cndmask_b32_e32 v4, v4, v176, vcc
	v_cmp_eq_u32_e32 vcc, 0, v6
	v_cmp_eq_u32_e64 s[2:3], s85, v6
	v_add_f32_e32 v20, v156, v139
	s_or_b64 s[4:5], vcc, s[2:3]
	v_cmp_eq_u32_e32 vcc, s7, v6
	v_cmp_ge_i32_e64 s[2:3], s85, v6
	s_or_b64 vcc, s[4:5], vcc
	v_add_f32_e32 v32, v32, v47
	v_cndmask_b32_e64 v6, -1.0, v20, s[2:3]
	v_cndmask_b32_e32 v6, v6, v176, vcc
	v_add_f32_e32 v47, v48, v67
	v_add_f32_e32 v48, v213, v215
	v_add_f32_e32 v67, v218, v219
	ds_write2_b32 v5, v4, v6 offset0:8 offset1:10
	v_add_u32_e32 v4, 12, v150
	v_add_f32_e32 v32, v32, v47
	v_add_f32_e32 v47, v222, v227
	v_add_f32_e32 v48, v48, v67
	v_fmac_f32_e32 v36, 2.0, v17
	v_cmp_eq_u32_e32 vcc, 0, v4
	v_cmp_eq_u32_e64 s[2:3], s85, v4
	v_add_f32_e32 v47, v48, v47
	v_add_f32_e32 v48, v201, v203
	v_add_f32_e32 v67, v205, v206
	v_add_f32_e32 v17, v36, v223
	s_or_b64 s[4:5], vcc, s[2:3]
	v_cmp_eq_u32_e32 vcc, s7, v4
	v_cmp_ge_i32_e64 s[2:3], s85, v4
	v_add_f32_e32 v37, v209, v37
	v_add_f32_e32 v48, v48, v67
	v_cndmask_b32_e64 v4, -1.0, v17, s[2:3]
	s_or_b64 vcc, s[4:5], vcc
	v_add_u32_e32 v6, 14, v150
	v_add_f32_e32 v37, v48, v37
	v_fmac_f32_e32 v60, 2.0, v16
; template <int VAR>
; __device__ __forceinline__ void nsa_attn_mfma(Frame& F, bf16* Y) {
;     ...
;           slc[T * 4 + q] = 2.f * (P[4 * q] + P[4 * q + 1] + P[4 * q + 2]) + P[4 * q + 3];
;           float a;
;           if (q > 0) a = P[4 * (q - 1) + 3];
;           else if (T > 0) { const f32x16& Pm = (T == 1) ? pA0 : (T == 2) ? pA1 : pB0; a = Pm[15]; }
;           else a = 0.f;
;           const float give = hi ? a : P[4 * q + 3];
;           slc[T * 4 + q] += __shfl_xor(give, 32); }
;       if (j == 0) {
; #pragma unroll
;         for (int T = 0; T < 4; ++T)
; #pragma unroll
;           for (int q = 0; q < 4; ++q) { const int blk = 8 * T + 2 * q + hi;
;             const float s = (blk == 0 || blk == cur || blk == cur - 1) ? 1e6f : (blk > cur ? -1.0f : slc[T * 4 + q]);
;             scl[(4 * wid + tsub) * 32 + blk] = s; }
	v_cndmask_b32_e32 v4, v4, v176, vcc
	v_cmp_eq_u32_e32 vcc, 0, v6
	v_cmp_eq_u32_e64 s[2:3], s85, v6
	v_fmac_f32_e32 v38, 2.0, v37
	v_add_f32_e32 v48, v169, v191
	v_add_f32_e32 v67, v193, v194
	v_add_f32_e32 v16, v60, v225
	s_or_b64 s[4:5], vcc, s[2:3]
	v_cmp_eq_u32_e32 vcc, s7, v6
	v_cmp_ge_i32_e64 s[2:3], s85, v6
	v_add_f32_e32 v37, v38, v231
	v_add_f32_e32 v38, v197, v157
	v_add_f32_e32 v48, v48, v67
	v_add_f32_e32 v21, v21, v31
	v_add_f32_e32 v31, v33, v40
	v_cndmask_b32_e64 v6, -1.0, v16, s[2:3]
	s_or_b64 vcc, s[4:5], vcc
	v_add_f32_e32 v38, v48, v38
	v_add_f32_e32 v48, v49, v152
	v_add_f32_e32 v21, v21, v31
	v_cndmask_b32_e32 v6, v6, v176, vcc
	v_add_f32_e32 v21, v21, v48
	ds_write2_b32 v5, v4, v6 offset0:12 offset1:14
	v_add_u32_e32 v4, 16, v150
	v_fmac_f32_e32 v154, 2.0, v21
	v_cmp_eq_u32_e32 vcc, 0, v4
	v_cmp_eq_u32_e64 s[2:3], s85, v4
	v_add_f32_e32 v21, v154, v228
	s_or_b64 s[4:5], vcc, s[2:3]
	v_cmp_eq_u32_e32 vcc, s7, v4
	v_cmp_ge_i32_e64 s[2:3], s85, v4
	s_or_b64 vcc, s[4:5], vcc
	v_add_u32_e32 v6, 18, v150
	v_cndmask_b32_e64 v4, -1.0, v21, s[2:3]
	v_fmac_f32_e32 v158, 2.0, v38
	v_cndmask_b32_e32 v4, v4, v176, vcc
	v_cmp_eq_u32_e32 vcc, 0, v6
	v_cmp_eq_u32_e64 s[2:3], s85, v6
	v_add_f32_e32 v38, v158, v230
	s_or_b64 s[4:5], vcc, s[2:3]
	v_cmp_eq_u32_e32 vcc, s7, v6
	v_cmp_ge_i32_e64 s[2:3], s85, v6
	s_or_b64 vcc, s[4:5], vcc
	v_fmac_f32_e32 v229, 2.0, v47
	v_cndmask_b32_e64 v6, -1.0, v38, s[2:3]
	v_cndmask_b32_e32 v6, v6, v176, vcc
	ds_write2_b32 v5, v4, v6 offset0:16 offset1:18
	v_add_u32_e32 v4, 20, v150
	v_cmp_eq_u32_e32 vcc, 0, v4
	v_cmp_eq_u32_e64 s[2:3], s85, v4
	s_or_b64 s[4:5], vcc, s[2:3]
	v_cmp_eq_u32_e32 vcc, s7, v4
	v_cmp_ge_i32_e64 s[2:3], s85, v4
	s_or_b64 vcc, s[4:5], vcc
	v_add_u32_e32 v6, 22, v150
	v_cndmask_b32_e64 v4, -1.0, v37, s[2:3]
	v_cndmask_b32_e32 v4, v4, v176, vcc
	v_cmp_eq_u32_e32 vcc, 0, v6
	v_cmp_eq_u32_e64 s[2:3], s85, v6
	v_add_f32_e32 v47, v229, v232
	s_or_b64 s[4:5], vcc, s[2:3]
	v_cmp_eq_u32_e32 vcc, s7, v6
	v_cmp_ge_i32_e64 s[2:3], s85, v6
	s_or_b64 vcc, s[4:5], vcc
	v_add_f32_e32 v153, v153, v167
	v_cndmask_b32_e64 v6, -1.0, v47, s[2:3]
	v_cndmask_b32_e32 v6, v6, v176, vcc
	v_add_f32_e32 v32, v32, v153
	ds_write2_b32 v5, v4, v6 offset0:20 offset1:22
	v_add_u32_e32 v4, 24, v150
	v_add_f32_e32 v192, v192, v195
	v_add_f32_e32 v195, v196, v198
	v_fmac_f32_e32 v171, 2.0, v32
	v_cmp_eq_u32_e32 vcc, 0, v4
	v_cmp_eq_u32_e64 s[2:3], s85, v4
	v_add_f32_e32 v199, v199, v200
	v_add_f32_e32 v192, v192, v195
	v_add_f32_e32 v32, v171, v235
	s_or_b64 s[4:5], vcc, s[2:3]
	v_cmp_eq_u32_e32 vcc, s7, v4
	v_cmp_ge_i32_e64 s[2:3], s85, v4
	v_add_f32_e32 v192, v192, v199
	s_or_b64 vcc, s[4:5], vcc
	v_cndmask_b32_e64 v4, -1.0, v32, s[2:3]
	v_add_u32_e32 v6, 26, v150
	v_fmac_f32_e32 v202, 2.0, v192
	v_cndmask_b32_e32 v4, v4, v176, vcc
	v_cmp_eq_u32_e32 vcc, 0, v6
	v_cmp_eq_u32_e64 s[2:3], s85, v6
	v_add_f32_e32 v192, v202, v236
	s_or_b64 s[4:5], vcc, s[2:3]
	v_cmp_eq_u32_e32 vcc, s7, v6
	v_cmp_ge_i32_e64 s[2:3], s85, v6
	v_add_f32_e32 v204, v204, v207
	v_add_f32_e32 v207, v208, v210
	v_cndmask_b32_e64 v6, -1.0, v192, s[2:3]
	s_or_b64 vcc, s[4:5], vcc
	v_add_f32_e32 v211, v211, v212
	v_add_f32_e32 v204, v204, v207
	v_cndmask_b32_e32 v6, v6, v176, vcc
	v_add_f32_e32 v204, v204, v211
	ds_write2_b32 v5, v4, v6 offset0:24 offset1:26
	v_add_u32_e32 v4, 28, v150
	v_add_f32_e32 v217, v217, v220
	v_add_f32_e32 v220, v221, v224
	v_fmac_f32_e32 v214, 2.0, v204
	v_cmp_eq_u32_e32 vcc, 0, v4
	v_cmp_eq_u32_e64 s[2:3], s85, v4
	v_add_f32_e32 v151, v226, v234
	v_add_f32_e32 v217, v217, v220
	v_add_f32_e32 v204, v214, v237
	s_or_b64 s[4:5], vcc, s[2:3]
	v_cmp_eq_u32_e32 vcc, s7, v4
	v_cmp_ge_i32_e64 s[2:3], s85, v4
	v_add_f32_e32 v151, v217, v151
	s_or_b64 vcc, s[4:5], vcc
	v_cndmask_b32_e64 v4, -1.0, v204, s[2:3]
	v_add_u32_e32 v6, 30, v150
	v_fmac_f32_e32 v233, 2.0, v151
	v_cndmask_b32_e32 v4, v4, v176, vcc
	v_cmp_eq_u32_e32 vcc, 0, v6
	v_cmp_eq_u32_e64 s[2:3], s85, v6
	v_add_f32_e32 v151, v233, v238
	s_or_b64 s[4:5], vcc, s[2:3]
	v_cmp_eq_u32_e32 vcc, s7, v6
	v_cmp_ge_i32_e64 s[2:3], s85, v6
	s_or_b64 vcc, s[4:5], vcc
	s_nop 0
	v_cndmask_b32_e64 v6, -1.0, v151, s[2:3]
	v_cndmask_b32_e32 v6, v6, v176, vcc
	ds_write2_b32 v5, v4, v6 offset0:28 offset1:30

; __device__ __forceinline__ void qkt(f32x16& p0, f32x16& p1, const char* Ks, const bf16x8* qr, int r32, int hi) {
;     ...
;   for (int d0 = 0; d0 < 8; ++d0) { int cb = (d0 * 16 + hi * 8) * 2;
;     bf16x8 b0 = *reinterpret_cast<const bf16x8*>(Ks + KSWZ(r32, cb));
;     bf16x8 b1 = *reinterpret_cast<const bf16x8*>(Ks + KSWZ(32 + r32, cb));
; template <int VAR>
; __device__ __forceinline__ void nsa_attn_mfma(Frame& F, bf16* Y) {
;     ...
;     const int r32 = lane & 31, hi = lane >> 5, tsub = r32 >> 3, j = r32 & 7, tl_ = wid * 64 + lane;
;     const int krow = tl_ >> 4, kcol = ((lane & 15) ^ (krow & 7)) * 8;
;     const int vkk = (wid >> 1) * 8 + ((lane >> 2) & 7), vrow = (vkk & ~0xC) | ((vkk & 4) << 1) | ((vkk & 8) >> 1), vcol = ((wid & 1) * 2 + (lane >> 5)) * 32 + (lane & 3) * 8;
;     const int vb0 = (int)(uintptr_t)((LAS unsigned char*)lds + AT_V) + v_rd_base(lane);
;     float* li_l = wsf; float* al_l = wsf + 32;
;     v4u* otl = (v4u*)(lds + AT_OT) + tl_;
;     constexpr int ROWP = 136;
;     unsigned short* rowst = (unsigned short*)(lds + AT_K) + (wid * 32 + 4 * hi) * ROWP + r32;
;     const int wg = uu >> 2, b = wg >> 6, kq_ = wg & 63, k32_ = (kq_ + 32) & 63;
;     const int g = ui, qb = (ui == 0) ? kq_ : (ui == 1) ? 63 - kq_ : (ui == 2) ? k32_ : 63 - k32_;
;     const int t0 = qb * 32, cur = t0 >> 6;
;     const int t = t0 + 4 * wid + tsub, h = g * 8 + j;
;     const float slope2 = exp2f(-0.25f * (float)(h + 1)) * LOG2E;
;     const size_t rowq = (size_t)(b * SEQ + t) * NSA_NP;
;     bf16x8 qr[8];
; #pragma unroll
;     for (int d0 = 0; d0 < 8; ++d0) qr[d0] = *(const bf16x8*)(proj + rowq + NSA_Q + h * 128 + d0 * 16 + hi * 8);
;     const float g0 = sigmoidf_(bf2f(proj[rowq + NSA_GL + 0 * 32 + h])), g1 = sigmoidf_(bf2f(proj[rowq + NSA_GL + 1 * 32 + h])), g2 = sigmoidf_(bf2f(proj[rowq + NSA_GL + 2 * 32 + h]));
;     f32x16 o[4];
; #pragma unroll
;     for (int d = 0; d < 4; ++d) { o[d] = f32x16{}; }
;     __syncthreads();
;     {
;       const bf16* kc = KC + (size_t)(b * 4 + g) * 128 * 128; const bf16* vc = VC + (size_t)(b * 4 + g) * 128 * 128;
;       { const bf16* kcp = kc + krow * 128 + kcol; const bf16* vcp = vc + vrow * 128 + vcol; TDMA(kcp, vcp, 128, 0, 0); TDMA(kcp + 64 * 128, vcp + 64 * 128, 128, 1, 1); }
;       TWAIT();
;       f32x16 pA0, pA1, pB0, pB1;
;       qkt(pA0, pA1, K_lds, qr, r32, hi); qkt(pB0, pB1, K_lds + SHM_K, qr, r32, hi);
.LBB0_2159:
	v_readlane_b32 s2, v254, 32
	v_lshrrev_b32_e32 v4, 1, v178
	v_bfe_u32 v2, v178, 2, 2
	v_add_u32_e32 v145, s2, v178
	v_and_b32_e32 v4, 8, v4
	v_readlane_b32 s2, v254, 33
	v_ashrrev_i32_e32 v150, 5, v178
	s_lshl_b32 s33, s4, 5
	v_or3_b32 v99, s2, v2, v4
	v_readlane_b32 s2, v254, 34
	v_bfe_u32 v140, v178, 3, 2
	v_lshlrev_b32_e32 v147, 3, v178
	v_add_u32_e32 v2, s2, v150
	v_readlane_b32 s2, v254, 36
	s_ashr_i32 s5, s80, 8
	s_add_i32 s2, s33, s2
	v_and_b32_e32 v151, 7, v178
	v_and_b32_e32 v148, 24, v147
	v_or_b32_e32 v181, s2, v140
	s_lshl_b32 s93, s8, 3
	s_lshl_b32 s96, s5, 11
	v_lshl_or_b32 v96, v2, 5, v148
	v_or_b32_e32 v64, s93, v151
	v_add_u32_e32 v2, s96, v181
	v_writelane_b32 v254, s2, 62
	v_mad_i64_i32 v[4:5], s[2:3], v2, s73, v[136:137]
	v_lshlrev_b32_e32 v2, 8, v64
	v_lshlrev_b32_e32 v8, 3, v150
	v_lshl_add_u64 v[6:7], v[4:5], 0, v[2:3]
	v_ashrrev_i32_e32 v9, 31, v8
	v_lshl_add_u64 v[6:7], v[8:9], 1, v[6:7]
	global_load_dwordx4 v[104:107], v[6:7], off
	global_load_dwordx4 v[108:111], v[6:7], off offset:32
	global_load_dwordx4 v[112:115], v[6:7], off offset:64
	global_load_dwordx4 v[116:119], v[6:7], off offset:96
	global_load_dwordx4 v[120:123], v[6:7], off offset:128
	global_load_dwordx4 v[124:127], v[6:7], off offset:160
	global_load_dwordx4 v[128:131], v[6:7], off offset:192
	global_load_dwordx4 v[132:135], v[6:7], off offset:224
	v_lshlrev_b32_e32 v2, 1, v64
	v_lshl_add_u64 v[4:5], v[4:5], 0, v[2:3]
	s_movk_i32 s2, 0x5000
	v_add_co_u32_e32 v4, vcc, s2, v4
	s_lshl_b32 s2, s5, 2
	s_or_b32 s2, s2, s8
	s_ashr_i32 s3, s2, 31
	v_ashrrev_i32_e32 v98, 4, v145
	s_lshr_b32 s97, s4, 1
	v_addc_co_u32_e32 v5, vcc, 0, v5, vcc
	s_lshl_b64 s[2:3], s[2:3], 15
	v_readlane_b32 s5, v254, 25
	v_and_b32_e32 v179, 15, v178
	global_load_ushort v146, v[4:5], off offset:2048
	global_load_ushort v144, v[4:5], off offset:2112
	global_load_ushort v143, v[4:5], off offset:2176
	s_add_u32 s6, s5, s2
	v_readlane_b32 s5, v254, 27
	v_lshlrev_b32_e32 v4, 7, v98
	v_bitop3_b32 v142, v98, v179, 15 bitop3:0x6c
	s_addc_u32 s7, s5, s3
	v_readlane_b32 s5, v254, 29
	v_ashrrev_i32_e32 v5, 31, v4
	s_add_u32 s2, s5, s2
	v_readlane_b32 s5, v254, 31
	v_lshl_add_u64 v[4:5], v[4:5], 1, s[6:7]
	v_lshlrev_b32_e32 v2, 4, v142
	s_mov_b32 m0, s95
	s_addc_u32 s3, s5, s3
	v_lshl_add_u64 v[4:5], v[4:5], 0, v[2:3]
	v_lshlrev_b32_e32 v6, 8, v99
	v_mov_b32_e32 v7, v3
	v_ashrrev_i32_e32 v97, 31, v96
	s_mov_b64 s[14:15], 0x2000
	v_readlane_b32 s6, v254, 41
	s_waitcnt vmcnt(0) lgkmcnt(0)
	s_barrier
	v_lshl_add_u64 v[6:7], s[2:3], 0, v[6:7]
	v_lshlrev_b64 v[68:69], 1, v[96:97]
	global_load_lds_dwordx4 v[4:5], off
	v_lshl_add_u64 v[8:9], v[4:5], 0, s[14:15]
	s_mov_b32 m0, s6
	v_readlane_b32 s2, v254, 42
	v_lshl_add_u64 v[6:7], v[6:7], 0, v[68:69]
	global_load_lds_dwordx4 v[8:9], off
	s_mov_b32 m0, s2
	v_readlane_b32 s2, v254, 43
	global_load_lds_dwordx4 v[6:7], off
	v_lshl_add_u64 v[8:9], v[6:7], 0, s[14:15]
	s_mov_b32 m0, s2
	s_mov_b64 s[14:15], 0x4000
	v_readlane_b32 s2, v254, 44
	global_load_lds_dwordx4 v[8:9], off
	v_lshl_add_u64 v[8:9], v[4:5], 0, s[14:15]
	s_mov_b32 m0, s2
	s_mov_b64 s[16:17], 0x6000
	v_readlane_b32 s2, v254, 45
	v_and_b32_e32 v180, 31, v178
	global_load_lds_dwordx4 v[8:9], off
	v_lshl_add_u64 v[4:5], v[4:5], 0, s[16:17]
	s_mov_b32 m0, s2
	v_readlane_b32 s2, v254, 46
	v_lshlrev_b32_e32 v149, 4, v178
	global_load_lds_dwordx4 v[4:5], off
	v_lshl_add_u64 v[4:5], v[6:7], 0, s[14:15]
	s_mov_b32 m0, s2
	v_readlane_b32 s2, v254, 47
	v_lshlrev_b32_e32 v24, 4, v150
	v_lshlrev_b32_e32 v25, 8, v180
	v_and_b32_e32 v26, 0xf0, v149
	global_load_lds_dwordx4 v[4:5], off
	v_lshl_add_u64 v[4:5], v[6:7], 0, s[16:17]
	s_mov_b32 m0, s2
	v_xad_u32 v182, v26, v24, v25
	global_load_lds_dwordx4 v[4:5], off
	v_add_u32_e32 v27, 0, v182
	s_waitcnt vmcnt(0)
	s_waitcnt vmcnt(0) lgkmcnt(0)
	s_barrier
	ds_read_b128 v[4:7], v27 offset:8192
	ds_read_b128 v[52:55], v27
	s_waitcnt lgkmcnt(1)
	v_mfma_f32_32x32x16_bf16 v[4:19], v[4:7], v[104:107], 0
	v_add_u32_e32 v20, 32, v24
	v_xad_u32 v183, v20, v26, v25
	v_add_u32_e32 v60, 0, v183
	ds_read_b128 v[20:23], v60 offset:8192
	ds_read_b128 v[70:73], v60
	s_mov_b32 s2, 0xc2fc0000
	s_lshl_b32 s82, s8, 8
	s_mov_b32 m0, s95
	s_waitcnt lgkmcnt(1)
	v_mfma_f32_32x32x16_bf16 v[4:19], v[20:23], v[108:111], v[4:19]
	v_add_u32_e32 v20, 64, v24
	v_xad_u32 v184, v20, v26, v25
	v_add_u32_e32 v65, 0, v184
	ds_read_b128 v[20:23], v65 offset:8192
	ds_read_b128 v[74:77], v65
	v_lshlrev_b32_e32 v188, 2, v150
	s_waitcnt lgkmcnt(1)
	v_mfma_f32_32x32x16_bf16 v[4:19], v[20:23], v[112:115], v[4:19]
	v_add_u32_e32 v20, 0x60, v24
	v_xad_u32 v185, v20, v26, v25
	v_add_u32_e32 v66, 0, v185
	ds_read_b128 v[20:23], v66 offset:8192
	ds_read_b128 v[78:81], v66
	s_waitcnt lgkmcnt(1)
	v_mfma_f32_32x32x16_bf16 v[4:19], v[20:23], v[116:119], v[4:19]
	v_add_u32_e32 v20, 0x80, v24
	v_xad_u32 v186, v20, v26, v25
	v_add_u32_e32 v67, 0, v186
	ds_read_b128 v[20:23], v67 offset:8192
	ds_read_b128 v[82:85], v67
	s_waitcnt lgkmcnt(1)
	v_mfma_f32_32x32x16_bf16 v[4:19], v[20:23], v[120:123], v[4:19]
	v_add_u32_e32 v20, 0xa0, v24
	v_xad_u32 v187, v20, v26, v25
	v_add_u32_e32 v94, 0, v187
	ds_read_b128 v[20:23], v94 offset:8192
	ds_read_b128 v[86:89], v94
	s_waitcnt lgkmcnt(1)
	v_mfma_f32_32x32x16_bf16 v[4:19], v[20:23], v[124:127], v[4:19]
	v_add_u32_e32 v20, 0xc0, v24
	v_xad_u32 v189, v20, v26, v25
	v_add_u32_e32 v95, 0, v189
	ds_read_b128 v[20:23], v95 offset:8192
	ds_read_b128 v[90:93], v95
	s_waitcnt lgkmcnt(1)
	v_mfma_f32_32x32x16_bf16 v[4:19], v[20:23], v[128:131], v[4:19]
	v_add_u32_e32 v20, 0xe0, v24
	v_xad_u32 v190, v20, v26, v25
	v_add_u32_e32 v139, 0, v190
	ds_read_b128 v[20:23], v139 offset:8192
	ds_read_b128 v[152:155], v139
	s_waitcnt lgkmcnt(1)
; __device__ __forceinline__ void qkt(f32x16& p0, f32x16& p1, const char* Ks, const bf16x8* qr, int r32, int hi) {
;     ...
;   for (int d0 = 0; d0 < 8; ++d0) { int cb = (d0 * 16 + hi * 8) * 2;
;     bf16x8 b0 = *reinterpret_cast<const bf16x8*>(Ks + KSWZ(r32, cb));
;     bf16x8 b1 = *reinterpret_cast<const bf16x8*>(Ks + KSWZ(32 + r32, cb));
;     p0 = __builtin_amdgcn_mfma_f32_32x32x16_bf16(b0, qr[d0], p0, 0, 0, 0);
;     p1 = __builtin_amdgcn_mfma_f32_32x32x16_bf16(b1, qr[d0], p1, 0, 0, 0); }
; template <int VAR>
; __device__ __forceinline__ void nsa_attn_mfma(Frame& F, bf16* Y) {
;     ...
;     const float slope2 = exp2f(-0.25f * (float)(h + 1)) * LOG2E;
;     const size_t rowq = (size_t)(b * SEQ + t) * NSA_NP;
;     bf16x8 qr[8];
; #pragma unroll
;     for (int d0 = 0; d0 < 8; ++d0) qr[d0] = *(const bf16x8*)(proj + rowq + NSA_Q + h * 128 + d0 * 16 + hi * 8);
;     const float g0 = sigmoidf_(bf2f(proj[rowq + NSA_GL + 0 * 32 + h])), g1 = sigmoidf_(bf2f(proj[rowq + NSA_GL + 1 * 32 + h])), g2 = sigmoidf_(bf2f(proj[rowq + NSA_GL + 2 * 32 + h]));
;     f32x16 o[4];
; #pragma unroll
;     for (int d = 0; d < 4; ++d) { o[d] = f32x16{}; }
;     __syncthreads();
;     {
;       const bf16* kc = KC + (size_t)(b * 4 + g) * 128 * 128; const bf16* vc = VC + (size_t)(b * 4 + g) * 128 * 128;
;       { const bf16* kcp = kc + krow * 128 + kcol; const bf16* vcp = vc + vrow * 128 + vcol; TDMA(kcp, vcp, 128, 0, 0); TDMA(kcp + 64 * 128, vcp + 64 * 128, 128, 1, 1); }
;       TWAIT();
;       f32x16 pA0, pA1, pB0, pB1;
;       qkt(pA0, pA1, K_lds, qr, r32, hi); qkt(pB0, pB1, K_lds + SHM_K, qr, r32, hi);
;       __syncthreads();
;       if (VAR < 5) TDMA(proj + (size_t)(b * SEQ + cur * 64 + krow) * NSA_NP + NSA_KS + g * 128 + kcol, proj + (size_t)(b * SEQ + cur * 64 + vrow) * NSA_NP + NSA_VS + g * 128 + vcol, NSA_NP, 0, 2);
;       const float sl16 = 16.f * slope2, s32_ = sl16 + sl16, s64_ = s32_ + s32_, s128_ = s64_ + s64_;
;       const float baseA = slope2 * (float)(16 * (4 * hi) + 31 - t);
;       const float ca_[4] = {0.f, sl16, s32_, s32_ + sl16};
;       float cb_[16]; cb_[0] = baseA;
; #pragma unroll
;       for (int q = 1; q < 16; ++q) cb_[q] = cb_[q - 1] + s128_;
;       float mx = -1e30f;
;       const int nlim = ((t - 31) >> 4) - 4 * hi;
; #pragma unroll
;       for (int r = 0; r < 16; ++r) { const int c = (r & 3) + 8 * (r >> 2);
	v_mfma_f32_32x32x16_bf16 v[4:19], v[20:23], v[132:135], v[4:19]
	ds_read_b128 v[20:23], v27 offset:16384
	ds_read_b128 v[24:27], v27 offset:24576
	ds_read_b128 v[56:59], v60 offset:16384
	ds_read_b128 v[60:63], v60 offset:24576
	s_waitcnt lgkmcnt(3)
	v_mfma_f32_32x32x16_bf16 v[36:51], v[20:23], v[104:107], 0
	s_waitcnt lgkmcnt(2)
	v_mfma_f32_32x32x16_bf16 v[20:35], v[24:27], v[104:107], 0
	s_waitcnt lgkmcnt(1)
	v_mfma_f32_32x32x16_bf16 v[36:51], v[56:59], v[108:111], v[36:51]
	s_waitcnt lgkmcnt(0)
	v_mfma_f32_32x32x16_bf16 v[20:35], v[60:63], v[108:111], v[20:35]
	ds_read_b128 v[56:59], v65 offset:16384
	ds_read_b128 v[60:63], v65 offset:24576
	s_waitcnt lgkmcnt(1)
	v_mfma_f32_32x32x16_bf16 v[36:51], v[56:59], v[112:115], v[36:51]
	s_waitcnt lgkmcnt(0)
	v_mfma_f32_32x32x16_bf16 v[20:35], v[60:63], v[112:115], v[20:35]
	ds_read_b128 v[56:59], v66 offset:16384
	ds_read_b128 v[60:63], v66 offset:24576
	s_waitcnt lgkmcnt(1)
	v_mfma_f32_32x32x16_bf16 v[36:51], v[56:59], v[116:119], v[36:51]
	s_waitcnt lgkmcnt(0)
	v_mfma_f32_32x32x16_bf16 v[20:35], v[60:63], v[116:119], v[20:35]
	ds_read_b128 v[56:59], v67 offset:16384
	ds_read_b128 v[60:63], v67 offset:24576
	s_waitcnt lgkmcnt(1)
	v_mfma_f32_32x32x16_bf16 v[36:51], v[56:59], v[120:123], v[36:51]
	s_waitcnt lgkmcnt(0)
	v_mfma_f32_32x32x16_bf16 v[20:35], v[60:63], v[120:123], v[20:35]
	ds_read_b128 v[56:59], v94 offset:16384
	ds_read_b128 v[60:63], v94 offset:24576
	s_waitcnt lgkmcnt(1)
	v_mfma_f32_32x32x16_bf16 v[36:51], v[56:59], v[124:127], v[36:51]
	s_waitcnt lgkmcnt(0)
	v_mfma_f32_32x32x16_bf16 v[20:35], v[60:63], v[124:127], v[20:35]
	ds_read_b128 v[56:59], v95 offset:16384
	ds_read_b128 v[60:63], v95 offset:24576
	s_waitcnt lgkmcnt(1)
	v_mfma_f32_32x32x16_bf16 v[36:51], v[56:59], v[128:131], v[36:51]
	ds_read_b128 v[56:59], v139 offset:16384
	s_waitcnt lgkmcnt(1)
	v_mfma_f32_32x32x16_bf16 v[20:35], v[60:63], v[128:131], v[20:35]
	v_add_u32_e32 v60, 1, v64
	v_cvt_f32_ubyte0_e32 v64, v60
	ds_read_b128 v[60:63], v139 offset:24576
	s_waitcnt lgkmcnt(0)
	s_barrier
	v_mfma_f32_32x32x16_bf16 v[36:51], v[56:59], v[132:135], v[36:51]
	v_mul_f32_e32 v56, 0xbe800000, v64
	v_cmp_gt_f32_e32 vcc, s2, v56
	s_lshl_b32 s2, s97, 6
	s_add_i32 s5, s2, s96
	v_cndmask_b32_e32 v56, 0, v172, vcc
	v_fmac_f32_e32 v56, 0xbe800000, v64
	v_exp_f32_e32 v56, v56
	v_cndmask_b32_e32 v57, 0, v173, vcc
	v_mfma_f32_32x32x16_bf16 v[20:35], v[60:63], v[132:135], v[20:35]
	v_add_u32_e32 v94, s5, v98
	v_ldexp_f32 v56, v56, v57
	v_mul_f32_e32 v141, 0x3fb8aa3b, v56
	v_mad_i64_i32 v[94:95], s[2:3], v94, s73, v[136:137]
	v_lshl_add_u64 v[94:95], v[94:95], 0, s[82:83]
	v_lshl_add_u64 v[94:95], v[94:95], 0, v[2:3]
	v_mfma_f32_32x32x16_bf16 v[52:67], v[52:55], v[104:107], 0
	s_mov_b64 s[2:3], 0x2800
	v_lshl_add_u64 v[156:157], v[94:95], 0, s[2:3]
	s_mov_b64 s[2:3], 0xb6800
	global_load_lds_dwordx4 v[156:157], off
	s_mov_b32 m0, s6
	v_add_u32_e32 v2, s5, v99
	v_mfma_f32_32x32x16_bf16 v[52:67], v[70:73], v[108:111], v[52:67]
	v_lshl_add_u64 v[70:71], v[94:95], 0, s[2:3]
	global_load_lds_dwordx4 v[70:71], off
	v_mad_i64_i32 v[70:71], s[2:3], v2, s73, v[136:137]
	v_lshl_or_b32 v2, v150, 6, 31
	v_sub_u32_e32 v2, v2, v181
	v_mfma_f32_32x32x16_bf16 v[52:67], v[74:77], v[112:115], v[52:67]
	v_cvt_f32_i32_e32 v139, v2
	v_mov_b32_e32 v2, v141
	v_lshl_add_u64 v[70:71], v[70:71], 0, s[82:83]
	v_lshl_add_u64 v[68:69], v[70:71], 0, v[68:69]
	s_mov_b64 s[2:3], 0x2c00
	v_lshl_add_u64 v[70:71], v[68:69], 0, s[2:3]
	v_readlane_b32 s2, v254, 48
	v_mfma_f32_32x32x16_bf16 v[52:67], v[78:81], v[116:119], v[52:67]
	v_mul_f32_e64 v80, v2, v138
	v_mul_f32_e64 v81, v2, v139
	v_add_f32_e64 v78, v80, v80
	v_add_f32_e64 v79, v81, v81
	s_mov_b32 m0, s2
	v_pk_fma_f32 v[76:77], v[80:81], 2.0, v[78:79] op_sel_hi:[1,0,1]
	global_load_lds_dwordx4 v[70:71], off
	v_pk_fma_f32 v[156:157], v[76:77], 2.0, v[80:81] op_sel:[0,0,1] op_sel_hi:[1,0,0]
	v_mfma_f32_32x32x16_bf16 v[52:67], v[82:85], v[120:123], v[52:67]
	v_fma_f32 v82, v76, 2.0, v156
	v_fma_f32 v83, v77, 2.0, v157
	s_mov_b64 s[2:3], 0xb6c00
	v_fma_f32 v70, v76, 2.0, v82
	v_fma_f32 v71, v77, 2.0, v83
	v_lshl_add_u64 v[68:69], v[68:69], 0, s[2:3]
	v_pk_fma_f32 v[158:159], v[76:77], 2.0, v[70:71] op_sel_hi:[1,0,1]
	v_subrev_u32_e32 v71, 31, v181
	v_ashrrev_i32_e32 v71, 4, v71
	v_mfma_f32_32x32x16_bf16 v[52:67], v[86:89], v[124:127], v[52:67]
	v_fma_f32 v88, v76, 2.0, v158
	v_fma_f32 v89, v77, 2.0, v159
	v_sub_u32_e32 v71, v71, v188
	v_fma_f32 v84, v76, 2.0, v88
	v_fma_f32 v85, v77, 2.0, v89
	v_cmp_lt_i32_e64 s[2:3], -1, v71
	v_pk_fma_f32 v[72:73], v[76:77], 2.0, v[84:85] op_sel_hi:[1,0,1]
	v_pk_fma_f32 v[94:95], v[78:79], 2.0, v[76:77] op_sel_hi:[1,0,1]
	v_pk_fma_f32 v[160:161], v[76:77], 2.0, v[72:73] op_sel_hi:[1,0,1]
	v_mfma_f32_32x32x16_bf16 v[52:67], v[90:93], v[128:131], v[52:67]
	v_fma_f32 v162, v76, 2.0, v160
	v_fma_f32 v163, v77, 2.0, v161
	v_add_f32_e32 v73, 0, v81
	v_fma_f32 v86, v76, 2.0, v162
	v_fma_f32 v87, v77, 2.0, v163
	v_cmp_lt_u32_e32 vcc, 31, v178
	v_pk_fma_f32 v[74:75], v[76:77], 2.0, v[86:87] op_sel_hi:[1,0,1]
	s_nop 0
	v_pk_fma_f32 v[90:91], v[76:77], 2.0, v[74:75] op_sel_hi:[1,0,1]
	v_mfma_f32_32x32x16_bf16 v[52:67], v[152:155], v[132:135], v[52:67]
	v_fma_f32 v92, v76, 2.0, v90
	v_fma_f32 v93, v77, 2.0, v91
	v_mov_b32_e32 v76, v80
	v_mov_b32_e32 v77, v94
	v_mov_b32_e32 v79, v92
	v_pk_add_f32 v[76:77], v[76:77], v[78:79]
	s_nop 5
	v_fmac_f32_e32 v73, 0x3e0293ee, v52
	v_add_f32_e32 v52, 0, v158
	v_fmac_f32_e32 v52, 0x3e0293ee, v4
	v_add_f32_e32 v4, 0, v160
	v_fmac_f32_e32 v4, 0x3e0293ee, v36
	v_add_f32_e32 v36, 0, v90
	v_fmac_f32_e32 v36, 0x3e0293ee, v20
	v_cndmask_b32_e64 v20, v174, v73, s[2:3]
; template <int VAR>
; __device__ __forceinline__ void nsa_attn_mfma(Frame& F, bf16* Y) {
;     ...
;       const int nlim = ((t - 31) >> 4) - 4 * hi;
; #pragma unroll
;       for (int r = 0; r < 16; ++r) { const int c = (r & 3) + 8 * (r >> 2);
;         float a0 = fmaf(pA0[r], CSC, ca_[r & 3] + cb_[r >> 2]), a1 = fmaf(pA1[r], CSC, ca_[r & 3] + cb_[4 + (r >> 2)]);
;         float b0 = fmaf(pB0[r], CSC, ca_[r & 3] + cb_[8 + (r >> 2)]), b1 = fmaf(pB1[r], CSC, ca_[r & 3] + cb_[12 + (r >> 2)]);
;         a0 = (c > nlim) ? -1e30f : a0; a1 = (c + 32 > nlim) ? -1e30f : a1;
;         b0 = (c + 64 > nlim) ? -1e30f : b0; b1 = (c + 96 > nlim || (c == 27 && hi)) ? -1e30f : b1;
;         pA0[r] = a0; pA1[r] = a1; pB0[r] = b0; pB1[r] = b1; mx = fmaxf(fmaxf(mx, fmaxf(a0, a1)), fmaxf(b0, b1)); }
	v_cmp_lt_i32_e64 s[2:3], 31, v71
	v_add_f32_e32 v2, v94, v77
	s_nop 0
	v_cndmask_b32_e64 v52, v174, v52, s[2:3]
	v_cmp_lt_i32_e64 s[2:3], 63, v71
	s_nop 1
	v_cndmask_b32_e64 v73, v174, v4, s[2:3]
	s_movk_i32 s2, 0x5f
	v_cmp_lt_i32_e64 s[2:3], s2, v71
	v_max_f32_e32 v4, v20, v52
	s_nop 0
	v_cndmask_b32_e64 v36, v174, v36, s[2:3]
	v_max_f32_e32 v75, v73, v36
	s_mov_b32 s2, 0xf149f2ca
	v_max3_f32 v4, v4, s2, v75
	v_add_f32_e32 v75, v80, v81
	v_fmac_f32_e32 v75, 0x3e0293ee, v53
	v_add_f32_e32 v53, v80, v158
	v_fmac_f32_e32 v53, 0x3e0293ee, v5
	v_add_f32_e32 v5, v80, v160
	v_fmac_f32_e32 v5, 0x3e0293ee, v37
	v_add_f32_e32 v37, v80, v90
	v_cmp_lt_i32_e64 s[2:3], 0, v71
	v_fmac_f32_e32 v37, 0x3e0293ee, v21
	s_nop 0
	v_cndmask_b32_e64 v21, v174, v75, s[2:3]
	v_cmp_lt_i32_e64 s[2:3], 32, v71
	s_nop 1
	v_cndmask_b32_e64 v53, v174, v53, s[2:3]
	v_cmp_lt_i32_e64 s[2:3], 64, v71
	s_nop 1
	v_cndmask_b32_e64 v75, v174, v5, s[2:3]
	s_movk_i32 s2, 0x60
	v_cmp_lt_i32_e64 s[2:3], s2, v71
	v_max_f32_e32 v5, v21, v53
	s_nop 0
	v_cndmask_b32_e64 v37, v174, v37, s[2:3]
	v_max_f32_e32 v79, v75, v37
	v_max3_f32 v4, v4, v5, v79
	v_add_f32_e32 v5, v78, v81
	v_fmac_f32_e32 v5, 0x3e0293ee, v54
	v_add_f32_e32 v54, v78, v158
	v_fmac_f32_e32 v54, 0x3e0293ee, v6
	v_add_f32_e32 v6, v78, v160
	v_fmac_f32_e32 v6, 0x3e0293ee, v38
	v_add_f32_e32 v38, v78, v90
	v_cmp_lt_i32_e64 s[2:3], 1, v71
	v_fmac_f32_e32 v38, 0x3e0293ee, v22
	s_nop 0
	v_cndmask_b32_e64 v22, v174, v5, s[2:3]
	v_cmp_lt_i32_e64 s[2:3], 33, v71
	s_nop 1
	v_cndmask_b32_e64 v54, v174, v54, s[2:3]
	s_movk_i32 s2, 0x41
	v_cmp_lt_i32_e64 s[2:3], s2, v71
	v_max_f32_e32 v5, v22, v54
	s_nop 0
	v_cndmask_b32_e64 v6, v174, v6, s[2:3]
	s_movk_i32 s2, 0x61
	v_cmp_lt_i32_e64 s[2:3], s2, v71
	s_nop 1
	v_cndmask_b32_e64 v38, v174, v38, s[2:3]
	v_max_f32_e32 v79, v6, v38
	v_max3_f32 v4, v4, v5, v79
	v_add_f32_e32 v5, v76, v81
	v_fmac_f32_e32 v5, 0x3e0293ee, v55
	v_add_f32_e32 v55, v76, v158
	v_cmp_lt_i32_e64 s[2:3], 2, v71
	v_fmac_f32_e32 v55, 0x3e0293ee, v7
	v_add_f32_e32 v7, v76, v160
	v_cndmask_b32_e64 v79, v174, v5, s[2:3]
	v_cmp_lt_i32_e64 s[2:3], 34, v71
	v_fmac_f32_e32 v7, 0x3e0293ee, v39
	v_add_f32_e32 v39, v76, v90
	v_cndmask_b32_e64 v55, v174, v55, s[2:3]
	s_movk_i32 s2, 0x42
	v_cmp_lt_i32_e64 s[2:3], s2, v71
	v_fmac_f32_e32 v39, 0x3e0293ee, v23
	v_max_f32_e32 v5, v79, v55
	v_cndmask_b32_e64 v7, v174, v7, s[2:3]
	s_movk_i32 s2, 0x62
	v_cmp_lt_i32_e64 s[2:3], s2, v71
	s_nop 1
	v_cndmask_b32_e64 v39, v174, v39, s[2:3]
	v_max_f32_e32 v23, v7, v39
	v_max3_f32 v4, v4, v5, v23
	v_add_f32_e32 v5, 0, v156
	v_fmac_f32_e32 v5, 0x3e0293ee, v56
	v_add_f32_e32 v23, 0, v88
	v_cmp_lt_i32_e64 s[2:3], 7, v71
	v_fmac_f32_e32 v23, 0x3e0293ee, v8
	v_add_f32_e32 v8, 0, v162
	v_cndmask_b32_e64 v56, v174, v5, s[2:3]
	v_cmp_lt_i32_e64 s[2:3], 39, v71
	v_fmac_f32_e32 v8, 0x3e0293ee, v40
	v_add_f32_e32 v40, 0, v92
	v_cndmask_b32_e64 v81, v174, v23, s[2:3]
	s_movk_i32 s2, 0x47
	v_cmp_lt_i32_e64 s[2:3], s2, v71
	v_fmac_f32_e32 v40, 0x3e0293ee, v24
	v_max_f32_e32 v5, v56, v81
	v_cndmask_b32_e64 v8, v174, v8, s[2:3]
	s_movk_i32 s2, 0x67
	v_cmp_lt_i32_e64 s[2:3], s2, v71
	v_add_f32_e32 v24, v80, v92
	v_fmac_f32_e32 v24, 0x3e0293ee, v25
	v_cndmask_b32_e64 v40, v174, v40, s[2:3]
	v_max_f32_e32 v23, v8, v40
	v_max3_f32 v4, v4, v5, v23
	v_add_f32_e32 v5, v80, v156
	v_add_f32_e32 v23, v80, v88
	v_fmac_f32_e32 v5, 0x3e0293ee, v57
	v_fmac_f32_e32 v23, 0x3e0293ee, v9
	v_add_f32_e32 v9, v80, v162
	v_cmp_lt_i32_e64 s[2:3], 8, v71
	v_fmac_f32_e32 v9, 0x3e0293ee, v41
	s_nop 0
	v_cndmask_b32_e64 v41, v174, v5, s[2:3]
	v_cmp_lt_i32_e64 s[2:3], 40, v71
	s_nop 1
	v_cndmask_b32_e64 v57, v174, v23, s[2:3]
	s_movk_i32 s2, 0x48
	v_cmp_lt_i32_e64 s[2:3], s2, v71
	v_max_f32_e32 v5, v41, v57
	s_nop 0
	v_cndmask_b32_e64 v9, v174, v9, s[2:3]
	s_movk_i32 s2, 0x68
	v_cmp_lt_i32_e64 s[2:3], s2, v71
	s_nop 1
	v_cndmask_b32_e64 v83, v174, v24, s[2:3]
	v_max_f32_e32 v23, v9, v83
	v_max3_f32 v4, v4, v5, v23
	v_add_f32_e32 v5, v78, v156
	v_add_f32_e32 v23, v78, v88
	v_fmac_f32_e32 v5, 0x3e0293ee, v58
	v_fmac_f32_e32 v23, 0x3e0293ee, v10
	v_add_f32_e32 v10, v78, v162
	v_cmp_lt_i32_e64 s[2:3], 9, v71
	v_fmac_f32_e32 v10, 0x3e0293ee, v42
	v_add_f32_e32 v24, v78, v92
	v_cndmask_b32_e64 v42, v174, v5, s[2:3]
	v_cmp_lt_i32_e64 s[2:3], 41, v71
	v_fmac_f32_e32 v24, 0x3e0293ee, v26
	s_nop 0
	v_cndmask_b32_e64 v85, v174, v23, s[2:3]
	s_movk_i32 s2, 0x49
	v_cmp_lt_i32_e64 s[2:3], s2, v71
	v_max_f32_e32 v5, v42, v85
	v_add_f32_e32 v23, v76, v92
	v_cndmask_b32_e64 v87, v174, v10, s[2:3]
	s_movk_i32 s2, 0x69
	v_cmp_lt_i32_e64 s[2:3], s2, v71
	v_fmac_f32_e32 v23, 0x3e0293ee, v27
	s_nop 0
	v_cndmask_b32_e64 v89, v174, v24, s[2:3]
	v_max_f32_e32 v10, v87, v89
	v_max3_f32 v4, v4, v5, v10
	v_add_f32_e32 v5, v76, v156
	v_fmac_f32_e32 v5, 0x3e0293ee, v59
	v_add_f32_e32 v10, v76, v88
	v_cmp_lt_i32_e64 s[2:3], 10, v71
	v_fmac_f32_e32 v10, 0x3e0293ee, v11
	v_add_f32_e32 v11, v76, v162
	v_cndmask_b32_e64 v27, v174, v5, s[2:3]
	v_cmp_lt_i32_e64 s[2:3], 42, v71
	v_fmac_f32_e32 v11, 0x3e0293ee, v43
	s_nop 0
	v_cndmask_b32_e64 v59, v174, v10, s[2:3]
	s_movk_i32 s2, 0x4a
	v_cmp_lt_i32_e64 s[2:3], s2, v71
	v_max_f32_e32 v5, v27, v59
	s_nop 0
	v_cndmask_b32_e64 v88, v174, v11, s[2:3]
	s_movk_i32 s2, 0x6a
	v_cmp_lt_i32_e64 s[2:3], s2, v71
	v_add_f32_e32 v11, 0, v86
	v_fmac_f32_e32 v11, 0x3e0293ee, v44
	v_cndmask_b32_e64 v90, v174, v23, s[2:3]
	v_max_f32_e32 v10, v88, v90
	v_max3_f32 v4, v4, v5, v10
	v_add_f32_e32 v5, 0, v82
	v_add_f32_e32 v10, 0, v84
	v_fmac_f32_e32 v5, 0x3e0293ee, v60
	v_fmac_f32_e32 v10, 0x3e0293ee, v12
	v_add_f32_e32 v12, 0, v77
	v_cmp_lt_i32_e64 s[2:3], 15, v71
	v_fmac_f32_e32 v12, 0x3e0293ee, v28
; __device__ __forceinline__ float swapmax(float x) { auto rr = __builtin_amdgcn_permlane32_swap(__float_as_uint(x), __float_as_uint(x), false, false); return fmaxf(__uint_as_float(rr[0]), __uint_as_float(rr[1])); }
; template <int VAR>
; __device__ __forceinline__ void nsa_attn_mfma(Frame& F, bf16* Y) {
;     ...
;       for (int r = 0; r < 16; ++r) { const int c = (r & 3) + 8 * (r >> 2);
;         float a0 = fmaf(pA0[r], CSC, ca_[r & 3] + cb_[r >> 2]), a1 = fmaf(pA1[r], CSC, ca_[r & 3] + cb_[4 + (r >> 2)]);
;         float b0 = fmaf(pB0[r], CSC, ca_[r & 3] + cb_[8 + (r >> 2)]), b1 = fmaf(pB1[r], CSC, ca_[r & 3] + cb_[12 + (r >> 2)]);
;         a0 = (c > nlim) ? -1e30f : a0; a1 = (c + 32 > nlim) ? -1e30f : a1;
;         b0 = (c + 64 > nlim) ? -1e30f : b0; b1 = (c + 96 > nlim || (c == 27 && hi)) ? -1e30f : b1;
;         pA0[r] = a0; pA1[r] = a1; pB0[r] = b0; pB1[r] = b1; mx = fmaxf(fmaxf(mx, fmaxf(a0, a1)), fmaxf(b0, b1)); }
;       mx = swapmax(mx);
;       float ps = 0.f;
; #pragma unroll
;       for (int r = 0; r < 16; ++r) { pA0[r] = __builtin_amdgcn_exp2f(pA0[r] - mx); pA1[r] = __builtin_amdgcn_exp2f(pA1[r] - mx); pB0[r] = __builtin_amdgcn_exp2f(pB0[r] - mx); pB1[r] = __builtin_amdgcn_exp2f(pB1[r] - mx);
	s_nop 0
	v_cndmask_b32_e64 v28, v174, v5, s[2:3]
	v_cmp_lt_i32_e64 s[2:3], 47, v71
	s_nop 1
	v_cndmask_b32_e64 v44, v174, v10, s[2:3]
	s_movk_i32 s2, 0x4f
	v_cmp_lt_i32_e64 s[2:3], s2, v71
	v_max_f32_e32 v5, v28, v44
	s_nop 0
	v_cndmask_b32_e64 v60, v174, v11, s[2:3]
	s_movk_i32 s2, 0x6f
	v_cmp_lt_i32_e64 s[2:3], s2, v71
	v_add_f32_e32 v11, v80, v86
	v_fmac_f32_e32 v11, 0x3e0293ee, v45
	v_cndmask_b32_e64 v91, v174, v12, s[2:3]
	v_max_f32_e32 v10, v60, v91
	v_max3_f32 v4, v4, v5, v10
	v_add_f32_e32 v5, v80, v82
	v_fmac_f32_e32 v5, 0x3e0293ee, v61
	v_add_f32_e32 v10, v80, v84
	v_add_f32_e32 v12, v80, v77
	v_cmp_lt_i32_e64 s[2:3], 16, v71
	v_fmac_f32_e32 v10, 0x3e0293ee, v13
	v_fmac_f32_e32 v12, 0x3e0293ee, v29
	v_cndmask_b32_e64 v29, v174, v5, s[2:3]
	v_cmp_lt_i32_e64 s[2:3], 48, v71
	s_nop 1
	v_cndmask_b32_e64 v45, v174, v10, s[2:3]
	s_movk_i32 s2, 0x50
	v_cmp_lt_i32_e64 s[2:3], s2, v71
	v_max_f32_e32 v5, v29, v45
	s_nop 0
	v_cndmask_b32_e64 v92, v174, v11, s[2:3]
	s_movk_i32 s2, 0x70
	v_cmp_lt_i32_e64 s[2:3], s2, v71
	v_add_f32_e32 v11, v78, v86
	v_fmac_f32_e32 v11, 0x3e0293ee, v46
	v_cndmask_b32_e64 v93, v174, v12, s[2:3]
	v_max_f32_e32 v10, v92, v93
	v_max3_f32 v4, v4, v5, v10
	v_add_f32_e32 v5, v78, v82
	v_fmac_f32_e32 v5, 0x3e0293ee, v62
	v_add_f32_e32 v10, v78, v84
	v_cmp_lt_i32_e64 s[2:3], 17, v71
	v_fmac_f32_e32 v10, 0x3e0293ee, v14
	v_add_f32_e32 v12, v78, v77
	v_cndmask_b32_e64 v14, v174, v5, s[2:3]
	v_cmp_lt_i32_e64 s[2:3], 49, v71
	v_fmac_f32_e32 v12, 0x3e0293ee, v30
	s_nop 0
	v_cndmask_b32_e64 v30, v174, v10, s[2:3]
	s_movk_i32 s2, 0x51
	v_cmp_lt_i32_e64 s[2:3], s2, v71
	v_max_f32_e32 v5, v14, v30
	s_nop 0
	v_cndmask_b32_e64 v46, v174, v11, s[2:3]
	s_movk_i32 s2, 0x71
	v_cmp_lt_i32_e64 s[2:3], s2, v71
	v_add_f32_e32 v11, v76, v86
	v_fmac_f32_e32 v11, 0x3e0293ee, v47
	v_cndmask_b32_e64 v94, v174, v12, s[2:3]
	v_max_f32_e32 v10, v46, v94
	v_max3_f32 v4, v4, v5, v10
	v_add_f32_e32 v5, v76, v82
	v_fmac_f32_e32 v5, 0x3e0293ee, v63
	v_add_f32_e32 v10, v76, v84
	v_cmp_lt_i32_e64 s[2:3], 18, v71
	v_fmac_f32_e32 v10, 0x3e0293ee, v15
	v_add_f32_e32 v12, v76, v77
	v_cndmask_b32_e64 v15, v174, v5, s[2:3]
	v_cmp_lt_i32_e64 s[2:3], 50, v71
	v_fmac_f32_e32 v12, 0x3e0293ee, v31
	s_nop 0
	v_cndmask_b32_e64 v31, v174, v10, s[2:3]
	s_movk_i32 s2, 0x52
	v_cmp_lt_i32_e64 s[2:3], s2, v71
	v_max_f32_e32 v5, v15, v31
	s_nop 0
	v_cndmask_b32_e64 v47, v174, v11, s[2:3]
	s_movk_i32 s2, 0x72
	v_cmp_lt_i32_e64 s[2:3], s2, v71
	v_add_f32_e32 v11, 0, v74
	v_fmac_f32_e32 v11, 0x3e0293ee, v48
	v_cndmask_b32_e64 v77, v174, v12, s[2:3]
	v_max_f32_e32 v10, v47, v77
	v_max3_f32 v4, v4, v5, v10
	v_add_f32_e32 v5, 0, v70
	v_fmac_f32_e32 v5, 0x3e0293ee, v64
	v_add_f32_e32 v10, 0, v72
	v_cmp_lt_i32_e64 s[2:3], 23, v71
	v_fmac_f32_e32 v10, 0x3e0293ee, v16
	v_add_f32_e32 v12, 0, v2
	v_cndmask_b32_e64 v16, v174, v5, s[2:3]
	v_cmp_lt_i32_e64 s[2:3], 55, v71
	v_fmac_f32_e32 v12, 0x3e0293ee, v32
	s_nop 0
	v_cndmask_b32_e64 v32, v174, v10, s[2:3]
	s_movk_i32 s2, 0x57
	v_cmp_lt_i32_e64 s[2:3], s2, v71
	v_max_f32_e32 v5, v16, v32
	s_nop 0
	v_cndmask_b32_e64 v48, v174, v11, s[2:3]
	s_movk_i32 s2, 0x77
	v_cmp_lt_i32_e64 s[2:3], s2, v71
	v_add_f32_e32 v11, v80, v74
	v_fmac_f32_e32 v11, 0x3e0293ee, v49
	v_cndmask_b32_e64 v82, v174, v12, s[2:3]
	v_max_f32_e32 v10, v48, v82
	v_max3_f32 v4, v4, v5, v10
	v_add_f32_e32 v5, v80, v70
	v_fmac_f32_e32 v5, 0x3e0293ee, v65
	v_add_f32_e32 v10, v80, v72
	v_cmp_lt_i32_e64 s[2:3], 24, v71
	v_fmac_f32_e32 v10, 0x3e0293ee, v17
	v_add_f32_e32 v12, v80, v2
	v_cndmask_b32_e64 v17, v174, v5, s[2:3]
	v_cmp_lt_i32_e64 s[2:3], 56, v71
	v_fmac_f32_e32 v12, 0x3e0293ee, v33
	s_nop 0
	v_cndmask_b32_e64 v33, v174, v10, s[2:3]
	s_movk_i32 s2, 0x58
	v_cmp_lt_i32_e64 s[2:3], s2, v71
	v_max_f32_e32 v5, v17, v33
	s_nop 0
	v_cndmask_b32_e64 v49, v174, v11, s[2:3]
	s_movk_i32 s2, 0x78
	v_cmp_lt_i32_e64 s[2:3], s2, v71
	v_add_f32_e32 v11, v78, v74
	v_fmac_f32_e32 v11, 0x3e0293ee, v50
	v_cndmask_b32_e64 v80, v174, v12, s[2:3]
	v_max_f32_e32 v10, v49, v80
	v_max3_f32 v4, v4, v5, v10
	v_add_f32_e32 v5, v78, v70
	v_fmac_f32_e32 v5, 0x3e0293ee, v66
	v_add_f32_e32 v10, v78, v72
	v_cmp_lt_i32_e64 s[2:3], 25, v71
	v_fmac_f32_e32 v10, 0x3e0293ee, v18
	v_add_f32_e32 v12, v78, v2
	v_cndmask_b32_e64 v78, v174, v5, s[2:3]
	v_cmp_lt_i32_e64 s[2:3], 57, v71
	v_fmac_f32_e32 v12, 0x3e0293ee, v34
	v_add_f32_e32 v2, v76, v2
	v_cndmask_b32_e64 v84, v174, v10, s[2:3]
	s_movk_i32 s2, 0x59
	v_cmp_lt_i32_e64 s[2:3], s2, v71
	v_max_f32_e32 v5, v78, v84
	v_fmac_f32_e32 v2, 0x3e0293ee, v35
	v_cndmask_b32_e64 v86, v174, v11, s[2:3]
	s_movk_i32 s2, 0x79
	v_cmp_lt_i32_e64 s[2:3], s2, v71
	v_add_f32_e32 v11, v76, v74
	v_fmac_f32_e32 v11, 0x3e0293ee, v51
	v_cndmask_b32_e64 v95, v174, v12, s[2:3]
	v_max_f32_e32 v10, v86, v95
	v_max3_f32 v4, v4, v5, v10
	v_add_f32_e32 v5, v76, v70
	v_fmac_f32_e32 v5, 0x3e0293ee, v67
	v_add_f32_e32 v10, v76, v72
	v_cmp_lt_i32_e64 s[2:3], 26, v71
	v_fmac_f32_e32 v10, 0x3e0293ee, v19
	s_nop 0
	v_cndmask_b32_e64 v67, v174, v5, s[2:3]
	v_cmp_lt_i32_e64 s[2:3], 58, v71
	s_nop 1
	v_cndmask_b32_e64 v70, v174, v10, s[2:3]
	s_movk_i32 s2, 0x5a
	v_cmp_lt_i32_e64 s[2:3], s2, v71
	v_max_f32_e32 v5, v67, v70
	s_nop 0
	v_cndmask_b32_e64 v72, v174, v11, s[2:3]
	s_movk_i32 s2, 0x7b
	v_cmp_gt_i32_e64 s[2:3], s2, v71
	s_or_b64 vcc, vcc, s[2:3]
	v_readlane_b32 s2, v254, 49
	s_mov_b32 m0, s2
	v_cndmask_b32_e32 v2, v2, v174, vcc
	global_load_lds_dwordx4 v[68:69], off
	v_max_f32_e32 v10, v72, v2
	v_max3_f32 v4, v4, v5, v10
	v_mov_b32_e32 v5, v4
	s_nop 1
	v_permlane32_swap_b32_e32 v4, v5
	v_max_f32_e32 v5, v5, v5
	v_max_f32_e32 v4, v4, v4
	v_max_f32_e32 v71, v4, v5
	v_sub_f32_e32 v9, v9, v71
; __device__ __forceinline__ float swapsum(float x) { auto rr = __builtin_amdgcn_permlane32_swap(__float_as_uint(x), __float_as_uint(x), false, false); return __uint_as_float(rr[0]) + __uint_as_float(rr[1]); }
; template <int VAR>
; __device__ __forceinline__ void nsa_attn_mfma(Frame& F, bf16* Y) {
;     ...
; #pragma unroll
;       for (int r = 0; r < 16; ++r) { pA0[r] = __builtin_amdgcn_exp2f(pA0[r] - mx); pA1[r] = __builtin_amdgcn_exp2f(pA1[r] - mx); pB0[r] = __builtin_amdgcn_exp2f(pB0[r] - mx); pB1[r] = __builtin_amdgcn_exp2f(pB1[r] - mx);
;         ps += (pA0[r] + pA1[r]) + (pB0[r] + pB1[r]); }
;       ps = swapsum(ps);
;       const float anyv = (t >= 31) ? 1.f : 0.f; const float inv = anyv / ps;
;       bf16x8 pa0, pa1, pa2, pa3;
;       bf16x8 pa4, pa5, pa6, pa7;
;       PK4(pA0, 0, pa0); PK4(pA0, 8, pa1); PK4(pA1, 0, pa2); PK4(pA1, 8, pa3);
;       PK4(pB0, 0, pa4); PK4(pB0, 8, pa5); PK4(pB1, 0, pa6); PK4(pB1, 8, pa7);
	v_exp_f32_e32 v168, v9
	v_sub_f32_e32 v9, v83, v71
	v_sub_f32_e32 v4, v20, v71
	v_sub_f32_e32 v5, v52, v71
	v_sub_f32_e32 v10, v73, v71
	v_sub_f32_e32 v11, v36, v71
	v_sub_f32_e32 v20, v75, v71
	v_exp_f32_e32 v170, v9
	v_sub_f32_e32 v9, v42, v71
	v_exp_f32_e32 v4, v4
	v_exp_f32_e32 v5, v5
	v_exp_f32_e32 v10, v10
	v_exp_f32_e32 v12, v11
	v_sub_f32_e32 v11, v21, v71
	v_sub_f32_e32 v13, v53, v71
	v_exp_f32_e32 v23, v20
	v_sub_f32_e32 v20, v37, v71
	v_exp_f32_e32 v163, v9
	v_sub_f32_e32 v9, v85, v71
	v_exp_f32_e32 v11, v11
	v_exp_f32_e32 v13, v13
	v_exp_f32_e32 v24, v20
	v_exp_f32_e32 v164, v9
	v_sub_f32_e32 v9, v87, v71
	v_exp_f32_e32 v165, v9
	v_sub_f32_e32 v9, v89, v71
	v_exp_f32_e32 v166, v9
	v_sub_f32_e32 v9, v27, v71
	v_add_f32_e32 v18, v4, v5
	v_add_f32_e32 v19, v10, v12
	v_sub_f32_e32 v21, v22, v71
	v_sub_f32_e32 v6, v6, v71
	v_exp_f32_e32 v156, v9
	v_sub_f32_e32 v9, v59, v71
	v_add_f32_e32 v18, v18, v19
	v_add_f32_e32 v19, v11, v13
	v_add_f32_e32 v20, v23, v24
	v_exp_f32_e32 v25, v21
	v_sub_f32_e32 v21, v54, v71
	v_exp_f32_e32 v35, v6
	v_sub_f32_e32 v6, v38, v71
	v_exp_f32_e32 v157, v9
	v_sub_f32_e32 v9, v88, v71
	v_exp_f32_e32 v26, v21
	v_exp_f32_e32 v43, v6
	v_add_f32_e32 v6, v19, v20
	v_sub_f32_e32 v20, v79, v71
	v_sub_f32_e32 v7, v7, v71
	v_exp_f32_e32 v158, v9
	v_sub_f32_e32 v9, v90, v71
	v_exp_f32_e32 v58, v20
	v_sub_f32_e32 v20, v55, v71
	v_exp_f32_e32 v154, v7
	v_sub_f32_e32 v7, v39, v71
	v_exp_f32_e32 v155, v9
	v_sub_f32_e32 v9, v28, v71
	v_exp_f32_e32 v152, v20
	v_exp_f32_e32 v39, v7
	v_exp_f32_e32 v61, v9
	v_sub_f32_e32 v9, v44, v71
	v_add_f32_e32 v18, 0, v18
	v_exp_f32_e32 v63, v9
	v_sub_f32_e32 v9, v60, v71
	v_add_f32_e32 v6, v6, v18
	v_add_f32_e32 v18, v25, v26
	v_add_f32_e32 v19, v35, v43
	v_exp_f32_e32 v64, v9
	v_sub_f32_e32 v9, v91, v71
	v_add_f32_e32 v7, v18, v19
	v_sub_f32_e32 v19, v56, v71
	v_sub_f32_e32 v8, v8, v71
	v_exp_f32_e32 v66, v9
	v_sub_f32_e32 v9, v29, v71
	v_add_f32_e32 v6, v7, v6
	v_add_f32_e32 v7, v58, v152
	v_add_f32_e32 v18, v154, v39
	v_exp_f32_e32 v62, v19
	v_sub_f32_e32 v19, v81, v71
	v_exp_f32_e32 v159, v8
	v_sub_f32_e32 v8, v40, v71
	v_exp_f32_e32 v50, v9
	v_sub_f32_e32 v9, v45, v71
	v_exp_f32_e32 v65, v19
	v_exp_f32_e32 v161, v8
	v_add_f32_e32 v7, v7, v18
	v_sub_f32_e32 v18, v41, v71
	v_exp_f32_e32 v51, v9
	v_sub_f32_e32 v9, v92, v71
	v_exp_f32_e32 v160, v18
	v_sub_f32_e32 v18, v57, v71
	v_exp_f32_e32 v56, v9
	v_sub_f32_e32 v9, v93, v71
	v_exp_f32_e32 v162, v18
	v_exp_f32_e32 v57, v9
	v_sub_f32_e32 v9, v14, v71
	v_exp_f32_e32 v42, v9
	v_sub_f32_e32 v9, v30, v71
	v_add_f32_e32 v6, v7, v6
	v_add_f32_e32 v7, v62, v65
	v_add_f32_e32 v8, v159, v161
	v_exp_f32_e32 v44, v9
	v_sub_f32_e32 v9, v46, v71
	v_add_f32_e32 v7, v7, v8
	v_exp_f32_e32 v45, v9
	v_sub_f32_e32 v9, v94, v71
	v_add_f32_e32 v6, v7, v6
	v_add_f32_e32 v7, v160, v162
	v_add_f32_e32 v8, v168, v170
	v_exp_f32_e32 v46, v9
	v_sub_f32_e32 v9, v15, v71
	v_add_f32_e32 v7, v7, v8
	v_exp_f32_e32 v36, v9
	v_sub_f32_e32 v9, v31, v71
	v_add_f32_e32 v6, v7, v6
	v_add_f32_e32 v7, v163, v164
	v_add_f32_e32 v8, v165, v166
	v_exp_f32_e32 v37, v9
	v_sub_f32_e32 v9, v47, v71
	v_add_f32_e32 v7, v7, v8
	v_exp_f32_e32 v38, v9
	v_sub_f32_e32 v9, v77, v71
	v_add_f32_e32 v6, v7, v6
	v_add_f32_e32 v7, v156, v157
	v_add_f32_e32 v8, v158, v155
	v_exp_f32_e32 v34, v9
	v_sub_f32_e32 v9, v16, v71
	v_add_f32_e32 v7, v7, v8
	v_exp_f32_e32 v27, v9
	v_sub_f32_e32 v9, v32, v71
	v_add_f32_e32 v6, v7, v6
	v_add_f32_e32 v7, v61, v63
	v_add_f32_e32 v8, v64, v66
	v_exp_f32_e32 v28, v9
	v_sub_f32_e32 v9, v48, v71
	v_add_f32_e32 v7, v7, v8
	v_exp_f32_e32 v29, v9
	v_sub_f32_e32 v9, v82, v71
	v_add_f32_e32 v6, v7, v6
	v_add_f32_e32 v7, v50, v51
	v_add_f32_e32 v8, v56, v57
	v_exp_f32_e32 v30, v9
	v_sub_f32_e32 v9, v17, v71
	v_add_f32_e32 v7, v7, v8
	v_exp_f32_e32 v18, v9
	v_sub_f32_e32 v9, v33, v71
	v_add_f32_e32 v6, v7, v6
	v_add_f32_e32 v7, v42, v44
	v_add_f32_e32 v8, v45, v46
	v_exp_f32_e32 v19, v9
	v_sub_f32_e32 v9, v49, v71
	v_add_f32_e32 v7, v7, v8
	v_exp_f32_e32 v20, v9
	v_sub_f32_e32 v9, v80, v71
	v_add_f32_e32 v6, v7, v6
	v_add_f32_e32 v7, v36, v37
	v_add_f32_e32 v8, v38, v34
	v_exp_f32_e32 v22, v9
	v_add_f32_e32 v7, v7, v8
	v_sub_f32_e32 v9, v78, v71
	v_add_f32_e32 v6, v7, v6
	v_add_f32_e32 v7, v27, v28
	v_add_f32_e32 v8, v29, v30
	v_exp_f32_e32 v14, v9
	v_sub_f32_e32 v9, v84, v71
	v_add_f32_e32 v7, v7, v8
	v_exp_f32_e32 v15, v9
	v_sub_f32_e32 v9, v86, v71
	v_add_f32_e32 v6, v7, v6
	v_add_f32_e32 v7, v18, v19
	v_add_f32_e32 v8, v20, v22
	v_exp_f32_e32 v16, v9
	v_sub_f32_e32 v9, v95, v71
	v_exp_f32_e32 v17, v9
	v_add_f32_e32 v7, v7, v8
	v_add_f32_e32 v21, v7, v6
	v_sub_f32_e32 v6, v67, v71
	v_sub_f32_e32 v7, v70, v71
	v_sub_f32_e32 v8, v72, v71
	v_sub_f32_e32 v2, v2, v71
	v_exp_f32_e32 v6, v6
	v_exp_f32_e32 v7, v7
	v_exp_f32_e32 v8, v8
	v_exp_f32_e32 v9, v2
	v_add_f32_e32 v31, v14, v15
	v_add_f32_e32 v32, v16, v17
	v_add_f32_e32 v2, v31, v32
	v_add_f32_e32 v2, v2, v21
	v_add_f32_e32 v21, v6, v7
	v_add_f32_e32 v31, v8, v9
	v_add_f32_e32 v21, v21, v31
	v_add_f32_e32 v2, v21, v2
	v_mov_b32_e32 v21, v2
	s_nop 1
	v_permlane32_swap_b32_e32 v2, v21
	v_cmp_lt_i32_e32 vcc, 30, v181
	v_add_f32_e32 v2, v2, v21
	v_cvt_pk_bf16_f32 v52, v4, v11
	v_cvt_pk_bf16_f32 v53, v25, v58
	v_cvt_pk_bf16_f32 v54, v62, v160
	v_cvt_pk_bf16_f32 v55, v163, v156
	s_nop 0
	v_cndmask_b32_e64 v21, 0, 1.0, vcc
	v_div_scale_f32 v31, s[2:3], v2, v2, v21
	v_rcp_f32_e32 v32, v31
	v_cvt_pk_bf16_f32 v92, v61, v50
	v_cvt_pk_bf16_f32 v93, v42, v36
	v_cvt_pk_bf16_f32 v94, v27, v18
	v_cvt_pk_bf16_f32 v95, v14, v6
	v_cvt_pk_bf16_f32 v88, v5, v13
	s_nop 0
	v_fma_f32 v33, -v31, v32, 1.0
	v_fmac_f32_e32 v32, v33, v32
; #define SBAR() __builtin_amdgcn_sched_barrier(0)
; template <int VAR>
; __device__ __forceinline__ void nsa_attn_mfma(Frame& F, bf16* Y) {
;     ...
;       const float anyv = (t >= 31) ? 1.f : 0.f; const float inv = anyv / ps;
;       bf16x8 pa0, pa1, pa2, pa3;
;       bf16x8 pa4, pa5, pa6, pa7;
;       PK4(pA0, 0, pa0); PK4(pA0, 8, pa1); PK4(pA1, 0, pa2); PK4(pA1, 8, pa3);
;       PK4(pB0, 0, pa4); PK4(pB0, 8, pa5); PK4(pB1, 0, pa6); PK4(pB1, 8, pa7);
;       SBAR();
;       if (cur <= 15) {
;         if (lane == 0) { mkl[4 * wid + 0] = 0xffffffffu; mkl[4 * wid + 1] = 0xffffffffu; mkl[4 * wid + 2] = 0xffffffffu; mkl[4 * wid + 3] = 0xffffffffu; }
;       } else {
; #pragma unroll
;       for (int r = 0; r < 16; ++r) {
;         float a0 = pA0[r] * inv, a1 = pA1[r] * inv, b0 = pB0[r] * inv, b1 = pB1[r] * inv;
;         a0 += __shfl_xor(a0, 1); a1 += __shfl_xor(a1, 1); b0 += __shfl_xor(b0, 1); b1 += __shfl_xor(b1, 1);
;         a0 += __shfl_xor(a0, 2); a1 += __shfl_xor(a1, 2); b0 += __shfl_xor(b0, 2); b1 += __shfl_xor(b1, 2);
;         a0 += __shfl_xor(a0, 4); a1 += __shfl_xor(a1, 4); b0 += __shfl_xor(b0, 4); b1 += __shfl_xor(b1, 4);
;         pA0[r] = a0; pA1[r] = a1; pB0[r] = b0; pB1[r] = b1; }
	v_div_scale_f32 v33, vcc, v21, v2, v21
	v_mul_f32_e32 v40, v33, v32
	v_fma_f32 v41, -v31, v40, v33
	v_fmac_f32_e32 v40, v41, v32
	v_fma_f32 v31, -v31, v40, v33
	v_div_fmas_f32 v31, v31, v32, v40
	v_cvt_pk_bf16_f32 v89, v26, v152
	v_cvt_pk_bf16_f32 v90, v65, v162
	v_cvt_pk_bf16_f32 v91, v164, v157
	v_cvt_pk_bf16_f32 v84, v63, v51
	v_cvt_pk_bf16_f32 v85, v44, v37
	v_cvt_pk_bf16_f32 v86, v28, v19
	v_cvt_pk_bf16_f32 v87, v15, v7
	v_cvt_pk_bf16_f32 v68, v10, v23
	v_cvt_pk_bf16_f32 v69, v35, v154
	v_cvt_pk_bf16_f32 v70, v159, v168
	v_cvt_pk_bf16_f32 v71, v165, v158
	v_cvt_pk_bf16_f32 v72, v64, v56
	v_cvt_pk_bf16_f32 v73, v45, v38
	v_cvt_pk_bf16_f32 v74, v29, v20
	v_cvt_pk_bf16_f32 v75, v16, v8
	v_cvt_pk_bf16_f32 v76, v12, v24
	v_cvt_pk_bf16_f32 v77, v43, v39
	v_cvt_pk_bf16_f32 v78, v161, v170
	v_cvt_pk_bf16_f32 v79, v166, v155
	v_cvt_pk_bf16_f32 v80, v66, v57
	v_cvt_pk_bf16_f32 v81, v46, v34
	v_cvt_pk_bf16_f32 v82, v30, v22
	v_cvt_pk_bf16_f32 v83, v17, v9
	v_div_fixup_f32 v2, v31, v2, v21
	v_permlane32_swap_b32_e32 v52, v54
	v_permlane32_swap_b32_e32 v53, v55
	v_permlane32_swap_b32_e32 v92, v94
	v_permlane32_swap_b32_e32 v93, v95
	v_permlane32_swap_b32_e32 v88, v90
	v_permlane32_swap_b32_e32 v89, v91
	v_permlane32_swap_b32_e32 v84, v86
	v_permlane32_swap_b32_e32 v85, v87
	v_permlane32_swap_b32_e32 v68, v70
	v_permlane32_swap_b32_e32 v69, v71
	v_permlane32_swap_b32_e32 v72, v74
	v_permlane32_swap_b32_e32 v73, v75
	v_permlane32_swap_b32_e32 v76, v78
	v_permlane32_swap_b32_e32 v77, v79
	v_permlane32_swap_b32_e32 v80, v82
	v_permlane32_swap_b32_e32 v81, v83
	s_mov_b64 s[2:3], -1
	s_cmp_lt_u32 s4, 32
	v_cmp_gt_u32_e32 vcc, 32, v178
	s_cbranch_scc1 .LBB0_2415
	v_and_b32_e32 v31, 64, v175
	v_xor_b32_e32 v21, 1, v175
	v_add_u32_e32 v41, 64, v31
	v_cmp_lt_i32_e64 s[2:3], v21, v41
	v_mul_f32_e32 v31, v2, v4
	v_mul_f32_e32 v32, v2, v5
	v_cndmask_b32_e64 v21, v175, v21, s[2:3]
	v_lshlrev_b32_e32 v60, 2, v21
	v_mul_f32_e32 v33, v2, v10
	v_mul_f32_e32 v40, v2, v12
	ds_bpermute_b32 v31, v60, v31
	ds_bpermute_b32 v32, v60, v32
	ds_bpermute_b32 v33, v60, v33
	ds_bpermute_b32 v40, v60, v40
	v_xor_b32_e32 v21, 2, v175
	v_cmp_lt_i32_e64 s[2:3], v21, v41
	s_waitcnt lgkmcnt(0)
	v_fmac_f32_e32 v31, v2, v4
	v_fmac_f32_e32 v32, v2, v5
	v_cndmask_b32_e64 v21, v175, v21, s[2:3]
	v_lshlrev_b32_e32 v59, 2, v21
	v_fmac_f32_e32 v33, v2, v10
	v_fmac_f32_e32 v40, v2, v12
	ds_bpermute_b32 v4, v59, v31
	ds_bpermute_b32 v5, v59, v32
	ds_bpermute_b32 v12, v59, v33
	ds_bpermute_b32 v47, v59, v40
	v_xor_b32_e32 v21, 4, v175
	v_cmp_lt_i32_e64 s[2:3], v21, v41
	s_waitcnt lgkmcnt(0)
	v_add_f32_e32 v4, v31, v4
	v_add_f32_e32 v10, v32, v5
	v_cndmask_b32_e64 v21, v175, v21, s[2:3]
	v_lshlrev_b32_e32 v139, 2, v21
	v_add_f32_e32 v21, v33, v12
	v_add_f32_e32 v32, v40, v47
	v_mul_f32_e32 v31, v2, v11
	v_mul_f32_e32 v33, v2, v13
	v_mul_f32_e32 v40, v2, v23
	v_mul_f32_e32 v47, v2, v24
	ds_bpermute_b32 v48, v60, v31
	ds_bpermute_b32 v33, v60, v33
	ds_bpermute_b32 v40, v60, v40
	ds_bpermute_b32 v49, v60, v47
	v_mul_f32_e32 v153, v2, v43
	s_waitcnt lgkmcnt(0)
	v_fmac_f32_e32 v48, v2, v11
	v_fmac_f32_e32 v33, v2, v13
	v_fmac_f32_e32 v40, v2, v23
	v_fmac_f32_e32 v49, v2, v24
	ds_bpermute_b32 v11, v59, v48
	ds_bpermute_b32 v13, v59, v33
	ds_bpermute_b32 v24, v59, v40
	ds_bpermute_b32 v67, v59, v49
	ds_bpermute_b32 v153, v60, v153
	s_waitcnt lgkmcnt(0)
	v_add_f32_e32 v11, v48, v11
	v_add_f32_e32 v23, v33, v13
	v_add_f32_e32 v33, v40, v24
	v_add_f32_e32 v48, v49, v67
	v_mul_f32_e32 v40, v2, v25
	v_mul_f32_e32 v49, v2, v26
	v_mul_f32_e32 v67, v2, v35
	ds_bpermute_b32 v167, v60, v40
	ds_bpermute_b32 v49, v60, v49
	ds_bpermute_b32 v169, v60, v67
	v_fmac_f32_e32 v153, v2, v43
	ds_bpermute_b32 v171, v59, v153
	s_waitcnt lgkmcnt(0)
	v_fmac_f32_e32 v167, v2, v25
	v_fmac_f32_e32 v49, v2, v26
	v_fmac_f32_e32 v169, v2, v35
	ds_bpermute_b32 v25, v59, v167
	ds_bpermute_b32 v26, v59, v49
	ds_bpermute_b32 v43, v59, v169
	v_add_f32_e32 v153, v153, v171
	v_mul_f32_e32 v191, v2, v39
	s_waitcnt lgkmcnt(0)
	v_add_f32_e32 v25, v167, v25
	v_add_f32_e32 v35, v49, v26
	v_add_f32_e32 v49, v169, v43
	v_mul_f32_e32 v43, v2, v58
	v_mul_f32_e32 v167, v2, v152
	v_mul_f32_e32 v169, v2, v154
	ds_bpermute_b32 v171, v60, v43
	ds_bpermute_b32 v167, v60, v167
	ds_bpermute_b32 v169, v60, v169
	v_mul_f32_e32 v199, v2, v166
	ds_bpermute_b32 v199, v60, v199
	s_waitcnt lgkmcnt(0)
	v_fmac_f32_e32 v171, v2, v58
	v_fmac_f32_e32 v167, v2, v152
	v_fmac_f32_e32 v169, v2, v154
	ds_bpermute_b32 v58, v60, v191
	ds_bpermute_b32 v154, v59, v171
	ds_bpermute_b32 v191, v59, v167
	ds_bpermute_b32 v192, v59, v169
	v_fmac_f32_e32 v199, v2, v166
	s_waitcnt lgkmcnt(0)
	v_fmac_f32_e32 v58, v2, v39
	v_add_f32_e32 v39, v171, v154
	v_add_f32_e32 v154, v167, v191
	v_add_f32_e32 v169, v169, v192
	ds_bpermute_b32 v171, v59, v58
	ds_bpermute_b32 v191, v139, v39
	ds_bpermute_b32 v192, v139, v154
	ds_bpermute_b32 v193, v139, v169
	ds_bpermute_b32 v202, v59, v199
	s_waitcnt lgkmcnt(0)
	v_add_f32_e32 v171, v58, v171
	v_add_f32_e32 v39, v39, v191
	v_add_f32_e32 v58, v154, v192
	v_add_f32_e32 v154, v169, v193
	v_mul_f32_e32 v169, v2, v62
	v_mul_f32_e32 v191, v2, v65
	v_mul_f32_e32 v192, v2, v159
	v_mul_f32_e32 v193, v2, v161
	ds_bpermute_b32 v169, v60, v169
	ds_bpermute_b32 v191, v60, v191
	ds_bpermute_b32 v192, v60, v192
	ds_bpermute_b32 v193, v60, v193
	ds_bpermute_b32 v194, v139, v171
	s_waitcnt lgkmcnt(0)
	v_fmac_f32_e32 v169, v2, v62
	v_fmac_f32_e32 v191, v2, v65
	v_fmac_f32_e32 v192, v2, v159
	v_fmac_f32_e32 v193, v2, v161
	ds_bpermute_b32 v62, v59, v169
	ds_bpermute_b32 v65, v59, v191
	ds_bpermute_b32 v161, v59, v192
	ds_bpermute_b32 v195, v59, v193
	v_add_f32_e32 v171, v171, v194
	s_waitcnt lgkmcnt(0)
; template <int VAR>
; __device__ __forceinline__ void nsa_attn_mfma(Frame& F, bf16* Y) {
;     ...
;       for (int r = 0; r < 16; ++r) {
;         float a0 = pA0[r] * inv, a1 = pA1[r] * inv, b0 = pB0[r] * inv, b1 = pB1[r] * inv;
;         a0 += __shfl_xor(a0, 1); a1 += __shfl_xor(a1, 1); b0 += __shfl_xor(b0, 1); b1 += __shfl_xor(b1, 1);
;         a0 += __shfl_xor(a0, 2); a1 += __shfl_xor(a1, 2); b0 += __shfl_xor(b0, 2); b1 += __shfl_xor(b1, 2);
;         a0 += __shfl_xor(a0, 4); a1 += __shfl_xor(a1, 4); b0 += __shfl_xor(b0, 4); b1 += __shfl_xor(b1, 4);
;         pA0[r] = a0; pA1[r] = a1; pB0[r] = b0; pB1[r] = b1; }
	v_add_f32_e32 v62, v169, v62
	v_add_f32_e32 v159, v191, v65
	v_add_f32_e32 v169, v192, v161
	v_add_f32_e32 v192, v193, v195
	v_mul_f32_e32 v191, v2, v160
	v_mul_f32_e32 v193, v2, v162
	v_mul_f32_e32 v194, v2, v168
	v_mul_f32_e32 v195, v2, v170
	ds_bpermute_b32 v196, v60, v191
	ds_bpermute_b32 v193, v60, v193
	ds_bpermute_b32 v194, v60, v194
	ds_bpermute_b32 v197, v60, v195
	v_add_f32_e32 v199, v199, v202
	s_waitcnt lgkmcnt(0)
	v_fmac_f32_e32 v196, v2, v160
	v_fmac_f32_e32 v193, v2, v162
	v_fmac_f32_e32 v194, v2, v168
	v_fmac_f32_e32 v197, v2, v170
	ds_bpermute_b32 v160, v59, v196
	ds_bpermute_b32 v162, v59, v193
	ds_bpermute_b32 v170, v59, v194
	ds_bpermute_b32 v198, v59, v197
	v_mul_f32_e32 v203, v2, v155
	s_waitcnt lgkmcnt(0)
	v_add_f32_e32 v160, v196, v160
	v_add_f32_e32 v168, v193, v162
	v_add_f32_e32 v193, v194, v170
	v_add_f32_e32 v196, v197, v198
	v_mul_f32_e32 v194, v2, v163
	v_mul_f32_e32 v197, v2, v164
	v_mul_f32_e32 v198, v2, v165
	ds_bpermute_b32 v200, v60, v194
	ds_bpermute_b32 v197, v60, v197
	ds_bpermute_b32 v201, v60, v198
	v_mul_f32_e32 v211, v2, v46
	ds_bpermute_b32 v211, v60, v211
	s_waitcnt lgkmcnt(0)
	v_fmac_f32_e32 v200, v2, v163
	v_fmac_f32_e32 v197, v2, v164
	v_fmac_f32_e32 v201, v2, v165
	ds_bpermute_b32 v163, v59, v200
	ds_bpermute_b32 v164, v59, v197
	ds_bpermute_b32 v166, v59, v201
	v_fmac_f32_e32 v211, v2, v46
	ds_bpermute_b32 v214, v59, v211
	s_waitcnt lgkmcnt(0)
	v_add_f32_e32 v163, v200, v163
	v_add_f32_e32 v165, v197, v164
	v_add_f32_e32 v197, v201, v166
	v_mul_f32_e32 v166, v2, v156
	v_mul_f32_e32 v200, v2, v157
	v_mul_f32_e32 v201, v2, v158
	ds_bpermute_b32 v202, v60, v166
	ds_bpermute_b32 v200, v60, v200
	ds_bpermute_b32 v201, v60, v201
	v_add_f32_e32 v211, v211, v214
	v_mul_f32_e32 v215, v2, v34
	s_waitcnt lgkmcnt(0)
	v_fmac_f32_e32 v202, v2, v156
	v_fmac_f32_e32 v200, v2, v157
	v_fmac_f32_e32 v201, v2, v158
	ds_bpermute_b32 v156, v60, v203
	ds_bpermute_b32 v158, v59, v202
	ds_bpermute_b32 v203, v59, v200
	ds_bpermute_b32 v204, v59, v201
	v_mul_f32_e32 v224, v2, v17
	s_waitcnt lgkmcnt(0)
	v_fmac_f32_e32 v156, v2, v155
	v_add_f32_e32 v155, v202, v158
	v_add_f32_e32 v158, v200, v203
	v_add_f32_e32 v201, v201, v204
	ds_bpermute_b32 v202, v59, v156
	ds_bpermute_b32 v203, v139, v155
	ds_bpermute_b32 v204, v139, v158
	ds_bpermute_b32 v205, v139, v201
	ds_bpermute_b32 v226, v60, v224
	s_waitcnt lgkmcnt(0)
	v_add_f32_e32 v202, v156, v202
	v_add_f32_e32 v155, v155, v203
	v_add_f32_e32 v156, v158, v204
	v_add_f32_e32 v158, v201, v205
	v_mul_f32_e32 v201, v2, v61
	v_mul_f32_e32 v203, v2, v63
	v_mul_f32_e32 v204, v2, v64
	v_mul_f32_e32 v205, v2, v66
	ds_bpermute_b32 v201, v60, v201
	ds_bpermute_b32 v203, v60, v203
	ds_bpermute_b32 v204, v60, v204
	ds_bpermute_b32 v205, v60, v205
	ds_bpermute_b32 v206, v139, v202
	s_waitcnt lgkmcnt(0)
	v_fmac_f32_e32 v201, v2, v61
	v_fmac_f32_e32 v203, v2, v63
	v_fmac_f32_e32 v204, v2, v64
	v_fmac_f32_e32 v205, v2, v66
	ds_bpermute_b32 v61, v59, v201
	ds_bpermute_b32 v63, v59, v203
	ds_bpermute_b32 v66, v59, v204
	ds_bpermute_b32 v207, v59, v205
	v_add_f32_e32 v202, v202, v206
	s_waitcnt lgkmcnt(0)
	v_add_f32_e32 v61, v201, v61
	v_add_f32_e32 v64, v203, v63
	v_add_f32_e32 v201, v204, v66
	v_add_f32_e32 v204, v205, v207
	v_mul_f32_e32 v203, v2, v50
	v_mul_f32_e32 v205, v2, v51
	v_mul_f32_e32 v206, v2, v56
	v_mul_f32_e32 v207, v2, v57
	ds_bpermute_b32 v208, v60, v203
	ds_bpermute_b32 v205, v60, v205
	ds_bpermute_b32 v206, v60, v206
	ds_bpermute_b32 v209, v60, v207
	v_fmac_f32_e32 v226, v2, v17
	s_waitcnt lgkmcnt(0)
	v_fmac_f32_e32 v208, v2, v50
	v_fmac_f32_e32 v205, v2, v51
	v_fmac_f32_e32 v206, v2, v56
	v_fmac_f32_e32 v209, v2, v57
	ds_bpermute_b32 v50, v59, v208
	ds_bpermute_b32 v51, v59, v205
	ds_bpermute_b32 v57, v59, v206
	ds_bpermute_b32 v210, v59, v209
	ds_bpermute_b32 v227, v59, v226
	s_waitcnt lgkmcnt(0)
	v_add_f32_e32 v50, v208, v50
	v_add_f32_e32 v56, v205, v51
	v_add_f32_e32 v205, v206, v57
	v_add_f32_e32 v208, v209, v210
	v_mul_f32_e32 v206, v2, v42
	v_mul_f32_e32 v209, v2, v44
	v_mul_f32_e32 v210, v2, v45
	ds_bpermute_b32 v212, v60, v206
	ds_bpermute_b32 v209, v60, v209
	ds_bpermute_b32 v213, v60, v210
	v_add_f32_e32 v226, v226, v227
	v_mul_f32_e32 v227, v2, v9
	s_waitcnt lgkmcnt(0)
	v_fmac_f32_e32 v212, v2, v42
	v_fmac_f32_e32 v209, v2, v44
	v_fmac_f32_e32 v213, v2, v45
	ds_bpermute_b32 v42, v59, v212
	ds_bpermute_b32 v44, v59, v209
	ds_bpermute_b32 v46, v59, v213
	ds_bpermute_b32 v5, v139, v4
	ds_bpermute_b32 v12, v139, v10
	s_waitcnt lgkmcnt(0)
	v_add_f32_e32 v42, v212, v42
	v_add_f32_e32 v45, v209, v44
	v_add_f32_e32 v209, v213, v46
	v_mul_f32_e32 v46, v2, v36
	v_mul_f32_e32 v212, v2, v37
	v_mul_f32_e32 v213, v2, v38
	ds_bpermute_b32 v214, v60, v46
	ds_bpermute_b32 v212, v60, v212
	ds_bpermute_b32 v213, v60, v213
	ds_bpermute_b32 v31, v139, v21
	ds_bpermute_b32 v47, v139, v32
	s_waitcnt lgkmcnt(0)
	v_fmac_f32_e32 v214, v2, v36
	v_fmac_f32_e32 v212, v2, v37
	v_fmac_f32_e32 v213, v2, v38
	ds_bpermute_b32 v36, v60, v215
	ds_bpermute_b32 v38, v59, v214
	ds_bpermute_b32 v215, v59, v212
	ds_bpermute_b32 v217, v59, v213
	ds_bpermute_b32 v13, v139, v11
	s_waitcnt lgkmcnt(0)
	v_fmac_f32_e32 v36, v2, v34
	v_add_f32_e32 v34, v214, v38
	v_add_f32_e32 v38, v212, v215
	v_add_f32_e32 v213, v213, v217
	ds_bpermute_b32 v214, v59, v36
	ds_bpermute_b32 v215, v139, v34
	ds_bpermute_b32 v217, v139, v38
	ds_bpermute_b32 v218, v139, v213
	ds_bpermute_b32 v24, v139, v23
	s_waitcnt lgkmcnt(0)
; template <int VAR>
; __device__ __forceinline__ void nsa_attn_mfma(Frame& F, bf16* Y) {
;     ...
;       for (int r = 0; r < 16; ++r) {
;         float a0 = pA0[r] * inv, a1 = pA1[r] * inv, b0 = pB0[r] * inv, b1 = pB1[r] * inv;
;         a0 += __shfl_xor(a0, 1); a1 += __shfl_xor(a1, 1); b0 += __shfl_xor(b0, 1); b1 += __shfl_xor(b1, 1);
;         a0 += __shfl_xor(a0, 2); a1 += __shfl_xor(a1, 2); b0 += __shfl_xor(b0, 2); b1 += __shfl_xor(b1, 2);
;         a0 += __shfl_xor(a0, 4); a1 += __shfl_xor(a1, 4); b0 += __shfl_xor(b0, 4); b1 += __shfl_xor(b1, 4);
;         pA0[r] = a0; pA1[r] = a1; pB0[r] = b0; pB1[r] = b1; }
;       float slc[16];
; #pragma unroll
;       for (int T = 0; T < 4; ++T)
; #pragma unroll
;         for (int q = 0; q < 4; ++q) {
;           const f32x16& P = (T == 0) ? pA0 : (T == 1) ? pA1 : (T == 2) ? pB0 : pB1;
;           slc[T * 4 + q] = 2.f * (P[4 * q] + P[4 * q + 1] + P[4 * q + 2]) + P[4 * q + 3];
;           float a;
;           if (q > 0) a = P[4 * (q - 1) + 3];
;           else if (T > 0) { const f32x16& Pm = (T == 1) ? pA0 : (T == 2) ? pA1 : pB0; a = Pm[15]; }
;           else a = 0.f;
;           const float give = hi ? a : P[4 * q + 3];
;           slc[T * 4 + q] += __shfl_xor(give, 32); }
;       if (j == 0) {
	v_add_f32_e32 v214, v36, v214
	v_add_f32_e32 v34, v34, v215
	v_add_f32_e32 v36, v38, v217
	v_add_f32_e32 v38, v213, v218
	v_mul_f32_e32 v213, v2, v27
	v_mul_f32_e32 v215, v2, v28
	v_mul_f32_e32 v217, v2, v29
	v_mul_f32_e32 v218, v2, v30
	ds_bpermute_b32 v213, v60, v213
	ds_bpermute_b32 v215, v60, v215
	ds_bpermute_b32 v217, v60, v217
	ds_bpermute_b32 v218, v60, v218
	ds_bpermute_b32 v219, v139, v214
	s_waitcnt lgkmcnt(0)
	v_fmac_f32_e32 v213, v2, v27
	v_fmac_f32_e32 v215, v2, v28
	v_fmac_f32_e32 v217, v2, v29
	v_fmac_f32_e32 v218, v2, v30
	ds_bpermute_b32 v27, v59, v213
	ds_bpermute_b32 v28, v59, v215
	ds_bpermute_b32 v30, v59, v217
	ds_bpermute_b32 v220, v59, v218
	v_add_f32_e32 v214, v214, v219
	s_waitcnt lgkmcnt(0)
	v_add_f32_e32 v27, v213, v27
	v_add_f32_e32 v29, v215, v28
	v_add_f32_e32 v213, v217, v30
	v_add_f32_e32 v217, v218, v220
	v_mul_f32_e32 v215, v2, v18
	v_mul_f32_e32 v220, v2, v22
	v_mul_f32_e32 v218, v2, v19
	v_mul_f32_e32 v219, v2, v20
	ds_bpermute_b32 v221, v60, v215
	ds_bpermute_b32 v222, v60, v220
	ds_bpermute_b32 v218, v60, v218
	ds_bpermute_b32 v219, v60, v219
	ds_bpermute_b32 v40, v139, v33
	s_waitcnt lgkmcnt(0)
	v_fmac_f32_e32 v221, v2, v18
	v_fmac_f32_e32 v222, v2, v22
	v_fmac_f32_e32 v218, v2, v19
	v_fmac_f32_e32 v219, v2, v20
	ds_bpermute_b32 v18, v59, v221
	ds_bpermute_b32 v223, v59, v222
	ds_bpermute_b32 v19, v59, v218
	ds_bpermute_b32 v22, v59, v219
	ds_bpermute_b32 v67, v139, v48
	s_waitcnt lgkmcnt(0)
	v_add_f32_e32 v18, v221, v18
	v_add_f32_e32 v221, v222, v223
	v_mul_f32_e32 v222, v2, v15
	v_mul_f32_e32 v223, v2, v16
	v_add_f32_e32 v20, v218, v19
	v_add_f32_e32 v218, v219, v22
	v_mul_f32_e32 v219, v2, v14
	ds_bpermute_b32 v222, v60, v222
	ds_bpermute_b32 v223, v60, v223
	ds_bpermute_b32 v225, v60, v219
	ds_bpermute_b32 v26, v139, v25
	ds_bpermute_b32 v43, v139, v35
	s_waitcnt lgkmcnt(0)
	v_fmac_f32_e32 v222, v2, v15
	v_fmac_f32_e32 v223, v2, v16
	v_fmac_f32_e32 v225, v2, v14
	ds_bpermute_b32 v15, v59, v222
	ds_bpermute_b32 v17, v59, v223
	ds_bpermute_b32 v14, v59, v225
	ds_bpermute_b32 v152, v139, v49
	ds_bpermute_b32 v167, v139, v153
	s_waitcnt lgkmcnt(0)
	v_add_f32_e32 v16, v222, v15
	v_add_f32_e32 v222, v223, v17
	v_mul_f32_e32 v17, v2, v6
	v_add_f32_e32 v14, v225, v14
	v_mul_f32_e32 v225, v2, v8
	ds_bpermute_b32 v228, v60, v17
	v_mul_f32_e32 v223, v2, v7
	ds_bpermute_b32 v225, v60, v225
	ds_bpermute_b32 v223, v60, v223
	ds_bpermute_b32 v60, v60, v227
	s_waitcnt lgkmcnt(0)
	v_fmac_f32_e32 v228, v2, v6
	ds_bpermute_b32 v6, v59, v228
	v_fmac_f32_e32 v225, v2, v8
	v_fmac_f32_e32 v223, v2, v7
	v_fmac_f32_e32 v60, v2, v9
	ds_bpermute_b32 v8, v59, v225
	ds_bpermute_b32 v7, v59, v223
	ds_bpermute_b32 v9, v59, v60
	s_waitcnt lgkmcnt(0)
	v_add_f32_e32 v6, v228, v6
	ds_bpermute_b32 v65, v139, v62
	v_add_f32_e32 v59, v225, v8
	ds_bpermute_b32 v8, v139, v6
	v_add_f32_e32 v7, v223, v7
	v_add_f32_e32 v9, v60, v9
	ds_bpermute_b32 v60, v139, v7
	ds_bpermute_b32 v223, v139, v59
	ds_bpermute_b32 v225, v139, v9
	s_waitcnt lgkmcnt(0)
	v_add_f32_e32 v8, v6, v8
	v_xor_b32_e32 v6, 32, v175
	v_cmp_lt_i32_e64 s[2:3], v6, v41
	v_add_f32_e32 v60, v7, v60
	v_add_f32_e32 v229, v59, v223
	v_add_f32_e32 v233, v9, v225
	v_cndmask_b32_e64 v6, v175, v6, s[2:3]
	ds_bpermute_b32 v161, v139, v159
	ds_bpermute_b32 v191, v139, v169
	ds_bpermute_b32 v195, v139, v192
	ds_bpermute_b32 v162, v139, v160
	ds_bpermute_b32 v170, v139, v168
	ds_bpermute_b32 v194, v139, v193
	ds_bpermute_b32 v198, v139, v196
	ds_bpermute_b32 v164, v139, v163
	ds_bpermute_b32 v166, v139, v165
	ds_bpermute_b32 v157, v139, v197
	ds_bpermute_b32 v200, v139, v199
	ds_bpermute_b32 v63, v139, v61
	ds_bpermute_b32 v66, v139, v64
	ds_bpermute_b32 v203, v139, v201
	ds_bpermute_b32 v207, v139, v204
	ds_bpermute_b32 v51, v139, v50
	ds_bpermute_b32 v57, v139, v56
	ds_bpermute_b32 v206, v139, v205
	ds_bpermute_b32 v210, v139, v208
	ds_bpermute_b32 v44, v139, v42
	ds_bpermute_b32 v46, v139, v45
	ds_bpermute_b32 v37, v139, v209
	ds_bpermute_b32 v212, v139, v211
	ds_bpermute_b32 v28, v139, v27
	ds_bpermute_b32 v30, v139, v29
	ds_bpermute_b32 v215, v139, v213
	ds_bpermute_b32 v220, v139, v217
	ds_bpermute_b32 v19, v139, v18
	ds_bpermute_b32 v22, v139, v20
	ds_bpermute_b32 v219, v139, v218
	ds_bpermute_b32 v224, v139, v221
	ds_bpermute_b32 v15, v139, v14
	ds_bpermute_b32 v17, v139, v16
	ds_bpermute_b32 v227, v139, v222
	ds_bpermute_b32 v234, v139, v226
	v_lshlrev_b32_e32 v238, 2, v6
	v_cndmask_b32_e32 v6, 0, v39, vcc
	v_cndmask_b32_e32 v7, v39, v155, vcc
	v_cndmask_b32_e32 v9, v155, v34, vcc
	v_cndmask_b32_e32 v41, v34, v8, vcc
	v_cndmask_b32_e32 v59, v8, v58, vcc
	v_cndmask_b32_e32 v139, v58, v156, vcc
	v_cndmask_b32_e32 v223, v156, v36, vcc
	v_cndmask_b32_e32 v225, v36, v60, vcc
	v_cndmask_b32_e32 v228, v60, v154, vcc
	v_cndmask_b32_e32 v230, v154, v158, vcc
	v_cndmask_b32_e32 v231, v158, v38, vcc
	v_cndmask_b32_e32 v232, v38, v229, vcc
	v_cndmask_b32_e32 v235, v229, v171, vcc
	v_cndmask_b32_e32 v236, v171, v202, vcc
	v_cndmask_b32_e32 v237, v202, v214, vcc
	v_cndmask_b32_e32 v239, v214, v233, vcc
	ds_bpermute_b32 v6, v238, v6
	ds_bpermute_b32 v7, v238, v7
	ds_bpermute_b32 v9, v238, v9
	ds_bpermute_b32 v41, v238, v41
	ds_bpermute_b32 v59, v238, v59
	ds_bpermute_b32 v139, v238, v139
	ds_bpermute_b32 v223, v238, v223
	ds_bpermute_b32 v225, v238, v225
	ds_bpermute_b32 v228, v238, v228
	ds_bpermute_b32 v230, v238, v230
	ds_bpermute_b32 v231, v238, v231
	ds_bpermute_b32 v232, v238, v232
	ds_bpermute_b32 v235, v238, v235
	ds_bpermute_b32 v236, v238, v236
	ds_bpermute_b32 v237, v238, v237
	ds_bpermute_b32 v238, v238, v239
	v_cmp_eq_u32_e64 s[2:3], 0, v151
	s_and_saveexec_b64 s[4:5], s[2:3]
	s_cbranch_execz .LBB0_2162
; template <int VAR>
; __device__ __forceinline__ void nsa_attn_mfma(Frame& F, bf16* Y) {
;     ...
;           slc[T * 4 + q] = 2.f * (P[4 * q] + P[4 * q + 1] + P[4 * q + 2]) + P[4 * q + 3];
;           float a;
;           if (q > 0) a = P[4 * (q - 1) + 3];
;           else if (T > 0) { const f32x16& Pm = (T == 1) ? pA0 : (T == 2) ? pA1 : pB0; a = Pm[15]; }
;           else a = 0.f;
;           const float give = hi ? a : P[4 * q + 3];
;           slc[T * 4 + q] += __shfl_xor(give, 32); }
;       if (j == 0) {
; #pragma unroll
;         for (int T = 0; T < 4; ++T)
; #pragma unroll
;           for (int q = 0; q < 4; ++q) { const int blk = 8 * T + 2 * q + hi;
;             const float s = (blk == 0 || blk == cur || blk == cur - 1) ? 1e6f : (blk > cur ? -1.0f : slc[T * 4 + q]);
;             scl[(4 * wid + tsub) * 32 + blk] = s; }
	v_add_f32_e32 v10, v10, v12
	v_add_f32_e32 v12, v23, v24
	v_add_f32_e32 v10, v10, v12
	s_waitcnt lgkmcnt(0)
	v_add_f32_e32 v12, v14, v15
	v_add_f32_e32 v14, v27, v28
	v_add_f32_e32 v15, v18, v19
	v_add_f32_e32 v14, v14, v15
	v_add_f32_e32 v12, v14, v12
	v_add_f32_e32 v14, v61, v63
	v_add_f32_e32 v15, v50, v51
	v_fmac_f32_e32 v8, 2.0, v12
	v_add_f32_e32 v12, v42, v44
	v_add_f32_e32 v14, v14, v15
	v_add_f32_e32 v12, v14, v12
	v_add_f32_e32 v14, v62, v65
	v_add_f32_e32 v15, v160, v162
	v_fmac_f32_e32 v34, 2.0, v12
	v_add_f32_e32 v12, v163, v164
	v_add_f32_e32 v14, v14, v15
	v_add_f32_e32 v12, v14, v12
	v_add_f32_e32 v4, v4, v5
	v_add_f32_e32 v5, v11, v13
	v_fmac_f32_e32 v155, 2.0, v12
	v_add_f32_e32 v12, v25, v26
	v_add_f32_e32 v4, v4, v5
	v_add_f32_e32 v4, v4, v12
	v_readlane_b32 s2, v254, 36
	v_fmac_f32_e32 v39, 2.0, v4
	s_add_i32 s9, s97, -1
	v_or_b32_e32 v5, s2, v140
	v_cmp_eq_u32_e64 s[2:3], s97, v150
	v_add_f32_e32 v4, v39, v6
	s_or_b64 s[6:7], vcc, s[2:3]
	v_cmp_eq_u32_e32 vcc, s9, v150
	v_cmp_ge_i32_e64 s[2:3], s97, v150
	s_or_b64 vcc, s[6:7], vcc
	v_lshlrev_b32_e32 v5, 7, v5
	v_cndmask_b32_e64 v4, -1.0, v4, s[2:3]
	v_readlane_b32 s2, v254, 39
	v_add_u32_e32 v6, 2, v150
	v_cndmask_b32_e32 v4, v4, v176, vcc
	v_add3_u32 v5, s2, v5, v188
	v_cmp_eq_u32_e32 vcc, 0, v6
	v_cmp_eq_u32_e64 s[2:3], s97, v6
	v_add_f32_e32 v7, v155, v7
	s_or_b64 s[6:7], vcc, s[2:3]
	v_cmp_eq_u32_e32 vcc, s9, v6
	v_cmp_ge_i32_e64 s[2:3], s97, v6
	s_or_b64 vcc, s[6:7], vcc
	v_add_f32_e32 v9, v34, v9
	v_cndmask_b32_e64 v6, -1.0, v7, s[2:3]
	v_cndmask_b32_e32 v6, v6, v176, vcc
	ds_write2_b32 v5, v4, v6 offset1:2
	v_add_u32_e32 v4, 4, v150
	v_cmp_eq_u32_e32 vcc, 0, v4
	v_cmp_eq_u32_e64 s[2:3], s97, v4
	s_or_b64 s[6:7], vcc, s[2:3]
	v_cmp_eq_u32_e32 vcc, s9, v4
	v_cmp_ge_i32_e64 s[2:3], s97, v4
	v_add_f32_e32 v16, v16, v17
	v_add_f32_e32 v17, v29, v30
	v_add_f32_e32 v20, v20, v22
	v_cndmask_b32_e64 v4, -1.0, v9, s[2:3]
	s_or_b64 vcc, s[6:7], vcc
	v_add_u32_e32 v6, 6, v150
	v_add_f32_e32 v17, v17, v20
	v_add_f32_e32 v20, v64, v66
	v_add_f32_e32 v22, v56, v57
	v_cndmask_b32_e32 v4, v4, v176, vcc
	v_cmp_eq_u32_e32 vcc, 0, v6
	v_cmp_eq_u32_e64 s[2:3], s97, v6
	v_add_f32_e32 v16, v17, v16
	v_add_f32_e32 v17, v45, v46
	v_add_f32_e32 v20, v20, v22
	v_add_f32_e32 v22, v159, v161
	v_add_f32_e32 v29, v168, v170
	v_add_f32_e32 v8, v8, v41
	s_or_b64 s[6:7], vcc, s[2:3]
	v_cmp_eq_u32_e32 vcc, s9, v6
	v_cmp_ge_i32_e64 s[2:3], s97, v6
	v_add_f32_e32 v17, v20, v17
	v_add_f32_e32 v20, v165, v166
	v_add_f32_e32 v22, v22, v29
	v_cndmask_b32_e64 v6, -1.0, v8, s[2:3]
	s_or_b64 vcc, s[6:7], vcc
	v_add_f32_e32 v20, v22, v20
	v_add_f32_e32 v22, v35, v43
	v_cndmask_b32_e32 v6, v6, v176, vcc
	v_add_f32_e32 v10, v10, v22
	ds_write2_b32 v5, v4, v6 offset0:4 offset1:6
	v_add_u32_e32 v4, 8, v150
	v_fmac_f32_e32 v58, 2.0, v10
	v_cmp_eq_u32_e32 vcc, 0, v4
	v_cmp_eq_u32_e64 s[2:3], s97, v4
	v_add_f32_e32 v10, v58, v59
	s_or_b64 s[6:7], vcc, s[2:3]
	v_cmp_eq_u32_e32 vcc, s9, v4
	v_cmp_ge_i32_e64 s[2:3], s97, v4
	s_or_b64 vcc, s[6:7], vcc
	v_add_u32_e32 v6, 10, v150
	v_cndmask_b32_e64 v4, -1.0, v10, s[2:3]
	v_fmac_f32_e32 v156, 2.0, v20
	v_cndmask_b32_e32 v4, v4, v176, vcc
	v_cmp_eq_u32_e32 vcc, 0, v6
	v_cmp_eq_u32_e64 s[2:3], s97, v6
	v_add_f32_e32 v20, v156, v139
	s_or_b64 s[6:7], vcc, s[2:3]
	v_cmp_eq_u32_e32 vcc, s9, v6
	v_cmp_ge_i32_e64 s[2:3], s97, v6
	s_or_b64 vcc, s[6:7], vcc
	v_add_f32_e32 v32, v32, v47
	v_cndmask_b32_e64 v6, -1.0, v20, s[2:3]
	v_cndmask_b32_e32 v6, v6, v176, vcc
	v_add_f32_e32 v47, v48, v67
	v_add_f32_e32 v48, v213, v215
	v_add_f32_e32 v67, v218, v219
	ds_write2_b32 v5, v4, v6 offset0:8 offset1:10
	v_add_u32_e32 v4, 12, v150
	v_add_f32_e32 v32, v32, v47
	v_add_f32_e32 v47, v222, v227
	v_add_f32_e32 v48, v48, v67
	v_fmac_f32_e32 v36, 2.0, v17
	v_cmp_eq_u32_e32 vcc, 0, v4
	v_cmp_eq_u32_e64 s[2:3], s97, v4
	v_add_f32_e32 v47, v48, v47
	v_add_f32_e32 v48, v201, v203
	v_add_f32_e32 v67, v205, v206
	v_add_f32_e32 v17, v36, v223
	s_or_b64 s[6:7], vcc, s[2:3]
	v_cmp_eq_u32_e32 vcc, s9, v4
	v_cmp_ge_i32_e64 s[2:3], s97, v4
	v_add_f32_e32 v37, v209, v37
	v_add_f32_e32 v48, v48, v67
	v_cndmask_b32_e64 v4, -1.0, v17, s[2:3]
	s_or_b64 vcc, s[6:7], vcc
	v_add_u32_e32 v6, 14, v150
	v_add_f32_e32 v37, v48, v37
	v_fmac_f32_e32 v60, 2.0, v16
; template <int VAR>
; __device__ __forceinline__ void nsa_attn_mfma(Frame& F, bf16* Y) {
;     ...
;           slc[T * 4 + q] = 2.f * (P[4 * q] + P[4 * q + 1] + P[4 * q + 2]) + P[4 * q + 3];
;           float a;
;           if (q > 0) a = P[4 * (q - 1) + 3];
;           else if (T > 0) { const f32x16& Pm = (T == 1) ? pA0 : (T == 2) ? pA1 : pB0; a = Pm[15]; }
;           else a = 0.f;
;           const float give = hi ? a : P[4 * q + 3];
;           slc[T * 4 + q] += __shfl_xor(give, 32); }
;       if (j == 0) {
; #pragma unroll
;         for (int T = 0; T < 4; ++T)
; #pragma unroll
;           for (int q = 0; q < 4; ++q) { const int blk = 8 * T + 2 * q + hi;
;             const float s = (blk == 0 || blk == cur || blk == cur - 1) ? 1e6f : (blk > cur ? -1.0f : slc[T * 4 + q]);
;             scl[(4 * wid + tsub) * 32 + blk] = s; }
	v_cndmask_b32_e32 v4, v4, v176, vcc
	v_cmp_eq_u32_e32 vcc, 0, v6
	v_cmp_eq_u32_e64 s[2:3], s97, v6
	v_fmac_f32_e32 v38, 2.0, v37
	v_add_f32_e32 v48, v169, v191
	v_add_f32_e32 v67, v193, v194
	v_add_f32_e32 v16, v60, v225
	s_or_b64 s[6:7], vcc, s[2:3]
	v_cmp_eq_u32_e32 vcc, s9, v6
	v_cmp_ge_i32_e64 s[2:3], s97, v6
	v_add_f32_e32 v37, v38, v231
	v_add_f32_e32 v38, v197, v157
	v_add_f32_e32 v48, v48, v67
	v_add_f32_e32 v21, v21, v31
	v_add_f32_e32 v31, v33, v40
	v_cndmask_b32_e64 v6, -1.0, v16, s[2:3]
	s_or_b64 vcc, s[6:7], vcc
	v_add_f32_e32 v38, v48, v38
	v_add_f32_e32 v48, v49, v152
	v_add_f32_e32 v21, v21, v31
	v_cndmask_b32_e32 v6, v6, v176, vcc
	v_add_f32_e32 v21, v21, v48
	ds_write2_b32 v5, v4, v6 offset0:12 offset1:14
	v_add_u32_e32 v4, 16, v150
	v_fmac_f32_e32 v154, 2.0, v21
	v_cmp_eq_u32_e32 vcc, 0, v4
	v_cmp_eq_u32_e64 s[2:3], s97, v4
	v_add_f32_e32 v21, v154, v228
	s_or_b64 s[6:7], vcc, s[2:3]
	v_cmp_eq_u32_e32 vcc, s9, v4
	v_cmp_ge_i32_e64 s[2:3], s97, v4
	s_or_b64 vcc, s[6:7], vcc
	v_add_u32_e32 v6, 18, v150
	v_cndmask_b32_e64 v4, -1.0, v21, s[2:3]
	v_fmac_f32_e32 v158, 2.0, v38
	v_cndmask_b32_e32 v4, v4, v176, vcc
	v_cmp_eq_u32_e32 vcc, 0, v6
	v_cmp_eq_u32_e64 s[2:3], s97, v6
	v_add_f32_e32 v38, v158, v230
	s_or_b64 s[6:7], vcc, s[2:3]
	v_cmp_eq_u32_e32 vcc, s9, v6
	v_cmp_ge_i32_e64 s[2:3], s97, v6
	s_or_b64 vcc, s[6:7], vcc
	v_fmac_f32_e32 v229, 2.0, v47
	v_cndmask_b32_e64 v6, -1.0, v38, s[2:3]
	v_cndmask_b32_e32 v6, v6, v176, vcc
	ds_write2_b32 v5, v4, v6 offset0:16 offset1:18
	v_add_u32_e32 v4, 20, v150
	v_cmp_eq_u32_e32 vcc, 0, v4
	v_cmp_eq_u32_e64 s[2:3], s97, v4
	s_or_b64 s[6:7], vcc, s[2:3]
	v_cmp_eq_u32_e32 vcc, s9, v4
	v_cmp_ge_i32_e64 s[2:3], s97, v4
	s_or_b64 vcc, s[6:7], vcc
	v_add_u32_e32 v6, 22, v150
	v_cndmask_b32_e64 v4, -1.0, v37, s[2:3]
	v_cndmask_b32_e32 v4, v4, v176, vcc
	v_cmp_eq_u32_e32 vcc, 0, v6
	v_cmp_eq_u32_e64 s[2:3], s97, v6
	v_add_f32_e32 v47, v229, v232
	s_or_b64 s[6:7], vcc, s[2:3]
	v_cmp_eq_u32_e32 vcc, s9, v6
	v_cmp_ge_i32_e64 s[2:3], s97, v6
	s_or_b64 vcc, s[6:7], vcc
	v_add_f32_e32 v153, v153, v167
	v_cndmask_b32_e64 v6, -1.0, v47, s[2:3]
	v_cndmask_b32_e32 v6, v6, v176, vcc
	v_add_f32_e32 v32, v32, v153
	ds_write2_b32 v5, v4, v6 offset0:20 offset1:22
	v_add_u32_e32 v4, 24, v150
	v_add_f32_e32 v192, v192, v195
	v_add_f32_e32 v195, v196, v198
	v_fmac_f32_e32 v171, 2.0, v32
	v_cmp_eq_u32_e32 vcc, 0, v4
	v_cmp_eq_u32_e64 s[2:3], s97, v4
	v_add_f32_e32 v199, v199, v200
	v_add_f32_e32 v192, v192, v195
	v_add_f32_e32 v32, v171, v235
	s_or_b64 s[6:7], vcc, s[2:3]
	v_cmp_eq_u32_e32 vcc, s9, v4
	v_cmp_ge_i32_e64 s[2:3], s97, v4
	v_add_f32_e32 v192, v192, v199
	s_or_b64 vcc, s[6:7], vcc
	v_cndmask_b32_e64 v4, -1.0, v32, s[2:3]
	v_add_u32_e32 v6, 26, v150
	v_fmac_f32_e32 v202, 2.0, v192
	v_cndmask_b32_e32 v4, v4, v176, vcc
	v_cmp_eq_u32_e32 vcc, 0, v6
	v_cmp_eq_u32_e64 s[2:3], s97, v6
	v_add_f32_e32 v192, v202, v236
	s_or_b64 s[6:7], vcc, s[2:3]
	v_cmp_eq_u32_e32 vcc, s9, v6
	v_cmp_ge_i32_e64 s[2:3], s97, v6
	v_add_f32_e32 v204, v204, v207
	v_add_f32_e32 v207, v208, v210
	v_cndmask_b32_e64 v6, -1.0, v192, s[2:3]
	s_or_b64 vcc, s[6:7], vcc
	v_add_f32_e32 v211, v211, v212
	v_add_f32_e32 v204, v204, v207
	v_cndmask_b32_e32 v6, v6, v176, vcc
	v_add_f32_e32 v204, v204, v211
	ds_write2_b32 v5, v4, v6 offset0:24 offset1:26
	v_add_u32_e32 v4, 28, v150
	v_add_f32_e32 v217, v217, v220
	v_add_f32_e32 v220, v221, v224
	v_fmac_f32_e32 v214, 2.0, v204
	v_cmp_eq_u32_e32 vcc, 0, v4
	v_cmp_eq_u32_e64 s[2:3], s97, v4
	v_add_f32_e32 v151, v226, v234
	v_add_f32_e32 v217, v217, v220
	v_add_f32_e32 v204, v214, v237
	s_or_b64 s[6:7], vcc, s[2:3]
	v_cmp_eq_u32_e32 vcc, s9, v4
	v_cmp_ge_i32_e64 s[2:3], s97, v4
	v_add_f32_e32 v151, v217, v151
	s_or_b64 vcc, s[6:7], vcc
	v_cndmask_b32_e64 v4, -1.0, v204, s[2:3]
	v_add_u32_e32 v6, 30, v150
	v_fmac_f32_e32 v233, 2.0, v151
	v_cndmask_b32_e32 v4, v4, v176, vcc
	v_cmp_eq_u32_e32 vcc, 0, v6
	v_cmp_eq_u32_e64 s[2:3], s97, v6
	v_add_f32_e32 v151, v233, v238
	s_or_b64 s[6:7], vcc, s[2:3]
	v_cmp_eq_u32_e32 vcc, s9, v6
	v_cmp_ge_i32_e64 s[2:3], s97, v6
	s_or_b64 vcc, s[6:7], vcc
	s_nop 0
	v_cndmask_b32_e64 v6, -1.0, v151, s[2:3]
	v_cndmask_b32_e32 v6, v6, v176, vcc
	ds_write2_b32 v5, v4, v6 offset0:28 offset1:30
